# tile-edge: trailing wave-group re-alignment barrier moved from before its tile header to K-loop entry (P1,P6,P7,P8) so its header/zeroing overlaps the leading group
# speedup vs baseline: 1.0333x; 1.0027x over previous
;     __device__ bool next(int i, Unit& u) const { return at((long)i * G + c, u); }
;     __device__ bool next(int i, Unit& u) const { if (i > 0) return false; u.pm = pm; u.pn = pn; u.g = 0; u.nt = nt; u.k0 = 0; u.part = -1; return true; }
; #define PG8_STAGE(bufoff, gbase, voff) do { _Pragma("unroll") for (int _i = 0; _i < 2; ++_i) \
;         __builtin_amdgcn_global_load_lds((const unsigned*)((const char*)(gbase) + (voff)[_i]), (LAS unsigned*)(lds + (bufoff) + ldsw + _i * 8192), 16, 0, 0); } while (0)
; #define PG8_WAIT_V(n) asm volatile("s_waitcnt vmcnt(" #n ")" ::: "memory")
; template <class Epi, class Sched>
; __device__ __forceinline__ void gemm_phase(LAS unsigned char* lds, const Gemm g, const Sched& S, const Epi& E) {
;     const int tid = threadIdx.x, wid = __builtin_amdgcn_readfirstlane(tid >> 6), lane = tid & 63, wr = wid >> 2, wc = wid & 3, fr = lane & 15, fq = lane >> 4;
;     unsigned voffA[2], voffB[2];
; #pragma unroll
;     for (int i = 0; i < 2; ++i) { int R, C; stage_rc(tid * 16 + i * 8192, R, C); const int Rb = Epi::PERM ? ((R & ~31) + perm32(R & 31)) : R;
;         voffA[i] = (unsigned)(R * g.lda + C) * 2u; voffB[i] = (unsigned)(Rb * g.ldb + C) * 2u; }
;     const size_t kstep = (size_t)(BK * 2);
;     const size_t hstepA = (size_t)HALF * g.lda * 2, hstepB = (size_t)HALF * g.ldb * 2;
;     const unsigned ldsw = (unsigned)wid * 1024u;
;     const int aoff = lds_byte(wr * 64 + fr, fq * 8), boff = lds_byte(wc * 32 + fr, fq * 8);
;     ...
;     Unit cur, nxt; int ui = 0;
;     if (!S.next(0, cur)) return;
;     f32x4 acc[2][2][4][2];
; #pragma unroll
;     for (int a = 0; a < 2; ++a)
; #pragma unroll
;         for (int b = 0; b < 2; ++b)
; #pragma unroll
;             for (int m = 0; m < 4; ++m)
; #pragma unroll
;                 for (int n = 0; n < 2; ++n) acc[a][b][m][n] = (f32x4){0.f, 0.f, 0.f, 0.f};
;     bf16x8 At[4][2], B0[2][2], B1[2][2];
;     const char* cA = PG8_ABASE(cur); const char* cB = PG8_BBASE(cur);
;     PG8_STAGE(PG8_SB(0, 0), cB, voffB); PG8_STAGE(PG8_SB(0, 1), cB + hstepB, voffB); PG8_STAGE(PG8_SA(0, 0), cA, voffA); PG8_STAGE(PG8_SA(0, 1), cA + hstepA, voffA);
;     if (wr == 1) PG8_BAR;
;     PG8_WAIT_V(2); PG8_BAR;
;     PG8_STAGE(PG8_SB(1, 0), cB + kstep, voffB); PG8_STAGE(PG8_SA(1, 0), cA + kstep, voffA); PG8_STAGE(PG8_SB(1, 1), cB + hstepB + kstep, voffB);
;     PG8_WAIT_V(6); PG8_BAR;
.LBB0_139:
	s_andn2_b64 vcc, exec, s[0:1]
	s_cbranch_vccnz .LBB0_235
	v_lshrrev_b32_e32 v12, 1, v136
	v_lshrrev_b32_e32 v2, 5, v136
	v_and_b32_e32 v13, 24, v12
	v_and_b32_e32 v2, 4, v2
	v_bfe_u32 v3, v136, 2, 2
	v_lshlrev_b32_e32 v0, 4, v136
	v_and_b32_e32 v1, 32, v136
	v_bfe_u32 v10, v136, 2, 4
	v_or3_b32 v2, v2, v3, v13
	v_lshrrev_b32_e32 v3, 3, v136
	s_movk_i32 s0, 0x70
	v_bitop3_b32 v8, v0, v1, 48 bitop3:0x6c
	v_and_b32_e32 v9, 64, v136
	v_and_or_b32 v4, v3, s0, v10
	s_movk_i32 s0, 0x60
	v_add_u32_e32 v11, 0x2000, v0
	v_or_b32_e32 v1, v8, v9
	v_and_or_b32 v3, v3, s0, v2
	v_lshrrev_b32_e32 v0, 7, v11
	s_movk_i32 s0, 0xf0
	v_writelane_b32 v242, s48, 18
	v_lshl_or_b32 v130, v3, 12, v1
	v_and_or_b32 v3, v0, s0, v10
	s_movk_i32 s0, 0xe0
	s_lshr_b32 s5, s2, 6
	s_ashr_i32 s9, s8, 31
	s_ashr_i32 s7, s6, 31
	v_writelane_b32 v242, s49, 19
	s_lshr_b32 s4, s2, 8
	v_and_or_b32 v0, v0, s0, v2
	s_lshl_b32 s33, s5, 10
	s_lshl_b64 s[0:1], s[8:9], 20
	s_lshl_b64 s[10:11], s[6:7], 20
	v_writelane_b32 v242, s88, 20
	s_add_u32 s70, s82, s10
	s_addc_u32 s71, s83, s11
	v_writelane_b32 v242, s89, 21
	s_add_i32 s88, s33, 0
	s_add_i32 m0, s88, 0x10000
	v_writelane_b32 v242, s90, 22
	global_load_lds_dwordx4 v130, s[70:71]
	s_add_i32 m0, s88, 0x12000
	v_writelane_b32 v242, s91, 23
	v_lshl_or_b32 v134, v0, 12, v1
	s_add_u32 s10, s70, 0x80000
	v_writelane_b32 v242, s94, 24
	global_load_lds_dwordx4 v134, s[70:71]
	s_addc_u32 s11, s71, 0
	s_add_i32 m0, s88, 0x14000
	v_writelane_b32 v242, s95, 25
	global_load_lds_dwordx4 v130, s[10:11]
	s_add_i32 m0, s88, 0x16000
	v_lshl_or_b32 v128, v4, 12, v1
	global_load_lds_dwordx4 v134, s[10:11]
	v_readlane_b32 s10, v242, 6
	v_readlane_b32 s11, v242, 7
	s_add_u32 s96, s10, s0
	s_addc_u32 s97, s11, s1
	s_add_i32 s89, s88, 0x2000
	s_mov_b32 m0, s88
	s_add_u32 s0, s96, 0x80000
	v_lshl_or_b32 v132, v3, 12, v1
	global_load_lds_dwordx4 v128, s[96:97]
	s_mov_b32 m0, s89
	s_addc_u32 s1, s97, 0
	s_add_i32 s60, s88, 0x4000
	global_load_lds_dwordx4 v132, s[96:97]
	s_mov_b32 m0, s60
	s_add_i32 s61, s88, 0x6000
	global_load_lds_dwordx4 v128, s[0:1]
	s_mov_b32 m0, s61
	v_mov_b32_e32 v139, 0
	global_load_lds_dwordx4 v132, s[0:1]
	s_cmp_eq_u32 s4, 1
	v_mov_b32_e32 v131, v139
	v_mov_b32_e32 v135, v139
	v_mov_b32_e32 v129, v139
	v_mov_b32_e32 v133, v139
	s_cselect_b64 s[10:11], -1, 0
	s_mov_b32 s79, s87
	s_mov_b32 s0, 0
	v_lshl_add_u64 v[4:5], s[70:71], 0, v[130:131]
	v_lshl_add_u64 v[2:3], s[70:71], 0, v[134:135]
	v_lshl_add_u64 v[0:1], s[96:97], 0, v[128:129]
	v_writelane_b32 v242, s10, 16
	s_cmp_lg_u32 s4, 1
	v_lshl_add_u64 v[6:7], s[96:97], 0, v[132:133]
	v_writelane_b32 v242, s11, 17
	s_cbranch_scc1 .LBB0_142
.LBB0_142:
	s_lshl_b32 s1, s4, 6
	s_lshl_b32 s7, s4, 13
	s_lshl_b32 s4, s5, 5
	s_mov_b64 s[84:85], 0x80
	s_and_b32 s9, s4, 0x60
	s_add_i32 m0, s88, 0x18000
	v_lshl_add_u64 v[4:5], v[4:5], 0, s[84:85]
	s_lshl_b32 s10, s9, 7
	s_waitcnt vmcnt(2)
	s_barrier
	global_load_lds_dwordx4 v[4:5], off
	v_lshl_add_u64 v[2:3], v[2:3], 0, s[84:85]
	s_add_i32 m0, s88, 0x1a000
	s_add_i32 s90, s88, 0x8000
	s_add_i32 s91, s88, 0xa000
	global_load_lds_dwordx4 v[2:3], off
	v_lshl_add_u64 v[0:1], v[0:1], 0, s[84:85]
	s_mov_b32 m0, s90
	s_add_u32 s4, s70, 0x80080
	global_load_lds_dwordx4 v[0:1], off
	v_lshl_add_u64 v[0:1], v[6:7], 0, s[84:85]
	s_mov_b32 m0, s91
	s_addc_u32 s5, s71, 0
	global_load_lds_dwordx4 v[0:1], off
	s_add_i32 m0, s88, 0x1c000
	v_lshl_add_u64 v[0:1], s[4:5], 0, v[130:131]
	global_load_lds_dwordx4 v[0:1], off
	v_lshl_add_u64 v[0:1], s[4:5], 0, v[134:135]
	s_add_i32 m0, s88, 0x1e000
	v_and_b32_e32 v137, 15, v136
	global_load_lds_dwordx4 v[0:1], off
	v_lshlrev_b32_e32 v0, 1, v13
	v_lshlrev_b32_e32 v2, 2, v136
	v_lshl_or_b32 v1, v137, 6, v0
	v_and_b32_e32 v2, 32, v2
	v_bitop3_b32 v3, v1, s7, v2 bitop3:0xde
	v_lshlrev_b32_e32 v1, 6, v136
	s_movk_i32 s4, 0x3c0
	v_and_or_b32 v0, v1, s4, v0
	v_and_b32_e32 v140, 8, v12
	v_cmp_lt_u32_e64 s[4:5], 13, v137
	v_lshlrev_b32_e32 v138, 5, v137
	v_bitop3_b32 v141, s10, v0, v2 bitop3:0xf6
	s_cmpk_lt_u32 s2, 0x100
	v_writelane_b32 v242, s4, 14
	v_lshl_add_u64 v[0:1], s[54:55], 0, v[138:139]
	v_lshlrev_b32_e32 v138, 1, v140
	s_cselect_b64 s[86:87], -1, 0
	v_writelane_b32 v242, s5, 15
	s_ashr_i32 s4, s3, 31
	s_ashr_i32 s5, s74, 31
	v_lshl_add_u64 v[142:143], v[0:1], 0, v[138:139]
	v_lshlrev_b32_e32 v0, 9, v136
	s_add_u32 s10, s28, 0x10468000
	v_and_b32_e32 v0, 0x70000, v0
	v_lshlrev_b32_e32 v1, 12, v10
	s_addc_u32 s11, s29, 0
	v_or3_b32 v0, v8, v0, v1
	v_writelane_b32 v242, s10, 26
	v_add_u32_e32 v144, v0, v9
	v_lshlrev_b32_e32 v0, 5, v11
	s_waitcnt vmcnt(6)
	v_writelane_b32 v242, s11, 27
	s_add_u32 s10, s28, 0x10420000
	v_and_b32_e32 v0, 0xf0000, v0
	v_or_b32_e32 v153, s9, v13
	s_addc_u32 s11, s29, 0
	v_or3_b32 v0, v8, v0, v1
	s_add_i32 s62, 0, 0x10000
	s_add_i32 s63, 0, 0x14000
	v_or_b32_e32 v164, 0xfffff400, v153
	v_or_b32_e32 v165, 0xfffffe00, v153
	v_add_u32_e32 v166, -14, v137
	v_writelane_b32 v242, s10, 28
	v_mov_b32_e32 v145, v139
	v_add_u32_e32 v146, v0, v9
	v_mov_b32_e32 v147, v139
	v_mov_b64_e32 v[148:149], 0x820
	v_mov_b64_e32 v[150:151], 0x81f
	v_add_u32_e32 v167, s62, v141
	v_add_u32_e32 v168, s63, v141
	v_add_u32_e32 v169, 0, v3
	s_movk_i32 s46, 0x208
	s_movk_i32 s47, 0x900
	s_barrier
	v_writelane_b32 v242, s11, 29
	s_branch .LBB0_145

;     __device__ bool next(int i, Unit& u) const { return at((long)i * G + c, u); }
;     __device__ bool next(int i, Unit& u) const { if (i > 0) return false; u.pm = pm; u.pn = pn; u.g = 0; u.nt = nt; u.k0 = 0; u.part = -1; return true; }
; #define PG8_STAGE(bufoff, gbase, voff) do { _Pragma("unroll") for (int _i = 0; _i < 2; ++_i) \
;         __builtin_amdgcn_global_load_lds((const unsigned*)((const char*)(gbase) + (voff)[_i]), (LAS unsigned*)(lds + (bufoff) + ldsw + _i * 8192), 16, 0, 0); } while (0)
; #define PG8_LDA(dst, b, h) do { _Pragma("unroll") for (int m = 0; m < 4; ++m) _Pragma("unroll") for (int k = 0; k < 2; ++k) dst[m][k] = *(const LAS bf16x8*)(lds + PG8_SA(b, h) + aoff + m * 2048 + k * 1024); } while (0)
; #define PG8_LDB(dst, b, h) do { _Pragma("unroll") for (int n = 0; n < 2; ++n) _Pragma("unroll") for (int k = 0; k < 2; ++k) dst[n][k] = *(const LAS bf16x8*)(lds + PG8_SB(b, h) + boff + n * 2048 + k * 1024); } while (0)
; #define PG8_WAIT_V(n) asm volatile("s_waitcnt vmcnt(" #n ")" ::: "memory")
; #define PG8_BAR __builtin_amdgcn_s_barrier()
; template <class Epi, class Sched>
; __device__ __forceinline__ void gemm_phase(LAS unsigned char* lds, const Gemm g, const Sched& S, const Epi& E) {
;     ...
;         const bool has_next = S.next(ui + 1, nxt);
;         const char* nA = has_next ? PG8_ABASE(nxt) : cA; const char* nB = has_next ? PG8_BBASE(nxt) : cB;
;         const int nt = cur.nt;
;         for (int t = 0; t < nt; t += 2) {
;             const bool last = (t == nt - 2);
;             const char* a1 = cA + (size_t)(t + 1) * kstep;
;             const char* a2 = last ? nA : cA + (size_t)(t + 2) * kstep; const char* b2 = last ? nB : cB + (size_t)(t + 2) * kstep;
;             const char* a3 = a2 + kstep; const char* b3 = b2 + kstep;
;             PG8_LDB(B0, 0, 0); PG8_LDB(B1, 0, 1); PG8_SCHED; PG8_LDA(At, 0, 0); PG8_STAGE(PG8_SA(1, 1), a1 + hstepA, voffA);
;             PG8_WAIT_V(8); PG8_WAIT_L(0); PG8_BAR; PG8_MMA(0, 0, At, B0); PG8_MMA(0, 1, At, B1); PG8_BAR; PG8_SCHED;
;     ...
; #pragma unroll
;         for (int a = 0; a < 2; ++a)
; #pragma unroll
;             for (int b = 0; b < 2; ++b)
; #pragma unroll
;                 for (int m = 0; m < 4; ++m)
; #pragma unroll
;                     for (int n = 0; n < 2; ++n) acc[a][b][m][n] = (f32x4){0.f, 0.f, 0.f, 0.f};
;         cur = nxt; cA = nA; cB = nB; ++ui;
;         if (wr == 1) PG8_BAR;
.LBB0_147:
	s_ashr_i32 s95, s94, 31
	s_lshl_b64 s[34:35], s[94:95], 20
	v_readlane_b32 s48, v242, 6
	v_readlane_b32 s49, v242, 7
	s_add_u32 s76, s48, s34
	s_addc_u32 s77, s49, s35
	s_and_b64 s[34:35], s[10:11], exec
	s_cselect_b32 s2, s77, s97
	s_cselect_b32 s7, s76, s96
	s_ashr_i32 s93, s92, 31
	s_lshl_b64 s[34:35], s[92:93], 20
	s_add_u32 s72, s82, s34
	s_addc_u32 s73, s83, s35
	s_and_b64 s[34:35], s[10:11], exec
	s_cselect_b32 s9, s73, s71
	s_cselect_b32 s34, s72, s70
	s_add_u32 vcc_lo, s96, 0x80080
	s_addc_u32 vcc_hi, s97, 0
	s_add_u32 s35, s70, 0x100
	v_mov_b32_e32 v0, 0
	s_addc_u32 s75, s71, 0
	s_mov_b32 s93, -2
	v_mov_b32_e32 v1, v0
	v_mov_b32_e32 v2, v0
	v_mov_b32_e32 v3, v0
	v_mov_b32_e32 v4, v0
	v_mov_b32_e32 v5, v0
	v_mov_b32_e32 v6, v0
	v_mov_b32_e32 v7, v0
	v_mov_b32_e32 v16, v0
	v_mov_b32_e32 v17, v0
	v_mov_b32_e32 v18, v0
	v_mov_b32_e32 v19, v0
	v_mov_b32_e32 v20, v0
	v_mov_b32_e32 v21, v0
	v_mov_b32_e32 v22, v0
	v_mov_b32_e32 v23, v0
	s_waitcnt vmcnt(0)
	v_mov_b32_e32 v32, v0
	v_mov_b32_e32 v33, v0
	v_mov_b32_e32 v34, v0
	v_mov_b32_e32 v35, v0
	v_mov_b32_e32 v36, v0
	v_mov_b32_e32 v37, v0
	v_mov_b32_e32 v38, v0
	v_mov_b32_e32 v39, v0
	v_mov_b32_e32 v48, v0
	v_mov_b32_e32 v49, v0
	v_mov_b32_e32 v50, v0
	v_mov_b32_e32 v51, v0
	v_mov_b32_e32 v52, v0
	v_mov_b32_e32 v53, v0
	v_mov_b32_e32 v54, v0
	v_mov_b32_e32 v55, v0
	v_mov_b32_e32 v8, v0
	v_mov_b32_e32 v9, v0
	v_mov_b32_e32 v10, v0
	v_mov_b32_e32 v11, v0
	v_mov_b32_e32 v12, v0
	v_mov_b32_e32 v13, v0
	v_mov_b32_e32 v14, v0
	v_mov_b32_e32 v15, v0
	v_mov_b32_e32 v24, v0
	v_mov_b32_e32 v25, v0
	v_mov_b32_e32 v26, v0
	v_mov_b32_e32 v27, v0
	v_mov_b32_e32 v28, v0
	v_mov_b32_e32 v29, v0
	v_mov_b32_e32 v30, v0
	v_mov_b32_e32 v31, v0
	v_mov_b32_e32 v40, v0
	v_mov_b32_e32 v41, v0
	v_mov_b32_e32 v42, v0
	v_mov_b32_e32 v43, v0
	v_mov_b32_e32 v44, v0
	v_mov_b32_e32 v45, v0
	v_mov_b32_e32 v46, v0
	v_mov_b32_e32 v47, v0
	v_mov_b32_e32 v56, v0
	v_mov_b32_e32 v57, v0
	v_mov_b32_e32 v58, v0
	v_mov_b32_e32 v59, v0
	v_mov_b32_e32 v60, v0
	v_mov_b32_e32 v61, v0
	v_mov_b32_e32 v62, v0
	v_mov_b32_e32 v63, v0
	v_mov_b32_e32 v64, v0
	v_mov_b32_e32 v65, v0
	v_mov_b32_e32 v66, v0
	v_mov_b32_e32 v67, v0
	v_mov_b32_e32 v68, v0
	v_mov_b32_e32 v69, v0
	v_mov_b32_e32 v70, v0
	v_mov_b32_e32 v71, v0
	v_mov_b32_e32 v80, v0
	v_mov_b32_e32 v81, v0
	v_mov_b32_e32 v82, v0
	v_mov_b32_e32 v83, v0
	v_mov_b32_e32 v84, v0
	v_mov_b32_e32 v85, v0
	v_mov_b32_e32 v86, v0
	v_mov_b32_e32 v87, v0
	v_mov_b32_e32 v96, v0
	v_mov_b32_e32 v97, v0
	v_mov_b32_e32 v98, v0
	v_mov_b32_e32 v99, v0
	v_mov_b32_e32 v100, v0
	v_mov_b32_e32 v101, v0
	v_mov_b32_e32 v102, v0
	v_mov_b32_e32 v103, v0
	v_mov_b32_e32 v112, v0
	v_mov_b32_e32 v113, v0
	v_mov_b32_e32 v114, v0
	v_mov_b32_e32 v115, v0
	v_mov_b32_e32 v116, v0
	v_mov_b32_e32 v117, v0
	v_mov_b32_e32 v118, v0
	v_mov_b32_e32 v119, v0
	v_mov_b32_e32 v72, v0
	v_mov_b32_e32 v73, v0
	v_mov_b32_e32 v74, v0
	v_mov_b32_e32 v75, v0
	v_mov_b32_e32 v76, v0
	v_mov_b32_e32 v77, v0
	v_mov_b32_e32 v78, v0
	v_mov_b32_e32 v79, v0
	v_mov_b32_e32 v88, v0
	v_mov_b32_e32 v89, v0
	v_mov_b32_e32 v90, v0
	v_mov_b32_e32 v91, v0
	v_mov_b32_e32 v92, v0
	v_mov_b32_e32 v93, v0
	v_mov_b32_e32 v94, v0
	v_mov_b32_e32 v95, v0
	v_mov_b32_e32 v104, v0
	v_mov_b32_e32 v105, v0
	v_mov_b32_e32 v106, v0
	v_mov_b32_e32 v107, v0
	v_mov_b32_e32 v108, v0
	v_mov_b32_e32 v109, v0
	v_mov_b32_e32 v110, v0
	v_mov_b32_e32 v111, v0
	v_mov_b32_e32 v120, v0
	v_mov_b32_e32 v121, v0
	v_mov_b32_e32 v122, v0
	v_mov_b32_e32 v123, v0
	v_mov_b32_e32 v124, v0
	v_mov_b32_e32 v125, v0
	v_mov_b32_e32 v126, v0
	v_mov_b32_e32 v127, v0
	v_readlane_b32 s100, v242, 16
	v_readlane_b32 s101, v242, 17
	s_nop 1
	s_cmp_lg_u64 s[100:101], 0
	s_cbranch_scc0 .Ledge_p1
	s_barrier
.Ledge_p1:
.LBB0_148:
	ds_read_b128 v[154:157], v167
	ds_read_b128 v[158:161], v167 offset:1024
	ds_read_b128 v[170:173], v167 offset:2048
	ds_read_b128 v[174:177], v167 offset:3072
	ds_read_b128 v[178:181], v168
	ds_read_b128 v[182:185], v168 offset:1024
	ds_read_b128 v[186:189], v168 offset:2048
	ds_read_b128 v[190:193], v168 offset:3072
	s_add_u32 s48, vcc_lo, 0xfff80080
	s_addc_u32 s49, vcc_hi, -1
	s_cmp_eq_u32 s93, 28
	s_cselect_b32 s97, s2, s49
	s_cselect_b32 s96, s7, s48
	s_cselect_b32 s71, s9, s75
	s_cselect_b32 s70, s34, s35
	v_lshl_add_u64 v[162:163], vcc, 0, v[144:145]
	s_add_i32 m0, s88, 0xc000
	ds_read_b128 v[194:197], v169
	ds_read_b128 v[198:201], v169 offset:1024
	ds_read_b128 v[202:205], v169 offset:2048
	ds_read_b128 v[206:209], v169 offset:3072
	ds_read_b128 v[210:213], v169 offset:4096
	ds_read_b128 v[214:217], v169 offset:5120
	ds_read_b128 v[218:221], v169 offset:6144
	ds_read_b128 v[222:225], v169 offset:7168
	global_load_lds_dwordx4 v[162:163], off
	v_lshl_add_u64 v[162:163], vcc, 0, v[146:147]
	s_add_i32 m0, s88, 0xe000
	s_nop 0
	global_load_lds_dwordx4 v[162:163], off
	s_waitcnt vmcnt(8)
	s_waitcnt lgkmcnt(0)
	s_barrier
; #define PG8_STAGE(bufoff, gbase, voff) do { _Pragma("unroll") for (int _i = 0; _i < 2; ++_i) \
;         __builtin_amdgcn_global_load_lds((const unsigned*)((const char*)(gbase) + (voff)[_i]), (LAS unsigned*)(lds + (bufoff) + ldsw + _i * 8192), 16, 0, 0); } while (0)
; #define PG8_LDA(dst, b, h) do { _Pragma("unroll") for (int m = 0; m < 4; ++m) _Pragma("unroll") for (int k = 0; k < 2; ++k) dst[m][k] = *(const LAS bf16x8*)(lds + PG8_SA(b, h) + aoff + m * 2048 + k * 1024); } while (0)
; #define PG8_LDB(dst, b, h) do { _Pragma("unroll") for (int n = 0; n < 2; ++n) _Pragma("unroll") for (int k = 0; k < 2; ++k) dst[n][k] = *(const LAS bf16x8*)(lds + PG8_SB(b, h) + boff + n * 2048 + k * 1024); } while (0)
; #define PG8_MMA(ai, bj, At, Bt) do { __builtin_amdgcn_s_setprio(1); _Pragma("unroll") for (int m = 0; m < 4; ++m) _Pragma("unroll") for (int n = 0; n < 2; ++n) _Pragma("unroll") for (int k = 0; k < 2; ++k) \
;         acc[ai][bj][m][n] = __builtin_amdgcn_mfma_f32_16x16x32_bf16(Bt[n][k], At[m][k], acc[ai][bj][m][n], 0, 0, 0); __builtin_amdgcn_s_setprio(0); } while (0)
; #define PG8_WAIT_V(n) asm volatile("s_waitcnt vmcnt(" #n ")" ::: "memory")
; #define PG8_WAIT_L(n) asm volatile("s_waitcnt lgkmcnt(" #n ")" ::: "memory")
; #define PG8_BAR __builtin_amdgcn_s_barrier()
; #define PG8_SCHED __builtin_amdgcn_sched_barrier(0)
; template <class Epi, class Sched>
; __device__ __forceinline__ void gemm_phase(LAS unsigned char* lds, const Gemm g, const Sched& S, const Epi& E) {
;     ...
;             PG8_LDB(B0, 0, 0); PG8_LDB(B1, 0, 1); PG8_SCHED; PG8_LDA(At, 0, 0); PG8_STAGE(PG8_SA(1, 1), a1 + hstepA, voffA);
;             PG8_WAIT_V(8); PG8_WAIT_L(0); PG8_BAR; PG8_MMA(0, 0, At, B0); PG8_MMA(0, 1, At, B1); PG8_BAR; PG8_SCHED;
;             PG8_LDA(At, 0, 1); PG8_STAGE(PG8_SB(0, 0), b2, voffB); PG8_STAGE(PG8_SB(0, 1), b2 + hstepB, voffB); PG8_STAGE(PG8_SA(0, 0), a2, voffA);
;             PG8_WAIT_V(8); PG8_WAIT_L(0); PG8_BAR; PG8_MMA(1, 0, At, B0); PG8_MMA(1, 1, At, B1); PG8_BAR; PG8_SCHED;
	s_setprio 1
	s_waitcnt lgkmcnt(0)
	v_mfma_f32_16x16x32_bf16 v[124:127], v[154:157], v[194:197], v[124:127]
	v_mfma_f32_16x16x32_bf16 v[120:123], v[170:173], v[194:197], v[120:123]
	v_mfma_f32_16x16x32_bf16 v[108:111], v[154:157], v[202:205], v[108:111]
	v_mfma_f32_16x16x32_bf16 v[104:107], v[170:173], v[202:205], v[104:107]
	v_mfma_f32_16x16x32_bf16 v[92:95], v[154:157], v[210:213], v[92:95]
	v_mfma_f32_16x16x32_bf16 v[88:91], v[170:173], v[210:213], v[88:91]
	v_mfma_f32_16x16x32_bf16 v[76:79], v[154:157], v[218:221], v[76:79]
	v_mfma_f32_16x16x32_bf16 v[72:75], v[170:173], v[218:221], v[72:75]
	v_mfma_f32_16x16x32_bf16 v[124:127], v[158:161], v[198:201], v[124:127]
	v_mfma_f32_16x16x32_bf16 v[120:123], v[174:177], v[198:201], v[120:123]
	v_mfma_f32_16x16x32_bf16 v[108:111], v[158:161], v[206:209], v[108:111]
	v_mfma_f32_16x16x32_bf16 v[104:107], v[174:177], v[206:209], v[104:107]
	v_mfma_f32_16x16x32_bf16 v[92:95], v[158:161], v[214:217], v[92:95]
	v_mfma_f32_16x16x32_bf16 v[88:91], v[174:177], v[214:217], v[88:91]
	v_mfma_f32_16x16x32_bf16 v[76:79], v[158:161], v[222:225], v[76:79]
	v_mfma_f32_16x16x32_bf16 v[72:75], v[174:177], v[222:225], v[72:75]
	s_setprio 0
	s_setprio 1
	v_mfma_f32_16x16x32_bf16 v[116:119], v[178:181], v[194:197], v[116:119]
	v_mfma_f32_16x16x32_bf16 v[112:115], v[186:189], v[194:197], v[112:115]
	v_mfma_f32_16x16x32_bf16 v[100:103], v[178:181], v[202:205], v[100:103]
	v_mfma_f32_16x16x32_bf16 v[96:99], v[186:189], v[202:205], v[96:99]
	v_mfma_f32_16x16x32_bf16 v[84:87], v[178:181], v[210:213], v[84:87]
	v_mfma_f32_16x16x32_bf16 v[80:83], v[186:189], v[210:213], v[80:83]
	v_mfma_f32_16x16x32_bf16 v[68:71], v[178:181], v[218:221], v[68:71]
	v_mfma_f32_16x16x32_bf16 v[64:67], v[186:189], v[218:221], v[64:67]
	v_mfma_f32_16x16x32_bf16 v[116:119], v[182:185], v[198:201], v[116:119]
	v_mfma_f32_16x16x32_bf16 v[112:115], v[190:193], v[198:201], v[112:115]
	v_mfma_f32_16x16x32_bf16 v[100:103], v[182:185], v[206:209], v[100:103]
	v_mfma_f32_16x16x32_bf16 v[96:99], v[190:193], v[206:209], v[96:99]
	v_mfma_f32_16x16x32_bf16 v[84:87], v[182:185], v[214:217], v[84:87]
	v_mfma_f32_16x16x32_bf16 v[80:83], v[190:193], v[214:217], v[80:83]
	v_mfma_f32_16x16x32_bf16 v[68:71], v[182:185], v[222:225], v[68:71]
	v_mfma_f32_16x16x32_bf16 v[64:67], v[190:193], v[222:225], v[64:67]
	s_setprio 0
	s_barrier
	s_add_i32 s48, s62, s33
	v_lshl_add_u64 v[162:163], s[70:71], 0, v[130:131]
	s_mov_b32 m0, s48
	ds_read_b128 v[194:197], v169 offset:16384
	ds_read_b128 v[198:201], v169 offset:17408
	ds_read_b128 v[202:205], v169 offset:18432
	ds_read_b128 v[206:209], v169 offset:19456
	ds_read_b128 v[210:213], v169 offset:20480
	ds_read_b128 v[214:217], v169 offset:21504
	ds_read_b128 v[218:221], v169 offset:22528
	ds_read_b128 v[222:225], v169 offset:23552
	global_load_lds_dwordx4 v[162:163], off
	s_add_i32 m0, s48, 0x2000
	s_add_u32 s48, s70, 0x80000
	v_lshl_add_u64 v[226:227], s[70:71], 0, v[134:135]
	s_addc_u32 s49, s71, 0
	s_add_i32 s95, s63, s33
	global_load_lds_dwordx4 v[226:227], off
	v_lshl_add_u64 v[228:229], s[48:49], 0, v[130:131]
	s_mov_b32 m0, s95
	v_lshl_add_u64 v[230:231], s[96:97], 0, v[132:133]
	global_load_lds_dwordx4 v[228:229], off
	v_lshl_add_u64 v[228:229], s[48:49], 0, v[134:135]
	s_add_i32 m0, s95, 0x2000
	s_nop 0
	global_load_lds_dwordx4 v[228:229], off
	v_lshl_add_u64 v[228:229], s[96:97], 0, v[128:129]
	s_mov_b32 m0, s88
	s_nop 0
	global_load_lds_dwordx4 v[228:229], off
	s_mov_b32 m0, s89
	s_nop 0
	global_load_lds_dwordx4 v[230:231], off
	s_waitcnt vmcnt(8)
	s_waitcnt lgkmcnt(0)
	s_barrier
	s_setprio 1
	s_waitcnt lgkmcnt(0)
	v_mfma_f32_16x16x32_bf16 v[60:63], v[154:157], v[194:197], v[60:63]
	v_mfma_f32_16x16x32_bf16 v[56:59], v[170:173], v[194:197], v[56:59]
	v_mfma_f32_16x16x32_bf16 v[44:47], v[154:157], v[202:205], v[44:47]
	v_mfma_f32_16x16x32_bf16 v[40:43], v[170:173], v[202:205], v[40:43]
	v_mfma_f32_16x16x32_bf16 v[28:31], v[154:157], v[210:213], v[28:31]
	v_mfma_f32_16x16x32_bf16 v[24:27], v[170:173], v[210:213], v[24:27]
	v_mfma_f32_16x16x32_bf16 v[12:15], v[154:157], v[218:221], v[12:15]
	v_mfma_f32_16x16x32_bf16 v[8:11], v[170:173], v[218:221], v[8:11]
	v_mfma_f32_16x16x32_bf16 v[60:63], v[158:161], v[198:201], v[60:63]
	v_mfma_f32_16x16x32_bf16 v[56:59], v[174:177], v[198:201], v[56:59]
	v_mfma_f32_16x16x32_bf16 v[44:47], v[158:161], v[206:209], v[44:47]
	v_mfma_f32_16x16x32_bf16 v[40:43], v[174:177], v[206:209], v[40:43]
	v_mfma_f32_16x16x32_bf16 v[28:31], v[158:161], v[214:217], v[28:31]
	v_mfma_f32_16x16x32_bf16 v[24:27], v[174:177], v[214:217], v[24:27]
	v_mfma_f32_16x16x32_bf16 v[12:15], v[158:161], v[222:225], v[12:15]
	v_mfma_f32_16x16x32_bf16 v[8:11], v[174:177], v[222:225], v[8:11]
	s_setprio 0
	s_setprio 1
	v_mfma_f32_16x16x32_bf16 v[52:55], v[178:181], v[194:197], v[52:55]
	v_mfma_f32_16x16x32_bf16 v[48:51], v[186:189], v[194:197], v[48:51]
	v_mfma_f32_16x16x32_bf16 v[36:39], v[178:181], v[202:205], v[36:39]
	v_mfma_f32_16x16x32_bf16 v[32:35], v[186:189], v[202:205], v[32:35]
	v_mfma_f32_16x16x32_bf16 v[20:23], v[178:181], v[210:213], v[20:23]
	v_mfma_f32_16x16x32_bf16 v[16:19], v[186:189], v[210:213], v[16:19]
	v_mfma_f32_16x16x32_bf16 v[4:7], v[178:181], v[218:221], v[4:7]
	v_mfma_f32_16x16x32_bf16 v[0:3], v[186:189], v[218:221], v[0:3]
	v_mfma_f32_16x16x32_bf16 v[52:55], v[182:185], v[198:201], v[52:55]
	v_mfma_f32_16x16x32_bf16 v[48:51], v[190:193], v[198:201], v[48:51]
	v_mfma_f32_16x16x32_bf16 v[36:39], v[182:185], v[206:209], v[36:39]
	v_mfma_f32_16x16x32_bf16 v[32:35], v[190:193], v[206:209], v[32:35]
	v_mfma_f32_16x16x32_bf16 v[20:23], v[182:185], v[214:217], v[20:23]
	v_mfma_f32_16x16x32_bf16 v[16:19], v[190:193], v[214:217], v[16:19]
	v_mfma_f32_16x16x32_bf16 v[4:7], v[182:185], v[222:225], v[4:7]
	v_mfma_f32_16x16x32_bf16 v[0:3], v[190:193], v[222:225], v[0:3]
	s_setprio 0
	s_barrier
; #define PG8_STAGE(bufoff, gbase, voff) do { _Pragma("unroll") for (int _i = 0; _i < 2; ++_i) \
;         __builtin_amdgcn_global_load_lds((const unsigned*)((const char*)(gbase) + (voff)[_i]), (LAS unsigned*)(lds + (bufoff) + ldsw + _i * 8192), 16, 0, 0); } while (0)
; #define PG8_LDA(dst, b, h) do { _Pragma("unroll") for (int m = 0; m < 4; ++m) _Pragma("unroll") for (int k = 0; k < 2; ++k) dst[m][k] = *(const LAS bf16x8*)(lds + PG8_SA(b, h) + aoff + m * 2048 + k * 1024); } while (0)
; #define PG8_LDB(dst, b, h) do { _Pragma("unroll") for (int n = 0; n < 2; ++n) _Pragma("unroll") for (int k = 0; k < 2; ++k) dst[n][k] = *(const LAS bf16x8*)(lds + PG8_SB(b, h) + boff + n * 2048 + k * 1024); } while (0)
; #define PG8_MMA(ai, bj, At, Bt) do { __builtin_amdgcn_s_setprio(1); _Pragma("unroll") for (int m = 0; m < 4; ++m) _Pragma("unroll") for (int n = 0; n < 2; ++n) _Pragma("unroll") for (int k = 0; k < 2; ++k) \
;         acc[ai][bj][m][n] = __builtin_amdgcn_mfma_f32_16x16x32_bf16(Bt[n][k], At[m][k], acc[ai][bj][m][n], 0, 0, 0); __builtin_amdgcn_s_setprio(0); } while (0)
; #define PG8_WAIT_V(n) asm volatile("s_waitcnt vmcnt(" #n ")" ::: "memory")
; #define PG8_WAIT_L(n) asm volatile("s_waitcnt lgkmcnt(" #n ")" ::: "memory")
; #define PG8_BAR __builtin_amdgcn_s_barrier()
; #define PG8_SCHED __builtin_amdgcn_sched_barrier(0)
; template <class Epi, class Sched>
; __device__ __forceinline__ void gemm_phase(LAS unsigned char* lds, const Gemm g, const Sched& S, const Epi& E) {
;     ...
;             PG8_LDB(B0, 1, 0); PG8_LDB(B1, 1, 1); PG8_SCHED; PG8_LDA(At, 1, 0); PG8_STAGE(PG8_SA(0, 1), a2 + hstepA, voffA);
;             PG8_WAIT_V(8); PG8_WAIT_L(0); PG8_BAR; PG8_MMA(0, 0, At, B0); PG8_MMA(0, 1, At, B1); PG8_BAR; PG8_SCHED;
	s_add_i32 s95, 0, 0x18000
	v_add_u32_e32 v138, s95, v141
	s_add_i32 s78, 0, 0x1c000
	ds_read_b128 v[154:157], v138
	ds_read_b128 v[158:161], v138 offset:1024
	ds_read_b128 v[170:173], v138 offset:2048
	ds_read_b128 v[174:177], v138 offset:3072
	v_add_u32_e32 v138, s78, v141
	ds_read_b128 v[178:181], v138
	ds_read_b128 v[182:185], v138 offset:1024
	ds_read_b128 v[186:189], v138 offset:2048
	ds_read_b128 v[190:193], v138 offset:3072
	s_add_u32 s48, s96, 0x80000
	s_addc_u32 s49, s97, 0
	s_mov_b32 m0, s60
	v_lshl_add_u64 v[232:233], s[48:49], 0, v[128:129]
	ds_read_b128 v[194:197], v169 offset:32768
	ds_read_b128 v[198:201], v169 offset:33792
	ds_read_b128 v[202:205], v169 offset:34816
	ds_read_b128 v[206:209], v169 offset:35840
	ds_read_b128 v[210:213], v169 offset:36864
	ds_read_b128 v[214:217], v169 offset:37888
	ds_read_b128 v[218:221], v169 offset:38912
	ds_read_b128 v[222:225], v169 offset:39936
	global_load_lds_dwordx4 v[232:233], off
	v_lshl_add_u64 v[232:233], s[48:49], 0, v[132:133]
	s_mov_b32 m0, s61
	s_nop 0
	global_load_lds_dwordx4 v[232:233], off
	s_waitcnt vmcnt(8)
	s_waitcnt lgkmcnt(0)
	s_barrier
	s_setprio 1
	s_waitcnt lgkmcnt(0)
	v_mfma_f32_16x16x32_bf16 v[124:127], v[154:157], v[194:197], v[124:127]
	v_mfma_f32_16x16x32_bf16 v[120:123], v[170:173], v[194:197], v[120:123]
	v_mfma_f32_16x16x32_bf16 v[108:111], v[154:157], v[202:205], v[108:111]
	v_mfma_f32_16x16x32_bf16 v[104:107], v[170:173], v[202:205], v[104:107]
	v_mfma_f32_16x16x32_bf16 v[92:95], v[154:157], v[210:213], v[92:95]
	v_mfma_f32_16x16x32_bf16 v[88:91], v[170:173], v[210:213], v[88:91]
	v_mfma_f32_16x16x32_bf16 v[76:79], v[154:157], v[218:221], v[76:79]
	v_mfma_f32_16x16x32_bf16 v[72:75], v[170:173], v[218:221], v[72:75]
	v_mfma_f32_16x16x32_bf16 v[124:127], v[158:161], v[198:201], v[124:127]
	v_mfma_f32_16x16x32_bf16 v[120:123], v[174:177], v[198:201], v[120:123]
	v_mfma_f32_16x16x32_bf16 v[108:111], v[158:161], v[206:209], v[108:111]
	v_mfma_f32_16x16x32_bf16 v[104:107], v[174:177], v[206:209], v[104:107]
	v_mfma_f32_16x16x32_bf16 v[92:95], v[158:161], v[214:217], v[92:95]
	v_mfma_f32_16x16x32_bf16 v[88:91], v[174:177], v[214:217], v[88:91]
	v_mfma_f32_16x16x32_bf16 v[76:79], v[158:161], v[222:225], v[76:79]
	v_mfma_f32_16x16x32_bf16 v[72:75], v[174:177], v[222:225], v[72:75]
	s_setprio 0
	s_setprio 1
	v_mfma_f32_16x16x32_bf16 v[116:119], v[178:181], v[194:197], v[116:119]
	v_mfma_f32_16x16x32_bf16 v[112:115], v[186:189], v[194:197], v[112:115]
	v_mfma_f32_16x16x32_bf16 v[100:103], v[178:181], v[202:205], v[100:103]
	v_mfma_f32_16x16x32_bf16 v[96:99], v[186:189], v[202:205], v[96:99]
	v_mfma_f32_16x16x32_bf16 v[84:87], v[178:181], v[210:213], v[84:87]
	v_mfma_f32_16x16x32_bf16 v[80:83], v[186:189], v[210:213], v[80:83]
	v_mfma_f32_16x16x32_bf16 v[68:71], v[178:181], v[218:221], v[68:71]
	v_mfma_f32_16x16x32_bf16 v[64:67], v[186:189], v[218:221], v[64:67]
	v_mfma_f32_16x16x32_bf16 v[116:119], v[182:185], v[198:201], v[116:119]
	v_mfma_f32_16x16x32_bf16 v[112:115], v[190:193], v[198:201], v[112:115]
	v_mfma_f32_16x16x32_bf16 v[100:103], v[182:185], v[206:209], v[100:103]
	v_mfma_f32_16x16x32_bf16 v[96:99], v[190:193], v[206:209], v[96:99]
	v_mfma_f32_16x16x32_bf16 v[84:87], v[182:185], v[214:217], v[84:87]
	v_mfma_f32_16x16x32_bf16 v[80:83], v[190:193], v[214:217], v[80:83]
	v_mfma_f32_16x16x32_bf16 v[68:71], v[182:185], v[222:225], v[68:71]
	v_mfma_f32_16x16x32_bf16 v[64:67], v[190:193], v[222:225], v[64:67]
	s_setprio 0
	s_barrier
; #define PG8_STAGE(bufoff, gbase, voff) do { _Pragma("unroll") for (int _i = 0; _i < 2; ++_i) \
;         __builtin_amdgcn_global_load_lds((const unsigned*)((const char*)(gbase) + (voff)[_i]), (LAS unsigned*)(lds + (bufoff) + ldsw + _i * 8192), 16, 0, 0); } while (0)
; #define PG8_LDA(dst, b, h) do { _Pragma("unroll") for (int m = 0; m < 4; ++m) _Pragma("unroll") for (int k = 0; k < 2; ++k) dst[m][k] = *(const LAS bf16x8*)(lds + PG8_SA(b, h) + aoff + m * 2048 + k * 1024); } while (0)
; #define PG8_MMA(ai, bj, At, Bt) do { __builtin_amdgcn_s_setprio(1); _Pragma("unroll") for (int m = 0; m < 4; ++m) _Pragma("unroll") for (int n = 0; n < 2; ++n) _Pragma("unroll") for (int k = 0; k < 2; ++k) \
;         acc[ai][bj][m][n] = __builtin_amdgcn_mfma_f32_16x16x32_bf16(Bt[n][k], At[m][k], acc[ai][bj][m][n], 0, 0, 0); __builtin_amdgcn_s_setprio(0); } while (0)
; #define PG8_WAIT_V(n) asm volatile("s_waitcnt vmcnt(" #n ")" ::: "memory")
; #define PG8_WAIT_L(n) asm volatile("s_waitcnt lgkmcnt(" #n ")" ::: "memory")
; #define PG8_BAR __builtin_amdgcn_s_barrier()
; #define PG8_SCHED __builtin_amdgcn_sched_barrier(0)
; template <class Epi, class Sched>
; __device__ __forceinline__ void gemm_phase(LAS unsigned char* lds, const Gemm g, const Sched& S, const Epi& E) {
;     ...
;             PG8_LDA(At, 1, 1); PG8_STAGE(PG8_SB(1, 0), b3, voffB); PG8_STAGE(PG8_SB(1, 1), b3 + hstepB, voffB); PG8_STAGE(PG8_SA(1, 0), a3, voffA);
;             PG8_WAIT_V(8); PG8_WAIT_L(0); PG8_BAR; PG8_MMA(1, 0, At, B0); PG8_MMA(1, 1, At, B1); PG8_BAR; PG8_SCHED;
;         }
;         if (wr == 0) PG8_BAR;
	s_add_i32 s48, s95, s33
	v_lshl_add_u64 v[162:163], v[162:163], 0, s[84:85]
	s_mov_b32 m0, s48
	ds_read_b128 v[194:197], v169 offset:49152
	ds_read_b128 v[198:201], v169 offset:50176
	ds_read_b128 v[202:205], v169 offset:51200
	ds_read_b128 v[206:209], v169 offset:52224
	ds_read_b128 v[210:213], v169 offset:53248
	ds_read_b128 v[214:217], v169 offset:54272
	ds_read_b128 v[218:221], v169 offset:55296
	ds_read_b128 v[222:225], v169 offset:56320
	global_load_lds_dwordx4 v[162:163], off
	s_add_i32 m0, s48, 0x2000
	s_add_u32 s48, s70, 0x80080
	v_lshl_add_u64 v[162:163], v[226:227], 0, s[84:85]
	s_addc_u32 s49, s71, 0
	s_add_i32 s70, s78, s33
	global_load_lds_dwordx4 v[162:163], off
	v_lshl_add_u64 v[162:163], s[48:49], 0, v[130:131]
	s_mov_b32 m0, s70
	s_nop 0
	global_load_lds_dwordx4 v[162:163], off
	v_lshl_add_u64 v[162:163], s[48:49], 0, v[134:135]
	s_add_i32 m0, s70, 0x2000
	s_nop 0
	global_load_lds_dwordx4 v[162:163], off
	v_lshl_add_u64 v[162:163], v[228:229], 0, s[84:85]
	s_mov_b32 m0, s90
	s_nop 0
	global_load_lds_dwordx4 v[162:163], off
	v_lshl_add_u64 v[162:163], v[230:231], 0, s[84:85]
	s_mov_b32 m0, s91
	s_nop 0
	global_load_lds_dwordx4 v[162:163], off
	s_waitcnt vmcnt(8)
	s_waitcnt lgkmcnt(0)
	s_barrier
	s_setprio 1
	s_waitcnt lgkmcnt(0)
	v_mfma_f32_16x16x32_bf16 v[60:63], v[154:157], v[194:197], v[60:63]
	v_mfma_f32_16x16x32_bf16 v[56:59], v[170:173], v[194:197], v[56:59]
	v_mfma_f32_16x16x32_bf16 v[44:47], v[154:157], v[202:205], v[44:47]
	v_mfma_f32_16x16x32_bf16 v[40:43], v[170:173], v[202:205], v[40:43]
	v_mfma_f32_16x16x32_bf16 v[28:31], v[154:157], v[210:213], v[28:31]
	v_mfma_f32_16x16x32_bf16 v[24:27], v[170:173], v[210:213], v[24:27]
	v_mfma_f32_16x16x32_bf16 v[12:15], v[154:157], v[218:221], v[12:15]
	v_mfma_f32_16x16x32_bf16 v[8:11], v[170:173], v[218:221], v[8:11]
	v_mfma_f32_16x16x32_bf16 v[60:63], v[158:161], v[198:201], v[60:63]
	v_mfma_f32_16x16x32_bf16 v[56:59], v[174:177], v[198:201], v[56:59]
	v_mfma_f32_16x16x32_bf16 v[44:47], v[158:161], v[206:209], v[44:47]
	v_mfma_f32_16x16x32_bf16 v[40:43], v[174:177], v[206:209], v[40:43]
	v_mfma_f32_16x16x32_bf16 v[28:31], v[158:161], v[214:217], v[28:31]
	v_mfma_f32_16x16x32_bf16 v[24:27], v[174:177], v[214:217], v[24:27]
	v_mfma_f32_16x16x32_bf16 v[12:15], v[158:161], v[222:225], v[12:15]
	v_mfma_f32_16x16x32_bf16 v[8:11], v[174:177], v[222:225], v[8:11]
	s_setprio 0
	s_setprio 1
	v_mfma_f32_16x16x32_bf16 v[52:55], v[178:181], v[194:197], v[52:55]
	v_mfma_f32_16x16x32_bf16 v[48:51], v[186:189], v[194:197], v[48:51]
	v_mfma_f32_16x16x32_bf16 v[36:39], v[178:181], v[202:205], v[36:39]
	v_mfma_f32_16x16x32_bf16 v[32:35], v[186:189], v[202:205], v[32:35]
	v_mfma_f32_16x16x32_bf16 v[20:23], v[178:181], v[210:213], v[20:23]
	v_mfma_f32_16x16x32_bf16 v[16:19], v[186:189], v[210:213], v[16:19]
	v_mfma_f32_16x16x32_bf16 v[4:7], v[178:181], v[218:221], v[4:7]
	v_mfma_f32_16x16x32_bf16 v[0:3], v[186:189], v[218:221], v[0:3]
	v_mfma_f32_16x16x32_bf16 v[52:55], v[182:185], v[198:201], v[52:55]
	v_mfma_f32_16x16x32_bf16 v[48:51], v[190:193], v[198:201], v[48:51]
	v_mfma_f32_16x16x32_bf16 v[36:39], v[182:185], v[206:209], v[36:39]
	v_mfma_f32_16x16x32_bf16 v[32:35], v[190:193], v[206:209], v[32:35]
	v_mfma_f32_16x16x32_bf16 v[20:23], v[182:185], v[214:217], v[20:23]
	v_mfma_f32_16x16x32_bf16 v[16:19], v[190:193], v[214:217], v[16:19]
	v_mfma_f32_16x16x32_bf16 v[4:7], v[182:185], v[222:225], v[4:7]
	v_mfma_f32_16x16x32_bf16 v[0:3], v[190:193], v[222:225], v[0:3]
	s_setprio 0
	s_barrier
	s_add_i32 s93, s93, 2
	s_add_u32 vcc_lo, vcc_lo, 0x100
	s_addc_u32 vcc_hi, vcc_hi, 0
	s_add_u32 s35, s35, 0x100
	s_addc_u32 s75, s75, 0
	s_cmp_gt_u32 s93, 29
	s_cbranch_scc0 .LBB0_148
	s_and_b64 vcc, exec, s[86:87]
	s_cbranch_vccz .LBB0_151
	s_barrier

; #define PG8_BAR __builtin_amdgcn_s_barrier()
; template <class Epi, class Sched>
; __device__ __forceinline__ void gemm_phase(LAS unsigned char* lds, const Gemm g, const Sched& S, const Epi& E) {
;     ...
;         cur = nxt; cA = nA; cB = nB; ++ui;
;         if (wr == 1) PG8_BAR;
;     }
.LBB0_232:
	v_readlane_b32 s6, v242, 16
	v_readlane_b32 s7, v242, 17
	s_andn2_b64 vcc, exec, s[6:7]
	s_cbranch_vccnz .LBB0_143
	s_branch .LBB0_143

; #define PG8_STAGE(bufoff, gbase, voff) do { _Pragma("unroll") for (int _i = 0; _i < 2; ++_i) \
;         __builtin_amdgcn_global_load_lds((const unsigned*)((const char*)(gbase) + (voff)[_i]), (LAS unsigned*)(lds + (bufoff) + ldsw + _i * 8192), 16, 0, 0); } while (0)
; #define PG8_WAIT_V(n) asm volatile("s_waitcnt vmcnt(" #n ")" ::: "memory")
; #define PG8_BAR __builtin_amdgcn_s_barrier()
; template <class Epi, class Sched>
; __device__ __forceinline__ void gemm_phase(LAS unsigned char* lds, const Gemm g, const Sched& S, const Epi& E) {
;     ...
;     const char* cA = PG8_ABASE(cur); const char* cB = PG8_BBASE(cur);
;     PG8_STAGE(PG8_SB(0, 0), cB, voffB); PG8_STAGE(PG8_SB(0, 1), cB + hstepB, voffB); PG8_STAGE(PG8_SA(0, 0), cA, voffA); PG8_STAGE(PG8_SA(0, 1), cA + hstepA, voffA);
;     if (wr == 1) PG8_BAR;
;     PG8_WAIT_V(2); PG8_BAR;
;     PG8_STAGE(PG8_SB(1, 0), cB + kstep, voffB); PG8_STAGE(PG8_SA(1, 0), cA + kstep, voffA); PG8_STAGE(PG8_SB(1, 1), cB + hstepB + kstep, voffB);
;     PG8_WAIT_V(6); PG8_BAR;
.LBB0_709:
	s_andn2_b64 vcc, exec, s[40:41]
	s_cbranch_vccnz .LBB0_686
	s_lshr_b32 s35, s2, 6
	s_ashr_i32 s39, s38, 31
	s_ashr_i32 s61, s60, 31
	s_lshr_b32 s34, s2, 8
	s_lshl_b32 s76, s35, 10
	s_lshl_b64 s[40:41], s[38:39], 20
	s_lshl_b64 s[42:43], s[60:61], 20
	s_add_u32 s64, s50, s42
	s_addc_u32 s65, s51, s43
	s_add_i32 s61, s76, 0
	s_add_i32 m0, s61, 0x10000
	s_waitcnt lgkmcnt(0)
	v_lshl_add_u64 v[0:1], s[64:65], 0, v[130:131]
	global_load_lds_dwordx4 v[0:1], off
	s_add_i32 m0, s61, 0x12000
	s_add_u32 s42, s64, 0x80000
	v_lshl_add_u64 v[2:3], s[64:65], 0, v[134:135]
	s_addc_u32 s43, s65, 0
	global_load_lds_dwordx4 v[2:3], off
	s_add_i32 m0, s61, 0x14000
	v_lshl_add_u64 v[4:5], s[42:43], 0, v[130:131]
	global_load_lds_dwordx4 v[4:5], off
	s_add_i32 m0, s61, 0x16000
	s_add_u32 s62, s10, s40
	v_lshl_add_u64 v[4:5], s[42:43], 0, v[134:135]
	s_addc_u32 s63, s11, s41
	s_add_i32 s77, s61, 0x2000
	global_load_lds_dwordx4 v[4:5], off
	v_lshl_add_u64 v[6:7], s[62:63], 0, v[128:129]
	s_mov_b32 m0, s61
	s_add_u32 s40, s62, 0x80000
	global_load_lds_dwordx4 v[6:7], off
	v_lshl_add_u64 v[4:5], s[62:63], 0, v[132:133]
	s_mov_b32 m0, s77
	s_addc_u32 s41, s63, 0
	s_add_i32 s78, s61, 0x4000
	global_load_lds_dwordx4 v[4:5], off
	v_lshl_add_u64 v[8:9], s[40:41], 0, v[128:129]
	s_mov_b32 m0, s78
	s_add_i32 s79, s61, 0x6000
	global_load_lds_dwordx4 v[8:9], off
	v_lshl_add_u64 v[8:9], s[40:41], 0, v[132:133]
	s_mov_b32 m0, s79
	s_cmp_eq_u32 s34, 1
	global_load_lds_dwordx4 v[8:9], off
	s_cselect_b64 s[40:41], -1, 0
	s_cmp_lg_u32 s34, 1
	s_cbranch_scc1 .LBB0_712
.LBB0_712:
	s_lshl_b32 s35, s35, 5
	s_add_i32 m0, s61, 0x18000
	v_lshl_add_u64 v[0:1], v[0:1], 0, s[22:23]
	s_lshl_b32 s39, s34, 13
	s_and_b32 s35, s35, 0x60
	s_waitcnt vmcnt(2)
	s_barrier
	global_load_lds_dwordx4 v[0:1], off
	v_lshl_add_u64 v[0:1], v[2:3], 0, s[22:23]
	s_add_i32 m0, s61, 0x1a000
	s_add_i32 s80, s61, 0x8000
	s_add_i32 s81, s61, 0xa000
	global_load_lds_dwordx4 v[0:1], off
	v_lshl_add_u64 v[0:1], v[6:7], 0, s[22:23]
	s_mov_b32 m0, s80
	s_add_u32 s42, s64, 0x80080
	global_load_lds_dwordx4 v[0:1], off
	v_lshl_add_u64 v[0:1], v[4:5], 0, s[22:23]
	s_mov_b32 m0, s81
	s_addc_u32 s43, s65, 0
	global_load_lds_dwordx4 v[0:1], off
	s_add_i32 m0, s61, 0x1c000
	v_lshl_add_u64 v[0:1], s[42:43], 0, v[130:131]
	global_load_lds_dwordx4 v[0:1], off
	v_lshl_add_u64 v[0:1], s[42:43], 0, v[134:135]
	s_add_i32 m0, s61, 0x1e000
	s_cmpk_lt_u32 s2, 0x100
	global_load_lds_dwordx4 v[0:1], off
	s_waitcnt vmcnt(6)
	v_bitop3_b32 v0, v156, s39, v145 bitop3:0xde
	v_lshl_or_b32 v158, s34, 6, v137
	v_lshl_or_b32 v159, s35, 7, v153
	s_cselect_b64 s[42:43], -1, 0
	v_or_b32_e32 v144, s35, v154
	s_mov_b32 s82, 0
	v_add_u32_e32 v160, 0, v0
	s_barrier
	s_branch .LBB0_715

;     __device__ bool next(int i, Unit& u) const { return at((long)i * G + c, u); }
;     __device__ bool next(int i, Unit& u) const { if (i > 0) return false; u.pm = pm; u.pn = pn; u.g = 0; u.nt = nt; u.k0 = 0; u.part = -1; return true; }
; #define PG8_STAGE(bufoff, gbase, voff) do { _Pragma("unroll") for (int _i = 0; _i < 2; ++_i) \
;         __builtin_amdgcn_global_load_lds((const unsigned*)((const char*)(gbase) + (voff)[_i]), (LAS unsigned*)(lds + (bufoff) + ldsw + _i * 8192), 16, 0, 0); } while (0)
; #define PG8_LDA(dst, b, h) do { _Pragma("unroll") for (int m = 0; m < 4; ++m) _Pragma("unroll") for (int k = 0; k < 2; ++k) dst[m][k] = *(const LAS bf16x8*)(lds + PG8_SA(b, h) + aoff + m * 2048 + k * 1024); } while (0)
; #define PG8_LDB(dst, b, h) do { _Pragma("unroll") for (int n = 0; n < 2; ++n) _Pragma("unroll") for (int k = 0; k < 2; ++k) dst[n][k] = *(const LAS bf16x8*)(lds + PG8_SB(b, h) + boff + n * 2048 + k * 1024); } while (0)
; #define PG8_WAIT_V(n) asm volatile("s_waitcnt vmcnt(" #n ")" ::: "memory")
; template <class Epi, class Sched>
; __device__ __forceinline__ void gemm_phase(LAS unsigned char* lds, const Gemm g, const Sched& S, const Epi& E) {
;     ...
;     for (;;) {
;         const bool has_next = S.next(ui + 1, nxt);
;         const char* nA = has_next ? PG8_ABASE(nxt) : cA; const char* nB = has_next ? PG8_BBASE(nxt) : cB;
;         const int nt = cur.nt;
;         for (int t = 0; t < nt; t += 2) {
;             const bool last = (t == nt - 2);
;             const char* a1 = cA + (size_t)(t + 1) * kstep;
;             const char* a2 = last ? nA : cA + (size_t)(t + 2) * kstep; const char* b2 = last ? nB : cB + (size_t)(t + 2) * kstep;
;             const char* a3 = a2 + kstep; const char* b3 = b2 + kstep;
;             PG8_LDB(B0, 0, 0); PG8_LDB(B1, 0, 1); PG8_SCHED; PG8_LDA(At, 0, 0); PG8_STAGE(PG8_SA(1, 1), a1 + hstepA, voffA);
;             PG8_WAIT_V(8); PG8_WAIT_L(0); PG8_BAR; PG8_MMA(0, 0, At, B0); PG8_MMA(0, 1, At, B1); PG8_BAR; PG8_SCHED;
;     ...
; #pragma unroll
;         for (int a = 0; a < 2; ++a)
; #pragma unroll
;             for (int b = 0; b < 2; ++b)
; #pragma unroll
;                 for (int m = 0; m < 4; ++m)
; #pragma unroll
;                     for (int n = 0; n < 2; ++n) acc[a][b][m][n] = (f32x4){0.f, 0.f, 0.f, 0.f};
;         cur = nxt; cA = nA; cB = nB; ++ui;
;         if (wr == 1) PG8_BAR;
.LBB0_723:
	s_ashr_i32 s53, s52, 31
	s_lshl_b64 s[34:35], s[52:53], 20
	s_add_u32 s56, s10, s34
	s_addc_u32 s57, s11, s35
	s_and_b64 s[34:35], s[54:55], exec
	s_cselect_b32 s2, s57, s63
	s_cselect_b32 s34, s56, s62
	s_ashr_i32 s45, s44, 31
	s_lshl_b64 s[48:49], s[44:45], 20
	s_add_u32 s58, s50, s48
	s_addc_u32 s59, s51, s49
	s_and_b64 s[48:49], s[54:55], exec
	s_cselect_b32 s35, s59, s65
	s_cselect_b32 s39, s58, s64
	s_add_u32 s62, s62, 0x80080
	s_addc_u32 s63, s63, 0
	s_add_u32 s45, s64, 0x100
	v_mov_b32_e32 v0, 0
	s_addc_u32 s53, s65, 0
	s_mov_b32 s75, -2
	s_waitcnt lgkmcnt(0)
	v_mov_b32_e32 v1, v0
	v_mov_b32_e32 v2, v0
	v_mov_b32_e32 v3, v0
	v_mov_b32_e32 v4, v0
	v_mov_b32_e32 v5, v0
	v_mov_b32_e32 v6, v0
	v_mov_b32_e32 v7, v0
	v_mov_b32_e32 v16, v0
	v_mov_b32_e32 v17, v0
	v_mov_b32_e32 v18, v0
	v_mov_b32_e32 v19, v0
	v_mov_b32_e32 v20, v0
	v_mov_b32_e32 v21, v0
	v_mov_b32_e32 v22, v0
	v_mov_b32_e32 v23, v0
	s_waitcnt vmcnt(0)
	v_mov_b32_e32 v32, v0
	v_mov_b32_e32 v33, v0
	v_mov_b32_e32 v34, v0
	v_mov_b32_e32 v35, v0
	v_mov_b32_e32 v36, v0
	v_mov_b32_e32 v37, v0
	v_mov_b32_e32 v38, v0
	v_mov_b32_e32 v39, v0
	v_mov_b32_e32 v48, v0
	v_mov_b32_e32 v49, v0
	v_mov_b32_e32 v50, v0
	v_mov_b32_e32 v51, v0
	v_mov_b32_e32 v52, v0
	v_mov_b32_e32 v53, v0
	v_mov_b32_e32 v54, v0
	v_mov_b32_e32 v55, v0
	v_mov_b32_e32 v8, v0
	v_mov_b32_e32 v9, v0
	v_mov_b32_e32 v10, v0
	v_mov_b32_e32 v11, v0
	v_mov_b32_e32 v12, v0
	v_mov_b32_e32 v13, v0
	v_mov_b32_e32 v14, v0
	v_mov_b32_e32 v15, v0
	v_mov_b32_e32 v24, v0
	v_mov_b32_e32 v25, v0
	v_mov_b32_e32 v26, v0
	v_mov_b32_e32 v27, v0
	v_mov_b32_e32 v28, v0
	v_mov_b32_e32 v29, v0
	v_mov_b32_e32 v30, v0
	v_mov_b32_e32 v31, v0
	v_mov_b32_e32 v40, v0
	v_mov_b32_e32 v41, v0
	v_mov_b32_e32 v42, v0
	v_mov_b32_e32 v43, v0
	v_mov_b32_e32 v44, v0
	v_mov_b32_e32 v45, v0
	v_mov_b32_e32 v46, v0
	v_mov_b32_e32 v47, v0
	v_mov_b32_e32 v56, v0
	v_mov_b32_e32 v57, v0
	v_mov_b32_e32 v58, v0
	v_mov_b32_e32 v59, v0
	v_mov_b32_e32 v60, v0
	v_mov_b32_e32 v61, v0
	v_mov_b32_e32 v62, v0
	v_mov_b32_e32 v63, v0
	v_mov_b32_e32 v64, v0
	v_mov_b32_e32 v65, v0
	v_mov_b32_e32 v66, v0
	v_mov_b32_e32 v67, v0
	v_mov_b32_e32 v68, v0
	v_mov_b32_e32 v69, v0
	v_mov_b32_e32 v70, v0
	v_mov_b32_e32 v71, v0
	v_mov_b32_e32 v80, v0
	v_mov_b32_e32 v81, v0
	v_mov_b32_e32 v82, v0
	v_mov_b32_e32 v83, v0
	v_mov_b32_e32 v84, v0
	v_mov_b32_e32 v85, v0
	v_mov_b32_e32 v86, v0
	v_mov_b32_e32 v87, v0
	v_mov_b32_e32 v96, v0
	v_mov_b32_e32 v97, v0
	v_mov_b32_e32 v98, v0
	v_mov_b32_e32 v99, v0
	v_mov_b32_e32 v100, v0
	v_mov_b32_e32 v101, v0
	v_mov_b32_e32 v102, v0
	v_mov_b32_e32 v103, v0
	v_mov_b32_e32 v112, v0
	v_mov_b32_e32 v113, v0
	v_mov_b32_e32 v114, v0
	v_mov_b32_e32 v115, v0
	v_mov_b32_e32 v116, v0
	v_mov_b32_e32 v117, v0
	v_mov_b32_e32 v118, v0
	v_mov_b32_e32 v119, v0
	v_mov_b32_e32 v72, v0
	v_mov_b32_e32 v73, v0
	v_mov_b32_e32 v74, v0
	v_mov_b32_e32 v75, v0
	v_mov_b32_e32 v76, v0
	v_mov_b32_e32 v77, v0
	v_mov_b32_e32 v78, v0
	v_mov_b32_e32 v79, v0
	v_mov_b32_e32 v88, v0
	v_mov_b32_e32 v89, v0
	v_mov_b32_e32 v90, v0
	v_mov_b32_e32 v91, v0
	v_mov_b32_e32 v92, v0
	v_mov_b32_e32 v93, v0
	v_mov_b32_e32 v94, v0
	v_mov_b32_e32 v95, v0
	v_mov_b32_e32 v104, v0
	v_mov_b32_e32 v105, v0
	v_mov_b32_e32 v106, v0
	v_mov_b32_e32 v107, v0
	v_mov_b32_e32 v108, v0
	v_mov_b32_e32 v109, v0
	v_mov_b32_e32 v110, v0
	v_mov_b32_e32 v111, v0
	v_mov_b32_e32 v120, v0
	v_mov_b32_e32 v121, v0
	v_mov_b32_e32 v122, v0
	v_mov_b32_e32 v123, v0
	v_mov_b32_e32 v124, v0
	v_mov_b32_e32 v125, v0
	v_mov_b32_e32 v126, v0
	v_mov_b32_e32 v127, v0
	s_cmp_lg_u64 s[40:41], 0
	s_cbranch_scc0 .Ledge_p6
	s_barrier
.Ledge_p6:
.LBB0_724:
	s_add_u32 s48, s62, 0xfff80080
	s_addc_u32 s49, s63, -1
	s_add_i32 s83, 0, 0x10000
	s_cmp_eq_u32 s75, 28
	s_cselect_b32 s67, s2, s49
	s_cselect_b32 s66, s34, s48
	v_add_u32_e32 v161, s83, v159
	s_cselect_b32 s65, s35, s53
	s_cselect_b32 s64, s39, s45
	s_add_i32 s84, 0, 0x14000
	ds_read_b128 v[146:149], v161
	ds_read_b128 v[162:165], v161 offset:1024
	ds_read_b128 v[166:169], v161 offset:2048
	ds_read_b128 v[170:173], v161 offset:3072
	v_add_u32_e32 v161, s84, v159
	ds_read_b128 v[174:177], v161
	ds_read_b128 v[178:181], v161 offset:1024
	ds_read_b128 v[182:185], v161 offset:2048
	ds_read_b128 v[186:189], v161 offset:3072
	v_lshl_add_u64 v[222:223], s[62:63], 0, v[138:139]
	s_add_i32 m0, s61, 0xc000
	ds_read_b128 v[190:193], v160
	ds_read_b128 v[194:197], v160 offset:1024
	ds_read_b128 v[198:201], v160 offset:2048
	ds_read_b128 v[202:205], v160 offset:3072
	ds_read_b128 v[206:209], v160 offset:4096
	ds_read_b128 v[210:213], v160 offset:5120
	ds_read_b128 v[214:217], v160 offset:6144
	ds_read_b128 v[218:221], v160 offset:7168
	global_load_lds_dwordx4 v[222:223], off
	v_lshl_add_u64 v[222:223], s[62:63], 0, v[140:141]
	s_add_i32 m0, s61, 0xe000
	s_nop 0
	global_load_lds_dwordx4 v[222:223], off
	s_waitcnt vmcnt(8)
	s_waitcnt lgkmcnt(0)
	s_barrier
; #define PG8_STAGE(bufoff, gbase, voff) do { _Pragma("unroll") for (int _i = 0; _i < 2; ++_i) \
;         __builtin_amdgcn_global_load_lds((const unsigned*)((const char*)(gbase) + (voff)[_i]), (LAS unsigned*)(lds + (bufoff) + ldsw + _i * 8192), 16, 0, 0); } while (0)
; #define PG8_LDA(dst, b, h) do { _Pragma("unroll") for (int m = 0; m < 4; ++m) _Pragma("unroll") for (int k = 0; k < 2; ++k) dst[m][k] = *(const LAS bf16x8*)(lds + PG8_SA(b, h) + aoff + m * 2048 + k * 1024); } while (0)
; #define PG8_MMA(ai, bj, At, Bt) do { __builtin_amdgcn_s_setprio(1); _Pragma("unroll") for (int m = 0; m < 4; ++m) _Pragma("unroll") for (int n = 0; n < 2; ++n) _Pragma("unroll") for (int k = 0; k < 2; ++k) \
;         acc[ai][bj][m][n] = __builtin_amdgcn_mfma_f32_16x16x32_bf16(Bt[n][k], At[m][k], acc[ai][bj][m][n], 0, 0, 0); __builtin_amdgcn_s_setprio(0); } while (0)
; #define PG8_WAIT_V(n) asm volatile("s_waitcnt vmcnt(" #n ")" ::: "memory")
; #define PG8_WAIT_L(n) asm volatile("s_waitcnt lgkmcnt(" #n ")" ::: "memory")
; #define PG8_BAR __builtin_amdgcn_s_barrier()
; #define PG8_SCHED __builtin_amdgcn_sched_barrier(0)
; template <class Epi, class Sched>
; __device__ __forceinline__ void gemm_phase(LAS unsigned char* lds, const Gemm g, const Sched& S, const Epi& E) {
;     ...
;             PG8_WAIT_V(8); PG8_WAIT_L(0); PG8_BAR; PG8_MMA(0, 0, At, B0); PG8_MMA(0, 1, At, B1); PG8_BAR; PG8_SCHED;
;             PG8_LDA(At, 0, 1); PG8_STAGE(PG8_SB(0, 0), b2, voffB); PG8_STAGE(PG8_SB(0, 1), b2 + hstepB, voffB); PG8_STAGE(PG8_SA(0, 0), a2, voffA);
;             PG8_WAIT_V(8); PG8_WAIT_L(0); PG8_BAR; PG8_MMA(1, 0, At, B0); PG8_MMA(1, 1, At, B1); PG8_BAR; PG8_SCHED;
	s_setprio 1
	s_waitcnt lgkmcnt(0)
	v_mfma_f32_16x16x32_bf16 v[124:127], v[146:149], v[190:193], v[124:127]
	v_mfma_f32_16x16x32_bf16 v[120:123], v[166:169], v[190:193], v[120:123]
	v_mfma_f32_16x16x32_bf16 v[108:111], v[146:149], v[198:201], v[108:111]
	v_mfma_f32_16x16x32_bf16 v[104:107], v[166:169], v[198:201], v[104:107]
	v_mfma_f32_16x16x32_bf16 v[92:95], v[146:149], v[206:209], v[92:95]
	v_mfma_f32_16x16x32_bf16 v[88:91], v[166:169], v[206:209], v[88:91]
	v_mfma_f32_16x16x32_bf16 v[76:79], v[146:149], v[214:217], v[76:79]
	v_mfma_f32_16x16x32_bf16 v[72:75], v[166:169], v[214:217], v[72:75]
	v_mfma_f32_16x16x32_bf16 v[124:127], v[162:165], v[194:197], v[124:127]
	v_mfma_f32_16x16x32_bf16 v[120:123], v[170:173], v[194:197], v[120:123]
	v_mfma_f32_16x16x32_bf16 v[108:111], v[162:165], v[202:205], v[108:111]
	v_mfma_f32_16x16x32_bf16 v[104:107], v[170:173], v[202:205], v[104:107]
	v_mfma_f32_16x16x32_bf16 v[92:95], v[162:165], v[210:213], v[92:95]
	v_mfma_f32_16x16x32_bf16 v[88:91], v[170:173], v[210:213], v[88:91]
	v_mfma_f32_16x16x32_bf16 v[76:79], v[162:165], v[218:221], v[76:79]
	v_mfma_f32_16x16x32_bf16 v[72:75], v[170:173], v[218:221], v[72:75]
	s_setprio 0
	s_setprio 1
	v_mfma_f32_16x16x32_bf16 v[116:119], v[174:177], v[190:193], v[116:119]
	v_mfma_f32_16x16x32_bf16 v[112:115], v[182:185], v[190:193], v[112:115]
	v_mfma_f32_16x16x32_bf16 v[100:103], v[174:177], v[198:201], v[100:103]
	v_mfma_f32_16x16x32_bf16 v[96:99], v[182:185], v[198:201], v[96:99]
	v_mfma_f32_16x16x32_bf16 v[84:87], v[174:177], v[206:209], v[84:87]
	v_mfma_f32_16x16x32_bf16 v[80:83], v[182:185], v[206:209], v[80:83]
	v_mfma_f32_16x16x32_bf16 v[68:71], v[174:177], v[214:217], v[68:71]
	v_mfma_f32_16x16x32_bf16 v[64:67], v[182:185], v[214:217], v[64:67]
	v_mfma_f32_16x16x32_bf16 v[116:119], v[178:181], v[194:197], v[116:119]
	v_mfma_f32_16x16x32_bf16 v[112:115], v[186:189], v[194:197], v[112:115]
	v_mfma_f32_16x16x32_bf16 v[100:103], v[178:181], v[202:205], v[100:103]
	v_mfma_f32_16x16x32_bf16 v[96:99], v[186:189], v[202:205], v[96:99]
	v_mfma_f32_16x16x32_bf16 v[84:87], v[178:181], v[210:213], v[84:87]
	v_mfma_f32_16x16x32_bf16 v[80:83], v[186:189], v[210:213], v[80:83]
	v_mfma_f32_16x16x32_bf16 v[68:71], v[178:181], v[218:221], v[68:71]
	v_mfma_f32_16x16x32_bf16 v[64:67], v[186:189], v[218:221], v[64:67]
	s_setprio 0
	s_barrier
	s_add_i32 s48, s83, s76
	v_lshl_add_u64 v[222:223], s[64:65], 0, v[130:131]
	s_mov_b32 m0, s48
	ds_read_b128 v[190:193], v160 offset:16384
	ds_read_b128 v[194:197], v160 offset:17408
	ds_read_b128 v[198:201], v160 offset:18432
	ds_read_b128 v[202:205], v160 offset:19456
	ds_read_b128 v[206:209], v160 offset:20480
	ds_read_b128 v[210:213], v160 offset:21504
	ds_read_b128 v[214:217], v160 offset:22528
	ds_read_b128 v[218:221], v160 offset:23552
	global_load_lds_dwordx4 v[222:223], off
	s_add_i32 m0, s48, 0x2000
	s_add_u32 s48, s64, 0x80000
	v_lshl_add_u64 v[224:225], s[64:65], 0, v[134:135]
	s_addc_u32 s49, s65, 0
	s_add_i32 s83, s84, s76
	global_load_lds_dwordx4 v[224:225], off
	v_lshl_add_u64 v[226:227], s[48:49], 0, v[130:131]
	s_mov_b32 m0, s83
	v_lshl_add_u64 v[228:229], s[66:67], 0, v[132:133]
	global_load_lds_dwordx4 v[226:227], off
	v_lshl_add_u64 v[226:227], s[48:49], 0, v[134:135]
	s_add_i32 m0, s83, 0x2000
	s_nop 0
	global_load_lds_dwordx4 v[226:227], off
	v_lshl_add_u64 v[226:227], s[66:67], 0, v[128:129]
	s_mov_b32 m0, s61
	s_nop 0
	global_load_lds_dwordx4 v[226:227], off
	s_mov_b32 m0, s77
	s_nop 0
	global_load_lds_dwordx4 v[228:229], off
	s_waitcnt vmcnt(8)
	s_waitcnt lgkmcnt(0)
	s_barrier
	s_setprio 1
	s_waitcnt lgkmcnt(0)
	v_mfma_f32_16x16x32_bf16 v[60:63], v[146:149], v[190:193], v[60:63]
	v_mfma_f32_16x16x32_bf16 v[56:59], v[166:169], v[190:193], v[56:59]
	v_mfma_f32_16x16x32_bf16 v[44:47], v[146:149], v[198:201], v[44:47]
	v_mfma_f32_16x16x32_bf16 v[40:43], v[166:169], v[198:201], v[40:43]
	v_mfma_f32_16x16x32_bf16 v[28:31], v[146:149], v[206:209], v[28:31]
	v_mfma_f32_16x16x32_bf16 v[24:27], v[166:169], v[206:209], v[24:27]
	v_mfma_f32_16x16x32_bf16 v[12:15], v[146:149], v[214:217], v[12:15]
	v_mfma_f32_16x16x32_bf16 v[8:11], v[166:169], v[214:217], v[8:11]
	v_mfma_f32_16x16x32_bf16 v[60:63], v[162:165], v[194:197], v[60:63]
	v_mfma_f32_16x16x32_bf16 v[56:59], v[170:173], v[194:197], v[56:59]
	v_mfma_f32_16x16x32_bf16 v[44:47], v[162:165], v[202:205], v[44:47]
	v_mfma_f32_16x16x32_bf16 v[40:43], v[170:173], v[202:205], v[40:43]
	v_mfma_f32_16x16x32_bf16 v[28:31], v[162:165], v[210:213], v[28:31]
	v_mfma_f32_16x16x32_bf16 v[24:27], v[170:173], v[210:213], v[24:27]
	v_mfma_f32_16x16x32_bf16 v[12:15], v[162:165], v[218:221], v[12:15]
	v_mfma_f32_16x16x32_bf16 v[8:11], v[170:173], v[218:221], v[8:11]
	s_setprio 0
	s_setprio 1
	v_mfma_f32_16x16x32_bf16 v[52:55], v[174:177], v[190:193], v[52:55]
	v_mfma_f32_16x16x32_bf16 v[48:51], v[182:185], v[190:193], v[48:51]
	v_mfma_f32_16x16x32_bf16 v[36:39], v[174:177], v[198:201], v[36:39]
	v_mfma_f32_16x16x32_bf16 v[32:35], v[182:185], v[198:201], v[32:35]
	v_mfma_f32_16x16x32_bf16 v[20:23], v[174:177], v[206:209], v[20:23]
	v_mfma_f32_16x16x32_bf16 v[16:19], v[182:185], v[206:209], v[16:19]
	v_mfma_f32_16x16x32_bf16 v[4:7], v[174:177], v[214:217], v[4:7]
	v_mfma_f32_16x16x32_bf16 v[0:3], v[182:185], v[214:217], v[0:3]
	v_mfma_f32_16x16x32_bf16 v[52:55], v[178:181], v[194:197], v[52:55]
	v_mfma_f32_16x16x32_bf16 v[48:51], v[186:189], v[194:197], v[48:51]
	v_mfma_f32_16x16x32_bf16 v[36:39], v[178:181], v[202:205], v[36:39]
	v_mfma_f32_16x16x32_bf16 v[32:35], v[186:189], v[202:205], v[32:35]
	v_mfma_f32_16x16x32_bf16 v[20:23], v[178:181], v[210:213], v[20:23]
	v_mfma_f32_16x16x32_bf16 v[16:19], v[186:189], v[210:213], v[16:19]
	v_mfma_f32_16x16x32_bf16 v[4:7], v[178:181], v[218:221], v[4:7]
	v_mfma_f32_16x16x32_bf16 v[0:3], v[186:189], v[218:221], v[0:3]
	s_setprio 0
	s_barrier
; #define PG8_STAGE(bufoff, gbase, voff) do { _Pragma("unroll") for (int _i = 0; _i < 2; ++_i) \
;         __builtin_amdgcn_global_load_lds((const unsigned*)((const char*)(gbase) + (voff)[_i]), (LAS unsigned*)(lds + (bufoff) + ldsw + _i * 8192), 16, 0, 0); } while (0)
; #define PG8_LDA(dst, b, h) do { _Pragma("unroll") for (int m = 0; m < 4; ++m) _Pragma("unroll") for (int k = 0; k < 2; ++k) dst[m][k] = *(const LAS bf16x8*)(lds + PG8_SA(b, h) + aoff + m * 2048 + k * 1024); } while (0)
; #define PG8_LDB(dst, b, h) do { _Pragma("unroll") for (int n = 0; n < 2; ++n) _Pragma("unroll") for (int k = 0; k < 2; ++k) dst[n][k] = *(const LAS bf16x8*)(lds + PG8_SB(b, h) + boff + n * 2048 + k * 1024); } while (0)
; #define PG8_MMA(ai, bj, At, Bt) do { __builtin_amdgcn_s_setprio(1); _Pragma("unroll") for (int m = 0; m < 4; ++m) _Pragma("unroll") for (int n = 0; n < 2; ++n) _Pragma("unroll") for (int k = 0; k < 2; ++k) \
;         acc[ai][bj][m][n] = __builtin_amdgcn_mfma_f32_16x16x32_bf16(Bt[n][k], At[m][k], acc[ai][bj][m][n], 0, 0, 0); __builtin_amdgcn_s_setprio(0); } while (0)
; #define PG8_WAIT_V(n) asm volatile("s_waitcnt vmcnt(" #n ")" ::: "memory")
; #define PG8_WAIT_L(n) asm volatile("s_waitcnt lgkmcnt(" #n ")" ::: "memory")
; #define PG8_BAR __builtin_amdgcn_s_barrier()
; #define PG8_SCHED __builtin_amdgcn_sched_barrier(0)
; template <class Epi, class Sched>
; __device__ __forceinline__ void gemm_phase(LAS unsigned char* lds, const Gemm g, const Sched& S, const Epi& E) {
;     ...
;             PG8_LDB(B0, 1, 0); PG8_LDB(B1, 1, 1); PG8_SCHED; PG8_LDA(At, 1, 0); PG8_STAGE(PG8_SA(0, 1), a2 + hstepA, voffA);
;             PG8_WAIT_V(8); PG8_WAIT_L(0); PG8_BAR; PG8_MMA(0, 0, At, B0); PG8_MMA(0, 1, At, B1); PG8_BAR; PG8_SCHED;
	s_add_i32 s83, 0, 0x18000
	v_add_u32_e32 v161, s83, v159
	s_add_i32 s84, 0, 0x1c000
	ds_read_b128 v[146:149], v161
	ds_read_b128 v[162:165], v161 offset:1024
	ds_read_b128 v[166:169], v161 offset:2048
	ds_read_b128 v[170:173], v161 offset:3072
	v_add_u32_e32 v161, s84, v159
	ds_read_b128 v[174:177], v161
	ds_read_b128 v[178:181], v161 offset:1024
	ds_read_b128 v[182:185], v161 offset:2048
	ds_read_b128 v[186:189], v161 offset:3072
	s_add_u32 s48, s66, 0x80000
	s_addc_u32 s49, s67, 0
	s_mov_b32 m0, s78
	v_lshl_add_u64 v[230:231], s[48:49], 0, v[128:129]
	ds_read_b128 v[190:193], v160 offset:32768
	ds_read_b128 v[194:197], v160 offset:33792
	ds_read_b128 v[198:201], v160 offset:34816
	ds_read_b128 v[202:205], v160 offset:35840
	ds_read_b128 v[206:209], v160 offset:36864
	ds_read_b128 v[210:213], v160 offset:37888
	ds_read_b128 v[214:217], v160 offset:38912
	ds_read_b128 v[218:221], v160 offset:39936
	global_load_lds_dwordx4 v[230:231], off
	v_lshl_add_u64 v[230:231], s[48:49], 0, v[132:133]
	s_mov_b32 m0, s79
	s_nop 0
	global_load_lds_dwordx4 v[230:231], off
	s_waitcnt vmcnt(8)
	s_waitcnt lgkmcnt(0)
	s_barrier
	s_setprio 1
	s_waitcnt lgkmcnt(0)
	v_mfma_f32_16x16x32_bf16 v[124:127], v[146:149], v[190:193], v[124:127]
	v_mfma_f32_16x16x32_bf16 v[120:123], v[166:169], v[190:193], v[120:123]
	v_mfma_f32_16x16x32_bf16 v[108:111], v[146:149], v[198:201], v[108:111]
	v_mfma_f32_16x16x32_bf16 v[104:107], v[166:169], v[198:201], v[104:107]
	v_mfma_f32_16x16x32_bf16 v[92:95], v[146:149], v[206:209], v[92:95]
	v_mfma_f32_16x16x32_bf16 v[88:91], v[166:169], v[206:209], v[88:91]
	v_mfma_f32_16x16x32_bf16 v[76:79], v[146:149], v[214:217], v[76:79]
	v_mfma_f32_16x16x32_bf16 v[72:75], v[166:169], v[214:217], v[72:75]
	v_mfma_f32_16x16x32_bf16 v[124:127], v[162:165], v[194:197], v[124:127]
	v_mfma_f32_16x16x32_bf16 v[120:123], v[170:173], v[194:197], v[120:123]
	v_mfma_f32_16x16x32_bf16 v[108:111], v[162:165], v[202:205], v[108:111]
	v_mfma_f32_16x16x32_bf16 v[104:107], v[170:173], v[202:205], v[104:107]
	v_mfma_f32_16x16x32_bf16 v[92:95], v[162:165], v[210:213], v[92:95]
	v_mfma_f32_16x16x32_bf16 v[88:91], v[170:173], v[210:213], v[88:91]
	v_mfma_f32_16x16x32_bf16 v[76:79], v[162:165], v[218:221], v[76:79]
	v_mfma_f32_16x16x32_bf16 v[72:75], v[170:173], v[218:221], v[72:75]
	s_setprio 0
	s_setprio 1
	v_mfma_f32_16x16x32_bf16 v[116:119], v[174:177], v[190:193], v[116:119]
	v_mfma_f32_16x16x32_bf16 v[112:115], v[182:185], v[190:193], v[112:115]
	v_mfma_f32_16x16x32_bf16 v[100:103], v[174:177], v[198:201], v[100:103]
	v_mfma_f32_16x16x32_bf16 v[96:99], v[182:185], v[198:201], v[96:99]
	v_mfma_f32_16x16x32_bf16 v[84:87], v[174:177], v[206:209], v[84:87]
	v_mfma_f32_16x16x32_bf16 v[80:83], v[182:185], v[206:209], v[80:83]
	v_mfma_f32_16x16x32_bf16 v[68:71], v[174:177], v[214:217], v[68:71]
	v_mfma_f32_16x16x32_bf16 v[64:67], v[182:185], v[214:217], v[64:67]
	v_mfma_f32_16x16x32_bf16 v[116:119], v[178:181], v[194:197], v[116:119]
	v_mfma_f32_16x16x32_bf16 v[112:115], v[186:189], v[194:197], v[112:115]
	v_mfma_f32_16x16x32_bf16 v[100:103], v[178:181], v[202:205], v[100:103]
	v_mfma_f32_16x16x32_bf16 v[96:99], v[186:189], v[202:205], v[96:99]
	v_mfma_f32_16x16x32_bf16 v[84:87], v[178:181], v[210:213], v[84:87]
	v_mfma_f32_16x16x32_bf16 v[80:83], v[186:189], v[210:213], v[80:83]
	v_mfma_f32_16x16x32_bf16 v[68:71], v[178:181], v[218:221], v[68:71]
	v_mfma_f32_16x16x32_bf16 v[64:67], v[186:189], v[218:221], v[64:67]
	s_setprio 0
	s_barrier
; #define PG8_STAGE(bufoff, gbase, voff) do { _Pragma("unroll") for (int _i = 0; _i < 2; ++_i) \
;         __builtin_amdgcn_global_load_lds((const unsigned*)((const char*)(gbase) + (voff)[_i]), (LAS unsigned*)(lds + (bufoff) + ldsw + _i * 8192), 16, 0, 0); } while (0)
; #define PG8_LDA(dst, b, h) do { _Pragma("unroll") for (int m = 0; m < 4; ++m) _Pragma("unroll") for (int k = 0; k < 2; ++k) dst[m][k] = *(const LAS bf16x8*)(lds + PG8_SA(b, h) + aoff + m * 2048 + k * 1024); } while (0)
; #define PG8_MMA(ai, bj, At, Bt) do { __builtin_amdgcn_s_setprio(1); _Pragma("unroll") for (int m = 0; m < 4; ++m) _Pragma("unroll") for (int n = 0; n < 2; ++n) _Pragma("unroll") for (int k = 0; k < 2; ++k) \
;         acc[ai][bj][m][n] = __builtin_amdgcn_mfma_f32_16x16x32_bf16(Bt[n][k], At[m][k], acc[ai][bj][m][n], 0, 0, 0); __builtin_amdgcn_s_setprio(0); } while (0)
; #define PG8_WAIT_V(n) asm volatile("s_waitcnt vmcnt(" #n ")" ::: "memory")
; #define PG8_WAIT_L(n) asm volatile("s_waitcnt lgkmcnt(" #n ")" ::: "memory")
; #define PG8_BAR __builtin_amdgcn_s_barrier()
; #define PG8_SCHED __builtin_amdgcn_sched_barrier(0)
; template <class Epi, class Sched>
; __device__ __forceinline__ void gemm_phase(LAS unsigned char* lds, const Gemm g, const Sched& S, const Epi& E) {
;     ...
;             PG8_LDA(At, 1, 1); PG8_STAGE(PG8_SB(1, 0), b3, voffB); PG8_STAGE(PG8_SB(1, 1), b3 + hstepB, voffB); PG8_STAGE(PG8_SA(1, 0), a3, voffA);
;             PG8_WAIT_V(8); PG8_WAIT_L(0); PG8_BAR; PG8_MMA(1, 0, At, B0); PG8_MMA(1, 1, At, B1); PG8_BAR; PG8_SCHED;
;         }
;         if (wr == 0) PG8_BAR;
	s_add_i32 s48, s83, s76
	v_lshl_add_u64 v[222:223], v[222:223], 0, s[22:23]
	s_mov_b32 m0, s48
	ds_read_b128 v[190:193], v160 offset:49152
	ds_read_b128 v[194:197], v160 offset:50176
	ds_read_b128 v[198:201], v160 offset:51200
	ds_read_b128 v[202:205], v160 offset:52224
	ds_read_b128 v[206:209], v160 offset:53248
	ds_read_b128 v[210:213], v160 offset:54272
	ds_read_b128 v[214:217], v160 offset:55296
	ds_read_b128 v[218:221], v160 offset:56320
	global_load_lds_dwordx4 v[222:223], off
	s_add_i32 m0, s48, 0x2000
	s_add_u32 s48, s64, 0x80080
	v_lshl_add_u64 v[222:223], v[224:225], 0, s[22:23]
	s_addc_u32 s49, s65, 0
	s_add_i32 s64, s84, s76
	global_load_lds_dwordx4 v[222:223], off
	v_lshl_add_u64 v[222:223], s[48:49], 0, v[130:131]
	s_mov_b32 m0, s64
	s_nop 0
	global_load_lds_dwordx4 v[222:223], off
	v_lshl_add_u64 v[222:223], s[48:49], 0, v[134:135]
	s_add_i32 m0, s64, 0x2000
	s_nop 0
	global_load_lds_dwordx4 v[222:223], off
	v_lshl_add_u64 v[222:223], v[226:227], 0, s[22:23]
	s_mov_b32 m0, s80
	s_nop 0
	global_load_lds_dwordx4 v[222:223], off
	v_lshl_add_u64 v[222:223], v[228:229], 0, s[22:23]
	s_mov_b32 m0, s81
	s_nop 0
	global_load_lds_dwordx4 v[222:223], off
	s_waitcnt vmcnt(8)
	s_waitcnt lgkmcnt(0)
	s_barrier
	s_setprio 1
	s_waitcnt lgkmcnt(0)
	v_mfma_f32_16x16x32_bf16 v[60:63], v[146:149], v[190:193], v[60:63]
	v_mfma_f32_16x16x32_bf16 v[56:59], v[166:169], v[190:193], v[56:59]
	v_mfma_f32_16x16x32_bf16 v[44:47], v[146:149], v[198:201], v[44:47]
	v_mfma_f32_16x16x32_bf16 v[40:43], v[166:169], v[198:201], v[40:43]
	v_mfma_f32_16x16x32_bf16 v[28:31], v[146:149], v[206:209], v[28:31]
	v_mfma_f32_16x16x32_bf16 v[24:27], v[166:169], v[206:209], v[24:27]
	v_mfma_f32_16x16x32_bf16 v[12:15], v[146:149], v[214:217], v[12:15]
	v_mfma_f32_16x16x32_bf16 v[8:11], v[166:169], v[214:217], v[8:11]
	v_mfma_f32_16x16x32_bf16 v[60:63], v[162:165], v[194:197], v[60:63]
	v_mfma_f32_16x16x32_bf16 v[56:59], v[170:173], v[194:197], v[56:59]
	v_mfma_f32_16x16x32_bf16 v[44:47], v[162:165], v[202:205], v[44:47]
	v_mfma_f32_16x16x32_bf16 v[40:43], v[170:173], v[202:205], v[40:43]
	v_mfma_f32_16x16x32_bf16 v[28:31], v[162:165], v[210:213], v[28:31]
	v_mfma_f32_16x16x32_bf16 v[24:27], v[170:173], v[210:213], v[24:27]
	v_mfma_f32_16x16x32_bf16 v[12:15], v[162:165], v[218:221], v[12:15]
	v_mfma_f32_16x16x32_bf16 v[8:11], v[170:173], v[218:221], v[8:11]
	s_setprio 0
	s_setprio 1
	v_mfma_f32_16x16x32_bf16 v[52:55], v[174:177], v[190:193], v[52:55]
	v_mfma_f32_16x16x32_bf16 v[48:51], v[182:185], v[190:193], v[48:51]
	v_mfma_f32_16x16x32_bf16 v[36:39], v[174:177], v[198:201], v[36:39]
	v_mfma_f32_16x16x32_bf16 v[32:35], v[182:185], v[198:201], v[32:35]
	v_mfma_f32_16x16x32_bf16 v[20:23], v[174:177], v[206:209], v[20:23]
	v_mfma_f32_16x16x32_bf16 v[16:19], v[182:185], v[206:209], v[16:19]
	v_mfma_f32_16x16x32_bf16 v[4:7], v[174:177], v[214:217], v[4:7]
	v_mfma_f32_16x16x32_bf16 v[0:3], v[182:185], v[214:217], v[0:3]
	v_mfma_f32_16x16x32_bf16 v[52:55], v[178:181], v[194:197], v[52:55]
	v_mfma_f32_16x16x32_bf16 v[48:51], v[186:189], v[194:197], v[48:51]
	v_mfma_f32_16x16x32_bf16 v[36:39], v[178:181], v[202:205], v[36:39]
	v_mfma_f32_16x16x32_bf16 v[32:35], v[186:189], v[202:205], v[32:35]
	v_mfma_f32_16x16x32_bf16 v[20:23], v[178:181], v[210:213], v[20:23]
	v_mfma_f32_16x16x32_bf16 v[16:19], v[186:189], v[210:213], v[16:19]
	v_mfma_f32_16x16x32_bf16 v[4:7], v[178:181], v[218:221], v[4:7]
	v_mfma_f32_16x16x32_bf16 v[0:3], v[186:189], v[218:221], v[0:3]
	s_setprio 0
	s_barrier
	s_add_i32 s75, s75, 2
	s_add_u32 s62, s62, 0x100
	s_addc_u32 s63, s63, 0
	s_add_u32 s45, s45, 0x100
	s_addc_u32 s53, s53, 0
	s_cmp_gt_u32 s75, 29
	s_cbranch_scc0 .LBB0_724
	s_and_b64 vcc, exec, s[42:43]
	s_cbranch_vccz .LBB0_727
	s_barrier

; #define PG8_BAR __builtin_amdgcn_s_barrier()
; template <class Epi, class Sched>
; __device__ __forceinline__ void gemm_phase(LAS unsigned char* lds, const Gemm g, const Sched& S, const Epi& E) {
;     ...
;         cur = nxt; cA = nA; cB = nB; ++ui;
;         if (wr == 1) PG8_BAR;
;     }
.LBB0_749:
	s_andn2_b64 vcc, exec, s[40:41]
	s_cbranch_vccnz .LBB0_713
	s_branch .LBB0_713

;     __device__ bool next(int i, Unit& u) const { return at((long)i * G + c, u); }
;     __device__ bool next(int i, Unit& u) const { if (i > 0) return false; u.pm = pm; u.pn = pn; u.g = 0; u.nt = nt; u.k0 = 0; u.part = -1; return true; }
; #define PG8_STAGE(bufoff, gbase, voff) do { _Pragma("unroll") for (int _i = 0; _i < 2; ++_i) \
;         __builtin_amdgcn_global_load_lds((const unsigned*)((const char*)(gbase) + (voff)[_i]), (LAS unsigned*)(lds + (bufoff) + ldsw + _i * 8192), 16, 0, 0); } while (0)
; #define PG8_WAIT_V(n) asm volatile("s_waitcnt vmcnt(" #n ")" ::: "memory")
; template <class Epi, class Sched>
; __device__ __forceinline__ void gemm_phase(LAS unsigned char* lds, const Gemm g, const Sched& S, const Epi& E) {
;     const int tid = threadIdx.x, wid = __builtin_amdgcn_readfirstlane(tid >> 6), lane = tid & 63, wr = wid >> 2, wc = wid & 3, fr = lane & 15, fq = lane >> 4;
;     unsigned voffA[2], voffB[2];
; #pragma unroll
;     for (int i = 0; i < 2; ++i) { int R, C; stage_rc(tid * 16 + i * 8192, R, C); const int Rb = Epi::PERM ? ((R & ~31) + perm32(R & 31)) : R;
;         voffA[i] = (unsigned)(R * g.lda + C) * 2u; voffB[i] = (unsigned)(Rb * g.ldb + C) * 2u; }
;     const size_t kstep = (size_t)(BK * 2);
;     const size_t hstepA = (size_t)HALF * g.lda * 2, hstepB = (size_t)HALF * g.ldb * 2;
;     const unsigned ldsw = (unsigned)wid * 1024u;
;     const int aoff = lds_byte(wr * 64 + fr, fq * 8), boff = lds_byte(wc * 32 + fr, fq * 8);
;     ...
;     Unit cur, nxt; int ui = 0;
;     if (!S.next(0, cur)) return;
;     f32x4 acc[2][2][4][2];
; #pragma unroll
;     for (int a = 0; a < 2; ++a)
; #pragma unroll
;         for (int b = 0; b < 2; ++b)
; #pragma unroll
;             for (int m = 0; m < 4; ++m)
; #pragma unroll
;                 for (int n = 0; n < 2; ++n) acc[a][b][m][n] = (f32x4){0.f, 0.f, 0.f, 0.f};
;     bf16x8 At[4][2], B0[2][2], B1[2][2];
;     const char* cA = PG8_ABASE(cur); const char* cB = PG8_BBASE(cur);
;     PG8_STAGE(PG8_SB(0, 0), cB, voffB); PG8_STAGE(PG8_SB(0, 1), cB + hstepB, voffB); PG8_STAGE(PG8_SA(0, 0), cA, voffA); PG8_STAGE(PG8_SA(0, 1), cA + hstepA, voffA);
;     if (wr == 1) PG8_BAR;
;     PG8_WAIT_V(2); PG8_BAR;
;     PG8_STAGE(PG8_SB(1, 0), cB + kstep, voffB); PG8_STAGE(PG8_SA(1, 0), cA + kstep, voffA); PG8_STAGE(PG8_SB(1, 1), cB + hstepB + kstep, voffB);
;     PG8_WAIT_V(6); PG8_BAR;
.LBB0_825:
	s_add_i32 s0, s8, s0
	s_ashr_i32 s8, s0, 31
	s_lshr_b32 s8, s8, 24
	s_add_i32 s8, s0, s8
	s_ashr_i32 s9, s8, 8
	s_and_b32 s8, s8, 0xff00
	s_sub_i32 s8, s0, s8
	v_lshrrev_b32_e32 v2, 1, v136
	s_sext_i32_i16 s0, s8
	v_and_b32_e32 v11, 24, v2
	v_lshrrev_b32_e32 v2, 5, v136
	s_bfe_u32 s0, s0, 0x3001c
	v_and_b32_e32 v2, 4, v2
	v_bfe_u32 v3, v136, 2, 2
	s_add_i32 s10, s8, s0
	v_lshlrev_b32_e32 v0, 4, v136
	s_waitcnt lgkmcnt(0)
	v_and_b32_e32 v1, 32, v136
	v_bfe_u32 v10, v136, 2, 4
	v_or3_b32 v2, v2, v3, v11
	v_lshrrev_b32_e32 v3, 3, v136
	s_movk_i32 s2, 0x70
	s_sext_i32_i16 s0, s10
	s_and_b32 s10, s10, 0xfff8
	v_bitop3_b32 v8, v0, v1, 48 bitop3:0x6c
	v_and_b32_e32 v9, 64, v136
	v_and_or_b32 v4, v3, s2, v10
	s_movk_i32 s2, 0x60
	v_add_u32_e32 v12, 0x2000, v0
	s_sub_i32 s8, s8, s10
	v_or_b32_e32 v1, v8, v9
	v_and_or_b32 v3, v3, s2, v2
	v_lshrrev_b32_e32 v0, 7, v12
	s_movk_i32 s2, 0xf0
	s_lshl_b32 s9, s9, 3
	s_sext_i32_i16 s8, s8
	s_lshr_b32 s1, s12, 8
	v_lshl_or_b32 v130, v3, 12, v1
	v_and_or_b32 v3, v0, s2, v10
	s_movk_i32 s2, 0xe0
	s_lshr_b32 s0, s0, 3
	s_add_i32 s24, s9, s8
	v_and_or_b32 v0, v0, s2, v2
	s_lshr_b32 s2, s12, 6
	s_ashr_i32 s25, s24, 31
	s_bfe_i64 s[10:11], s[0:1], 0x100000
	s_lshl_b32 s5, s2, 10
	s_lshl_b64 s[8:9], s[24:25], 20
	s_lshl_b64 s[10:11], s[10:11], 20
	s_add_u32 s38, s88, s10
	s_addc_u32 s39, s89, s11
	s_add_i32 s25, s5, 0
	s_add_i32 m0, s25, 0x10000
	v_lshl_or_b32 v134, v0, 12, v1
	global_load_lds_dwordx4 v130, s[38:39]
	s_add_i32 m0, s25, 0x12000
	s_add_u32 s10, s38, 0x80000
	global_load_lds_dwordx4 v134, s[38:39]
	s_addc_u32 s11, s39, 0
	s_add_i32 m0, s25, 0x14000
	v_lshl_or_b32 v128, v4, 12, v1
	v_and_b32_e32 v238, 0x70000, v128
	v_and_b32_e32 v239, 64, v128
	v_lshl_or_b32 v238, v239, 4, v238
	v_and_b32_e32 v239, 63, v136
	v_lshl_or_b32 v128, v239, 4, v238
	global_load_lds_dwordx4 v130, s[10:11]
	s_add_i32 m0, s25, 0x16000
	s_add_u32 s36, s14, s8
	s_addc_u32 s37, s15, s9
	s_add_i32 s33, s25, 0x2000
	global_load_lds_dwordx4 v134, s[10:11]
	s_mov_b32 m0, s25
	s_add_u32 s8, s36, 0x80000
	v_lshl_or_b32 v132, v3, 12, v1
	v_and_b32_e32 v238, 0x70000, v132
	v_and_b32_e32 v239, 64, v132
	v_lshl_or_b32 v238, v239, 4, v238
	v_and_b32_e32 v239, 63, v136
	v_lshl_or_b32 v132, v239, 4, v238
	global_load_lds_dwordx4 v128, s[36:37]
	s_mov_b32 m0, s33
	s_addc_u32 s9, s37, 0
	s_add_i32 s34, s25, 0x4000
	global_load_lds_dwordx4 v132, s[36:37]
	s_mov_b32 m0, s34
	s_add_i32 s35, s25, 0x6000
	global_load_lds_dwordx4 v128, s[8:9]
	s_mov_b32 m0, s35
	v_mov_b32_e32 v131, 0
	global_load_lds_dwordx4 v132, s[8:9]
	v_mov_b32_e32 v135, v131
	v_mov_b32_e32 v129, v131
	v_mov_b32_e32 v133, v131
	s_cmp_eq_u32 s1, 1
	s_mov_b32 s42, 0
	v_lshl_add_u64 v[6:7], s[38:39], 0, v[130:131]
	v_lshl_add_u64 v[4:5], s[38:39], 0, v[134:135]
	v_lshl_add_u64 v[0:1], s[36:37], 0, v[128:129]
	s_cselect_b64 s[8:9], -1, 0
	s_cmp_lg_u32 s1, 1
	v_lshl_add_u64 v[2:3], s[36:37], 0, v[132:133]
	s_cbranch_scc1 .LBB0_827
.LBB0_827:
	s_lshl_b32 s2, s2, 5
	s_mov_b64 s[10:11], 0x80
	s_mov_b64 s[98:99], 0x800
	s_and_b32 s18, s2, 0x60
	s_add_i32 m0, s25, 0x18000
	v_lshl_add_u64 v[6:7], v[6:7], 0, s[10:11]
	s_lshl_b32 s13, s1, 13
	s_lshl_b32 s19, s18, 7
	s_waitcnt vmcnt(2)
	s_barrier
	global_load_lds_dwordx4 v[6:7], off
	v_lshl_add_u64 v[4:5], v[4:5], 0, s[10:11]
	s_add_i32 m0, s25, 0x1a000
	s_add_i32 s43, s25, 0x8000
	s_add_i32 s44, s25, 0xa000
	global_load_lds_dwordx4 v[4:5], off
	v_lshl_add_u64 v[0:1], v[0:1], 0, s[98:99]
	s_mov_b32 m0, s43
	s_add_u32 s16, s38, 0x80080
	global_load_lds_dwordx4 v[0:1], off
	v_lshl_add_u64 v[0:1], v[2:3], 0, s[98:99]
	s_mov_b32 m0, s44
	s_addc_u32 s17, s39, 0
	global_load_lds_dwordx4 v[0:1], off
	s_add_i32 m0, s25, 0x1c000
	v_lshl_add_u64 v[0:1], s[16:17], 0, v[130:131]
	global_load_lds_dwordx4 v[0:1], off
	v_lshl_add_u64 v[0:1], s[16:17], 0, v[134:135]
	s_add_i32 m0, s25, 0x1e000
	s_sext_i32_i16 s2, s0
	global_load_lds_dwordx4 v[0:1], off
	v_and_b32_e32 v0, 15, v136
	v_lshlrev_b32_e32 v1, 1, v11
	v_lshlrev_b32_e32 v2, 2, v136
	v_lshlrev_b32_e32 v3, 6, v136
	s_movk_i32 s0, 0x3c0
	v_lshl_or_b32 v137, s1, 6, v0
	v_lshl_or_b32 v0, v0, 6, v1
	v_and_b32_e32 v2, 32, v2
	v_and_or_b32 v1, v3, s0, v1
	v_bitop3_b32 v153, s19, v1, v2 bitop3:0xf6
	v_lshlrev_b32_e32 v1, 9, v136
	v_bitop3_b32 v0, v0, s13, v2 bitop3:0xde
	v_and_b32_e32 v1, 0x70000, v1
	v_lshlrev_b32_e32 v2, 12, v10
	v_or3_b32 v1, v8, v1, v2
	v_add_u32_e32 v138, v1, v9
	v_and_b32_e32 v238, 0x70000, v138
	v_and_b32_e32 v239, 64, v138
	v_lshl_or_b32 v238, v239, 4, v238
	v_and_b32_e32 v239, 63, v136
	v_lshl_or_b32 v138, v239, 4, v238
	v_lshlrev_b32_e32 v1, 5, v12
	s_waitcnt vmcnt(6)
	s_cmpk_lt_u32 s12, 0x100
	v_and_b32_e32 v1, 0xf0000, v1
	s_cselect_b64 s[12:13], -1, 0
	v_or3_b32 v1, v8, v1, v2
	s_add_i32 s46, 0, 0x10000
	s_add_i32 s47, 0, 0x14000
	s_ashr_i32 s45, s3, 31
	v_or_b32_e32 v154, s18, v11
	v_mov_b32_e32 v139, v131
	v_add_u32_e32 v140, v1, v9
	v_and_b32_e32 v238, 0x70000, v140
	v_and_b32_e32 v239, 64, v140
	v_lshl_or_b32 v238, v239, 4, v238
	v_and_b32_e32 v239, 63, v136
	v_lshl_or_b32 v140, v239, 4, v238
	v_mov_b32_e32 v141, v131
	v_mov_b64_e32 v[142:143], 0x1000
	v_mov_b64_e32 v[144:145], 0xfff
	v_add_u32_e32 v155, s46, v153
	v_add_u32_e32 v156, s47, v153
	v_and_b32_e32 v157, 0xffffe000, v0
	v_and_b32_e32 v238, 63, v136
	v_lshl_or_b32 v157, v238, 4, v157
	v_mov_b32_e32 v158, 0x358637bd
	s_mov_b32 s50, 0x800000
	s_barrier
	s_branch .LBB0_830

;     __device__ bool next(int i, Unit& u) const { return at((long)i * G + c, u); }
;     __device__ bool next(int i, Unit& u) const { if (i > 0) return false; u.pm = pm; u.pn = pn; u.g = 0; u.nt = nt; u.k0 = 0; u.part = -1; return true; }
; #define PG8_STAGE(bufoff, gbase, voff) do { _Pragma("unroll") for (int _i = 0; _i < 2; ++_i) \
;         __builtin_amdgcn_global_load_lds((const unsigned*)((const char*)(gbase) + (voff)[_i]), (LAS unsigned*)(lds + (bufoff) + ldsw + _i * 8192), 16, 0, 0); } while (0)
; #define PG8_LDA(dst, b, h) do { _Pragma("unroll") for (int m = 0; m < 4; ++m) _Pragma("unroll") for (int k = 0; k < 2; ++k) dst[m][k] = *(const LAS bf16x8*)(lds + PG8_SA(b, h) + aoff + m * 2048 + k * 1024); } while (0)
; #define PG8_LDB(dst, b, h) do { _Pragma("unroll") for (int n = 0; n < 2; ++n) _Pragma("unroll") for (int k = 0; k < 2; ++k) dst[n][k] = *(const LAS bf16x8*)(lds + PG8_SB(b, h) + boff + n * 2048 + k * 1024); } while (0)
; #define PG8_WAIT_V(n) asm volatile("s_waitcnt vmcnt(" #n ")" ::: "memory")
; template <class Epi, class Sched>
; __device__ __forceinline__ void gemm_phase(LAS unsigned char* lds, const Gemm g, const Sched& S, const Epi& E) {
;     ...
;     for (;;) {
;         const bool has_next = S.next(ui + 1, nxt);
;         const char* nA = has_next ? PG8_ABASE(nxt) : cA; const char* nB = has_next ? PG8_BBASE(nxt) : cB;
;         const int nt = cur.nt;
;         for (int t = 0; t < nt; t += 2) {
;             const bool last = (t == nt - 2);
;             const char* a1 = cA + (size_t)(t + 1) * kstep;
;             const char* a2 = last ? nA : cA + (size_t)(t + 2) * kstep; const char* b2 = last ? nB : cB + (size_t)(t + 2) * kstep;
;             const char* a3 = a2 + kstep; const char* b3 = b2 + kstep;
;             PG8_LDB(B0, 0, 0); PG8_LDB(B1, 0, 1); PG8_SCHED; PG8_LDA(At, 0, 0); PG8_STAGE(PG8_SA(1, 1), a1 + hstepA, voffA);
;             PG8_WAIT_V(8); PG8_WAIT_L(0); PG8_BAR; PG8_MMA(0, 0, At, B0); PG8_MMA(0, 1, At, B1); PG8_BAR; PG8_SCHED;
;     ...
; #pragma unroll
;         for (int a = 0; a < 2; ++a)
; #pragma unroll
;             for (int b = 0; b < 2; ++b)
; #pragma unroll
;                 for (int m = 0; m < 4; ++m)
; #pragma unroll
;                     for (int n = 0; n < 2; ++n) acc[a][b][m][n] = (f32x4){0.f, 0.f, 0.f, 0.f};
;         cur = nxt; cA = nA; cB = nB; ++ui;
;         if (wr == 1) PG8_BAR;
.LBB0_836:
	s_ashr_i32 s19, s18, 31
	s_lshl_b64 s[20:21], s[18:19], 20
	s_add_u32 s20, s14, s20
	s_addc_u32 s21, s15, s21
	s_and_b64 s[22:23], s[0:1], exec
	s_cselect_b32 s19, s21, s37
	s_cselect_b32 s51, s20, s36
	s_ashr_i32 s17, s16, 31
	s_lshl_b64 s[22:23], s[16:17], 20
	s_add_u32 s22, s88, s22
	s_addc_u32 s23, s89, s23
	s_and_b64 s[40:41], s[0:1], exec
	s_cselect_b32 s17, s23, s39
	s_cselect_b32 s52, s22, s38
	s_add_u32 s36, s36, 0x80800
	s_addc_u32 s37, s37, 0
	s_add_u32 s53, s38, 0x100
	v_mov_b32_e32 v0, 0
	s_addc_u32 s54, s39, 0
	s_mov_b32 s55, -2
	v_mov_b32_e32 v1, v0
	v_mov_b32_e32 v2, v0
	v_mov_b32_e32 v3, v0
	v_mov_b32_e32 v4, v0
	v_mov_b32_e32 v5, v0
	v_mov_b32_e32 v6, v0
	v_mov_b32_e32 v7, v0
	v_mov_b32_e32 v16, v0
	v_mov_b32_e32 v17, v0
	v_mov_b32_e32 v18, v0
	v_mov_b32_e32 v19, v0
	v_mov_b32_e32 v20, v0
	v_mov_b32_e32 v21, v0
	v_mov_b32_e32 v22, v0
	v_mov_b32_e32 v23, v0
	s_waitcnt vmcnt(0)
	v_mov_b32_e32 v32, v0
	v_mov_b32_e32 v33, v0
	v_mov_b32_e32 v34, v0
	v_mov_b32_e32 v35, v0
	v_mov_b32_e32 v36, v0
	v_mov_b32_e32 v37, v0
	v_mov_b32_e32 v38, v0
	v_mov_b32_e32 v39, v0
	v_mov_b32_e32 v48, v0
	v_mov_b32_e32 v49, v0
	v_mov_b32_e32 v50, v0
	v_mov_b32_e32 v51, v0
	v_mov_b32_e32 v52, v0
	v_mov_b32_e32 v53, v0
	v_mov_b32_e32 v54, v0
	v_mov_b32_e32 v55, v0
	v_mov_b32_e32 v8, v0
	v_mov_b32_e32 v9, v0
	v_mov_b32_e32 v10, v0
	v_mov_b32_e32 v11, v0
	v_mov_b32_e32 v12, v0
	v_mov_b32_e32 v13, v0
	v_mov_b32_e32 v14, v0
	v_mov_b32_e32 v15, v0
	v_mov_b32_e32 v24, v0
	v_mov_b32_e32 v25, v0
	v_mov_b32_e32 v26, v0
	v_mov_b32_e32 v27, v0
	v_mov_b32_e32 v28, v0
	v_mov_b32_e32 v29, v0
	v_mov_b32_e32 v30, v0
	v_mov_b32_e32 v31, v0
	v_mov_b32_e32 v40, v0
	v_mov_b32_e32 v41, v0
	v_mov_b32_e32 v42, v0
	v_mov_b32_e32 v43, v0
	v_mov_b32_e32 v44, v0
	v_mov_b32_e32 v45, v0
	v_mov_b32_e32 v46, v0
	v_mov_b32_e32 v47, v0
	v_mov_b32_e32 v56, v0
	v_mov_b32_e32 v57, v0
	v_mov_b32_e32 v58, v0
	v_mov_b32_e32 v59, v0
	v_mov_b32_e32 v60, v0
	v_mov_b32_e32 v61, v0
	v_mov_b32_e32 v62, v0
	v_mov_b32_e32 v63, v0
	v_mov_b32_e32 v64, v0
	v_mov_b32_e32 v65, v0
	v_mov_b32_e32 v66, v0
	v_mov_b32_e32 v67, v0
	v_mov_b32_e32 v68, v0
	v_mov_b32_e32 v69, v0
	v_mov_b32_e32 v70, v0
	v_mov_b32_e32 v71, v0
	v_mov_b32_e32 v80, v0
	v_mov_b32_e32 v81, v0
	v_mov_b32_e32 v82, v0
	v_mov_b32_e32 v83, v0
	v_mov_b32_e32 v84, v0
	v_mov_b32_e32 v85, v0
	v_mov_b32_e32 v86, v0
	v_mov_b32_e32 v87, v0
	v_mov_b32_e32 v96, v0
	v_mov_b32_e32 v97, v0
	v_mov_b32_e32 v98, v0
	v_mov_b32_e32 v99, v0
	v_mov_b32_e32 v100, v0
	v_mov_b32_e32 v101, v0
	v_mov_b32_e32 v102, v0
	v_mov_b32_e32 v103, v0
	v_mov_b32_e32 v112, v0
	v_mov_b32_e32 v113, v0
	v_mov_b32_e32 v114, v0
	v_mov_b32_e32 v115, v0
	v_mov_b32_e32 v116, v0
	v_mov_b32_e32 v117, v0
	v_mov_b32_e32 v118, v0
	v_mov_b32_e32 v119, v0
	v_mov_b32_e32 v72, v0
	v_mov_b32_e32 v73, v0
	v_mov_b32_e32 v74, v0
	v_mov_b32_e32 v75, v0
	v_mov_b32_e32 v76, v0
	v_mov_b32_e32 v77, v0
	v_mov_b32_e32 v78, v0
	v_mov_b32_e32 v79, v0
	v_mov_b32_e32 v88, v0
	v_mov_b32_e32 v89, v0
	v_mov_b32_e32 v90, v0
	v_mov_b32_e32 v91, v0
	v_mov_b32_e32 v92, v0
	v_mov_b32_e32 v93, v0
	v_mov_b32_e32 v94, v0
	v_mov_b32_e32 v95, v0
	v_mov_b32_e32 v104, v0
	v_mov_b32_e32 v105, v0
	v_mov_b32_e32 v106, v0
	v_mov_b32_e32 v107, v0
	v_mov_b32_e32 v108, v0
	v_mov_b32_e32 v109, v0
	v_mov_b32_e32 v110, v0
	v_mov_b32_e32 v111, v0
	v_mov_b32_e32 v120, v0
	v_mov_b32_e32 v121, v0
	v_mov_b32_e32 v122, v0
	v_mov_b32_e32 v123, v0
	v_mov_b32_e32 v124, v0
	v_mov_b32_e32 v125, v0
	v_mov_b32_e32 v126, v0
	v_mov_b32_e32 v127, v0
	s_cmp_lg_u64 s[8:9], 0
	s_cbranch_scc0 .Ledge_p7
	s_barrier
.Ledge_p7:
.LBB0_837:
	ds_read_b128 v[146:149], v155
	ds_read_b128 v[160:163], v155 offset:1024
	ds_read_b128 v[164:167], v155 offset:2048
	ds_read_b128 v[168:171], v155 offset:3072
	ds_read_b128 v[172:175], v156
	ds_read_b128 v[176:179], v156 offset:1024
	ds_read_b128 v[180:183], v156 offset:2048
	ds_read_b128 v[184:187], v156 offset:3072
	s_add_u32 s38, s36, 0xfff80800
	s_addc_u32 s39, s37, -1
	s_cmp_eq_u32 s55, 28
	s_cselect_b32 s41, s19, s39
	s_cselect_b32 s40, s51, s38
	s_cselect_b32 s39, s17, s54
	s_cselect_b32 s38, s52, s53
	v_lshl_add_u64 v[150:151], s[36:37], 0, v[138:139]
	s_add_i32 m0, s25, 0xc000
	ds_read_b128 v[188:191], v157
	ds_read_b128 v[192:195], v157 offset:1024
	ds_read_b128 v[196:199], v157 offset:2048
	ds_read_b128 v[200:203], v157 offset:3072
	ds_read_b128 v[204:207], v157 offset:4096
	ds_read_b128 v[208:211], v157 offset:5120
	ds_read_b128 v[212:215], v157 offset:6144
	ds_read_b128 v[216:219], v157 offset:7168
	global_load_lds_dwordx4 v[150:151], off
	v_lshl_add_u64 v[150:151], s[36:37], 0, v[140:141]
	s_add_i32 m0, s25, 0xe000
	s_nop 0
	global_load_lds_dwordx4 v[150:151], off
	s_waitcnt vmcnt(8)
	s_waitcnt lgkmcnt(0)
	s_barrier
; #define PG8_STAGE(bufoff, gbase, voff) do { _Pragma("unroll") for (int _i = 0; _i < 2; ++_i) \
;         __builtin_amdgcn_global_load_lds((const unsigned*)((const char*)(gbase) + (voff)[_i]), (LAS unsigned*)(lds + (bufoff) + ldsw + _i * 8192), 16, 0, 0); } while (0)
; #define PG8_LDA(dst, b, h) do { _Pragma("unroll") for (int m = 0; m < 4; ++m) _Pragma("unroll") for (int k = 0; k < 2; ++k) dst[m][k] = *(const LAS bf16x8*)(lds + PG8_SA(b, h) + aoff + m * 2048 + k * 1024); } while (0)
; #define PG8_MMA(ai, bj, At, Bt) do { __builtin_amdgcn_s_setprio(1); _Pragma("unroll") for (int m = 0; m < 4; ++m) _Pragma("unroll") for (int n = 0; n < 2; ++n) _Pragma("unroll") for (int k = 0; k < 2; ++k) \
;         acc[ai][bj][m][n] = __builtin_amdgcn_mfma_f32_16x16x32_bf16(Bt[n][k], At[m][k], acc[ai][bj][m][n], 0, 0, 0); __builtin_amdgcn_s_setprio(0); } while (0)
; #define PG8_WAIT_V(n) asm volatile("s_waitcnt vmcnt(" #n ")" ::: "memory")
; #define PG8_WAIT_L(n) asm volatile("s_waitcnt lgkmcnt(" #n ")" ::: "memory")
; #define PG8_BAR __builtin_amdgcn_s_barrier()
; #define PG8_SCHED __builtin_amdgcn_sched_barrier(0)
; template <class Epi, class Sched>
; __device__ __forceinline__ void gemm_phase(LAS unsigned char* lds, const Gemm g, const Sched& S, const Epi& E) {
;     ...
;             PG8_WAIT_V(8); PG8_WAIT_L(0); PG8_BAR; PG8_MMA(0, 0, At, B0); PG8_MMA(0, 1, At, B1); PG8_BAR; PG8_SCHED;
;             PG8_LDA(At, 0, 1); PG8_STAGE(PG8_SB(0, 0), b2, voffB); PG8_STAGE(PG8_SB(0, 1), b2 + hstepB, voffB); PG8_STAGE(PG8_SA(0, 0), a2, voffA);
;             PG8_WAIT_V(8); PG8_WAIT_L(0); PG8_BAR; PG8_MMA(1, 0, At, B0); PG8_MMA(1, 1, At, B1); PG8_BAR; PG8_SCHED;
	s_setprio 1
	s_waitcnt lgkmcnt(0)
	v_mfma_f32_16x16x32_bf16 v[124:127], v[146:149], v[188:191], v[124:127]
	v_mfma_f32_16x16x32_bf16 v[120:123], v[164:167], v[188:191], v[120:123]
	v_mfma_f32_16x16x32_bf16 v[108:111], v[146:149], v[196:199], v[108:111]
	v_mfma_f32_16x16x32_bf16 v[104:107], v[164:167], v[196:199], v[104:107]
	v_mfma_f32_16x16x32_bf16 v[92:95], v[146:149], v[204:207], v[92:95]
	v_mfma_f32_16x16x32_bf16 v[88:91], v[164:167], v[204:207], v[88:91]
	v_mfma_f32_16x16x32_bf16 v[76:79], v[146:149], v[212:215], v[76:79]
	v_mfma_f32_16x16x32_bf16 v[72:75], v[164:167], v[212:215], v[72:75]
	v_mfma_f32_16x16x32_bf16 v[124:127], v[160:163], v[192:195], v[124:127]
	v_mfma_f32_16x16x32_bf16 v[120:123], v[168:171], v[192:195], v[120:123]
	v_mfma_f32_16x16x32_bf16 v[108:111], v[160:163], v[200:203], v[108:111]
	v_mfma_f32_16x16x32_bf16 v[104:107], v[168:171], v[200:203], v[104:107]
	v_mfma_f32_16x16x32_bf16 v[92:95], v[160:163], v[208:211], v[92:95]
	v_mfma_f32_16x16x32_bf16 v[88:91], v[168:171], v[208:211], v[88:91]
	v_mfma_f32_16x16x32_bf16 v[76:79], v[160:163], v[216:219], v[76:79]
	v_mfma_f32_16x16x32_bf16 v[72:75], v[168:171], v[216:219], v[72:75]
	s_setprio 0
	s_setprio 1
	v_mfma_f32_16x16x32_bf16 v[116:119], v[172:175], v[188:191], v[116:119]
	v_mfma_f32_16x16x32_bf16 v[112:115], v[180:183], v[188:191], v[112:115]
	v_mfma_f32_16x16x32_bf16 v[100:103], v[172:175], v[196:199], v[100:103]
	v_mfma_f32_16x16x32_bf16 v[96:99], v[180:183], v[196:199], v[96:99]
	v_mfma_f32_16x16x32_bf16 v[84:87], v[172:175], v[204:207], v[84:87]
	v_mfma_f32_16x16x32_bf16 v[80:83], v[180:183], v[204:207], v[80:83]
	v_mfma_f32_16x16x32_bf16 v[68:71], v[172:175], v[212:215], v[68:71]
	v_mfma_f32_16x16x32_bf16 v[64:67], v[180:183], v[212:215], v[64:67]
	v_mfma_f32_16x16x32_bf16 v[116:119], v[176:179], v[192:195], v[116:119]
	v_mfma_f32_16x16x32_bf16 v[112:115], v[184:187], v[192:195], v[112:115]
	v_mfma_f32_16x16x32_bf16 v[100:103], v[176:179], v[200:203], v[100:103]
	v_mfma_f32_16x16x32_bf16 v[96:99], v[184:187], v[200:203], v[96:99]
	v_mfma_f32_16x16x32_bf16 v[84:87], v[176:179], v[208:211], v[84:87]
	v_mfma_f32_16x16x32_bf16 v[80:83], v[184:187], v[208:211], v[80:83]
	v_mfma_f32_16x16x32_bf16 v[68:71], v[176:179], v[216:219], v[68:71]
	v_mfma_f32_16x16x32_bf16 v[64:67], v[184:187], v[216:219], v[64:67]
	s_setprio 0
	s_barrier
	s_add_i32 s48, s46, s5
	v_lshl_add_u64 v[150:151], s[38:39], 0, v[130:131]
	s_mov_b32 m0, s48
	ds_read_b128 v[188:191], v157 offset:16384
	ds_read_b128 v[192:195], v157 offset:17408
	ds_read_b128 v[196:199], v157 offset:18432
	ds_read_b128 v[200:203], v157 offset:19456
	ds_read_b128 v[204:207], v157 offset:20480
	ds_read_b128 v[208:211], v157 offset:21504
	ds_read_b128 v[212:215], v157 offset:22528
	ds_read_b128 v[216:219], v157 offset:23552
	global_load_lds_dwordx4 v[150:151], off
	s_add_i32 m0, s48, 0x2000
	s_add_u32 s48, s38, 0x80000
	v_lshl_add_u64 v[220:221], s[38:39], 0, v[134:135]
	s_addc_u32 s49, s39, 0
	s_add_i32 s56, s47, s5
	global_load_lds_dwordx4 v[220:221], off
	v_lshl_add_u64 v[222:223], s[48:49], 0, v[130:131]
	s_mov_b32 m0, s56
	v_lshl_add_u64 v[224:225], s[40:41], 0, v[132:133]
	global_load_lds_dwordx4 v[222:223], off
	v_lshl_add_u64 v[222:223], s[48:49], 0, v[134:135]
	s_add_i32 m0, s56, 0x2000
	s_nop 0
	global_load_lds_dwordx4 v[222:223], off
	v_lshl_add_u64 v[222:223], s[40:41], 0, v[128:129]
	s_mov_b32 m0, s25
	s_nop 0
	global_load_lds_dwordx4 v[222:223], off
	s_mov_b32 m0, s33
	s_nop 0
	global_load_lds_dwordx4 v[224:225], off
	s_waitcnt vmcnt(8)
	s_waitcnt lgkmcnt(0)
	s_barrier
	s_setprio 1
	s_waitcnt lgkmcnt(0)
	v_mfma_f32_16x16x32_bf16 v[60:63], v[146:149], v[188:191], v[60:63]
	v_mfma_f32_16x16x32_bf16 v[56:59], v[164:167], v[188:191], v[56:59]
	v_mfma_f32_16x16x32_bf16 v[44:47], v[146:149], v[196:199], v[44:47]
	v_mfma_f32_16x16x32_bf16 v[40:43], v[164:167], v[196:199], v[40:43]
	v_mfma_f32_16x16x32_bf16 v[28:31], v[146:149], v[204:207], v[28:31]
	v_mfma_f32_16x16x32_bf16 v[24:27], v[164:167], v[204:207], v[24:27]
	v_mfma_f32_16x16x32_bf16 v[12:15], v[146:149], v[212:215], v[12:15]
	v_mfma_f32_16x16x32_bf16 v[8:11], v[164:167], v[212:215], v[8:11]
	v_mfma_f32_16x16x32_bf16 v[60:63], v[160:163], v[192:195], v[60:63]
	v_mfma_f32_16x16x32_bf16 v[56:59], v[168:171], v[192:195], v[56:59]
	v_mfma_f32_16x16x32_bf16 v[44:47], v[160:163], v[200:203], v[44:47]
	v_mfma_f32_16x16x32_bf16 v[40:43], v[168:171], v[200:203], v[40:43]
	v_mfma_f32_16x16x32_bf16 v[28:31], v[160:163], v[208:211], v[28:31]
	v_mfma_f32_16x16x32_bf16 v[24:27], v[168:171], v[208:211], v[24:27]
	v_mfma_f32_16x16x32_bf16 v[12:15], v[160:163], v[216:219], v[12:15]
	v_mfma_f32_16x16x32_bf16 v[8:11], v[168:171], v[216:219], v[8:11]
	s_setprio 0
	s_setprio 1
	v_mfma_f32_16x16x32_bf16 v[52:55], v[172:175], v[188:191], v[52:55]
	v_mfma_f32_16x16x32_bf16 v[48:51], v[180:183], v[188:191], v[48:51]
	v_mfma_f32_16x16x32_bf16 v[36:39], v[172:175], v[196:199], v[36:39]
	v_mfma_f32_16x16x32_bf16 v[32:35], v[180:183], v[196:199], v[32:35]
	v_mfma_f32_16x16x32_bf16 v[20:23], v[172:175], v[204:207], v[20:23]
	v_mfma_f32_16x16x32_bf16 v[16:19], v[180:183], v[204:207], v[16:19]
	v_mfma_f32_16x16x32_bf16 v[4:7], v[172:175], v[212:215], v[4:7]
	v_mfma_f32_16x16x32_bf16 v[0:3], v[180:183], v[212:215], v[0:3]
	v_mfma_f32_16x16x32_bf16 v[52:55], v[176:179], v[192:195], v[52:55]
	v_mfma_f32_16x16x32_bf16 v[48:51], v[184:187], v[192:195], v[48:51]
	v_mfma_f32_16x16x32_bf16 v[36:39], v[176:179], v[200:203], v[36:39]
	v_mfma_f32_16x16x32_bf16 v[32:35], v[184:187], v[200:203], v[32:35]
	v_mfma_f32_16x16x32_bf16 v[20:23], v[176:179], v[208:211], v[20:23]
	v_mfma_f32_16x16x32_bf16 v[16:19], v[184:187], v[208:211], v[16:19]
	v_mfma_f32_16x16x32_bf16 v[4:7], v[176:179], v[216:219], v[4:7]
	v_mfma_f32_16x16x32_bf16 v[0:3], v[184:187], v[216:219], v[0:3]
	s_setprio 0
	s_barrier
; #define PG8_STAGE(bufoff, gbase, voff) do { _Pragma("unroll") for (int _i = 0; _i < 2; ++_i) \
;         __builtin_amdgcn_global_load_lds((const unsigned*)((const char*)(gbase) + (voff)[_i]), (LAS unsigned*)(lds + (bufoff) + ldsw + _i * 8192), 16, 0, 0); } while (0)
; #define PG8_LDA(dst, b, h) do { _Pragma("unroll") for (int m = 0; m < 4; ++m) _Pragma("unroll") for (int k = 0; k < 2; ++k) dst[m][k] = *(const LAS bf16x8*)(lds + PG8_SA(b, h) + aoff + m * 2048 + k * 1024); } while (0)
; #define PG8_LDB(dst, b, h) do { _Pragma("unroll") for (int n = 0; n < 2; ++n) _Pragma("unroll") for (int k = 0; k < 2; ++k) dst[n][k] = *(const LAS bf16x8*)(lds + PG8_SB(b, h) + boff + n * 2048 + k * 1024); } while (0)
; #define PG8_MMA(ai, bj, At, Bt) do { __builtin_amdgcn_s_setprio(1); _Pragma("unroll") for (int m = 0; m < 4; ++m) _Pragma("unroll") for (int n = 0; n < 2; ++n) _Pragma("unroll") for (int k = 0; k < 2; ++k) \
;         acc[ai][bj][m][n] = __builtin_amdgcn_mfma_f32_16x16x32_bf16(Bt[n][k], At[m][k], acc[ai][bj][m][n], 0, 0, 0); __builtin_amdgcn_s_setprio(0); } while (0)
; #define PG8_WAIT_V(n) asm volatile("s_waitcnt vmcnt(" #n ")" ::: "memory")
; #define PG8_WAIT_L(n) asm volatile("s_waitcnt lgkmcnt(" #n ")" ::: "memory")
; #define PG8_BAR __builtin_amdgcn_s_barrier()
; #define PG8_SCHED __builtin_amdgcn_sched_barrier(0)
; template <class Epi, class Sched>
; __device__ __forceinline__ void gemm_phase(LAS unsigned char* lds, const Gemm g, const Sched& S, const Epi& E) {
;     ...
;             PG8_LDB(B0, 1, 0); PG8_LDB(B1, 1, 1); PG8_SCHED; PG8_LDA(At, 1, 0); PG8_STAGE(PG8_SA(0, 1), a2 + hstepA, voffA);
;             PG8_WAIT_V(8); PG8_WAIT_L(0); PG8_BAR; PG8_MMA(0, 0, At, B0); PG8_MMA(0, 1, At, B1); PG8_BAR; PG8_SCHED;
;             PG8_LDA(At, 1, 1); PG8_STAGE(PG8_SB(1, 0), b3, voffB); PG8_STAGE(PG8_SB(1, 1), b3 + hstepB, voffB); PG8_STAGE(PG8_SA(1, 0), a3, voffA);
;             PG8_WAIT_V(8); PG8_WAIT_L(0); PG8_BAR; PG8_MMA(1, 0, At, B0); PG8_MMA(1, 1, At, B1); PG8_BAR; PG8_SCHED;
	s_add_i32 s48, 0, 0x18000
	v_add_u32_e32 v159, s48, v153
	s_add_i32 s49, 0, 0x1c000
	ds_read_b128 v[146:149], v159
	ds_read_b128 v[160:163], v159 offset:1024
	ds_read_b128 v[164:167], v159 offset:2048
	ds_read_b128 v[168:171], v159 offset:3072
	v_add_u32_e32 v159, s49, v153
	ds_read_b128 v[172:175], v159
	ds_read_b128 v[176:179], v159 offset:1024
	ds_read_b128 v[180:183], v159 offset:2048
	ds_read_b128 v[184:187], v159 offset:3072
	s_add_u32 s40, s40, 0x80000
	s_addc_u32 s41, s41, 0
	s_mov_b32 m0, s34
	v_lshl_add_u64 v[226:227], s[40:41], 0, v[128:129]
	ds_read_b128 v[188:191], v157 offset:32768
	ds_read_b128 v[192:195], v157 offset:33792
	ds_read_b128 v[196:199], v157 offset:34816
	ds_read_b128 v[200:203], v157 offset:35840
	ds_read_b128 v[204:207], v157 offset:36864
	ds_read_b128 v[208:211], v157 offset:37888
	ds_read_b128 v[212:215], v157 offset:38912
	ds_read_b128 v[216:219], v157 offset:39936
	global_load_lds_dwordx4 v[226:227], off
	v_lshl_add_u64 v[226:227], s[40:41], 0, v[132:133]
	s_mov_b32 m0, s35
	s_nop 0
	global_load_lds_dwordx4 v[226:227], off
	s_waitcnt vmcnt(8)
	s_waitcnt lgkmcnt(0)
	s_barrier
	s_setprio 1
	s_waitcnt lgkmcnt(0)
	v_mfma_f32_16x16x32_bf16 v[124:127], v[146:149], v[188:191], v[124:127]
	v_mfma_f32_16x16x32_bf16 v[120:123], v[164:167], v[188:191], v[120:123]
	v_mfma_f32_16x16x32_bf16 v[108:111], v[146:149], v[196:199], v[108:111]
	v_mfma_f32_16x16x32_bf16 v[104:107], v[164:167], v[196:199], v[104:107]
	v_mfma_f32_16x16x32_bf16 v[92:95], v[146:149], v[204:207], v[92:95]
	v_mfma_f32_16x16x32_bf16 v[88:91], v[164:167], v[204:207], v[88:91]
	v_mfma_f32_16x16x32_bf16 v[76:79], v[146:149], v[212:215], v[76:79]
	v_mfma_f32_16x16x32_bf16 v[72:75], v[164:167], v[212:215], v[72:75]
	v_mfma_f32_16x16x32_bf16 v[124:127], v[160:163], v[192:195], v[124:127]
	v_mfma_f32_16x16x32_bf16 v[120:123], v[168:171], v[192:195], v[120:123]
	v_mfma_f32_16x16x32_bf16 v[108:111], v[160:163], v[200:203], v[108:111]
	v_mfma_f32_16x16x32_bf16 v[104:107], v[168:171], v[200:203], v[104:107]
	v_mfma_f32_16x16x32_bf16 v[92:95], v[160:163], v[208:211], v[92:95]
	v_mfma_f32_16x16x32_bf16 v[88:91], v[168:171], v[208:211], v[88:91]
	v_mfma_f32_16x16x32_bf16 v[76:79], v[160:163], v[216:219], v[76:79]
	v_mfma_f32_16x16x32_bf16 v[72:75], v[168:171], v[216:219], v[72:75]
	s_setprio 0
	s_setprio 1
	v_mfma_f32_16x16x32_bf16 v[116:119], v[172:175], v[188:191], v[116:119]
	v_mfma_f32_16x16x32_bf16 v[112:115], v[180:183], v[188:191], v[112:115]
	v_mfma_f32_16x16x32_bf16 v[100:103], v[172:175], v[196:199], v[100:103]
	v_mfma_f32_16x16x32_bf16 v[96:99], v[180:183], v[196:199], v[96:99]
	v_mfma_f32_16x16x32_bf16 v[84:87], v[172:175], v[204:207], v[84:87]
	v_mfma_f32_16x16x32_bf16 v[80:83], v[180:183], v[204:207], v[80:83]
	v_mfma_f32_16x16x32_bf16 v[68:71], v[172:175], v[212:215], v[68:71]
	v_mfma_f32_16x16x32_bf16 v[64:67], v[180:183], v[212:215], v[64:67]
	v_mfma_f32_16x16x32_bf16 v[116:119], v[176:179], v[192:195], v[116:119]
	v_mfma_f32_16x16x32_bf16 v[112:115], v[184:187], v[192:195], v[112:115]
	v_mfma_f32_16x16x32_bf16 v[100:103], v[176:179], v[200:203], v[100:103]
	v_mfma_f32_16x16x32_bf16 v[96:99], v[184:187], v[200:203], v[96:99]
	v_mfma_f32_16x16x32_bf16 v[84:87], v[176:179], v[208:211], v[84:87]
	v_mfma_f32_16x16x32_bf16 v[80:83], v[184:187], v[208:211], v[80:83]
	v_mfma_f32_16x16x32_bf16 v[68:71], v[176:179], v[216:219], v[68:71]
	v_mfma_f32_16x16x32_bf16 v[64:67], v[184:187], v[216:219], v[64:67]
	s_setprio 0
	s_barrier
	s_add_i32 s40, s48, s5
	v_lshl_add_u64 v[150:151], v[150:151], 0, s[10:11]
	s_mov_b32 m0, s40
	ds_read_b128 v[188:191], v157 offset:49152
	ds_read_b128 v[192:195], v157 offset:50176
	ds_read_b128 v[196:199], v157 offset:51200
	ds_read_b128 v[200:203], v157 offset:52224
	ds_read_b128 v[204:207], v157 offset:53248
	ds_read_b128 v[208:211], v157 offset:54272
	ds_read_b128 v[212:215], v157 offset:55296
	ds_read_b128 v[216:219], v157 offset:56320
	global_load_lds_dwordx4 v[150:151], off
	s_add_i32 m0, s40, 0x2000
	s_add_u32 s38, s38, 0x80080
	v_lshl_add_u64 v[150:151], v[220:221], 0, s[10:11]
	s_addc_u32 s39, s39, 0
	s_add_i32 s40, s49, s5
	global_load_lds_dwordx4 v[150:151], off
	v_lshl_add_u64 v[150:151], s[38:39], 0, v[130:131]
	s_mov_b32 m0, s40
	s_nop 0
	global_load_lds_dwordx4 v[150:151], off
	v_lshl_add_u64 v[150:151], s[38:39], 0, v[134:135]
	s_add_i32 m0, s40, 0x2000
	s_nop 0
	global_load_lds_dwordx4 v[150:151], off
	v_lshl_add_u64 v[150:151], v[222:223], 0, s[98:99]
	s_mov_b32 m0, s43
	s_nop 0
	global_load_lds_dwordx4 v[150:151], off
	v_lshl_add_u64 v[150:151], v[224:225], 0, s[98:99]
	s_mov_b32 m0, s44
	s_nop 0
	global_load_lds_dwordx4 v[150:151], off
	s_waitcnt vmcnt(8)
	s_waitcnt lgkmcnt(0)
	s_barrier
; __device__ __forceinline__ u32x4 pack8(const f32x4 a, const f32x4 b) { u32x4 w; w.x = cvt_pk_bf16(a[0], a[1]); w.y = cvt_pk_bf16(a[2], a[3]); w.z = cvt_pk_bf16(b[0], b[1]); w.w = cvt_pk_bf16(b[2], b[3]); return w; }
; #define PG8_MMA(ai, bj, At, Bt) do { __builtin_amdgcn_s_setprio(1); _Pragma("unroll") for (int m = 0; m < 4; ++m) _Pragma("unroll") for (int n = 0; n < 2; ++n) _Pragma("unroll") for (int k = 0; k < 2; ++k) \
;         acc[ai][bj][m][n] = __builtin_amdgcn_mfma_f32_16x16x32_bf16(Bt[n][k], At[m][k], acc[ai][bj][m][n], 0, 0, 0); __builtin_amdgcn_s_setprio(0); } while (0)
; #define PG8_WAIT_V(n) asm volatile("s_waitcnt vmcnt(" #n ")" ::: "memory")
; #define PG8_WAIT_L(n) asm volatile("s_waitcnt lgkmcnt(" #n ")" ::: "memory")
; #define PG8_BAR __builtin_amdgcn_s_barrier()
; #define PG8_SCHED __builtin_amdgcn_sched_barrier(0)
; template <class Epi, class Sched>
; __device__ __forceinline__ void gemm_phase(LAS unsigned char* lds, const Gemm g, const Sched& S, const Epi& E) {
;     ...
;             PG8_WAIT_V(8); PG8_WAIT_L(0); PG8_BAR; PG8_MMA(1, 0, At, B0); PG8_MMA(1, 1, At, B1); PG8_BAR; PG8_SCHED;
;         }
;         if (wr == 0) PG8_BAR;
;     __device__ __forceinline__ void operator()(AccRef acc, const Unit& u, int wr, int wc, int fr, int fq) const {
; #pragma unroll
;         for (int ai = 0; ai < 2; ++ai)
; #pragma unroll
;             for (int m = 0; m < 4; ++m) { const int row = u.pm * 256 + ai * 128 + wr * 64 + m * 16 + fr;
;                 const float r2 = rsqrtf(ssq[row] * (1.0f / D) + EPS);
; #pragma unroll
;                 for (int bj = 0; bj < 2; ++bj) { const int col = u.pn * 256 + bj * 128 + wc * 32 + 8 * fq;
;                     f32x4 h0 = acc[ai][bj][m][0] * r2, h1 = acc[ai][bj][m][1] * r2;
; #pragma unroll
;                     for (int q = 0; q < 4; ++q) { const float a = fmaxf(h0[q], 0.f), b = fmaxf(h1[q], 0.f); h0[q] = a * a; h1[q] = b * b; }
;                     __builtin_nontemporal_store(pack8(h0, h1), (u32x4*)(HID + (size_t)row * DFF + col)); } }
	s_setprio 1
	s_waitcnt lgkmcnt(0)
	v_mfma_f32_16x16x32_bf16 v[60:63], v[146:149], v[188:191], v[60:63]
	v_mfma_f32_16x16x32_bf16 v[56:59], v[164:167], v[188:191], v[56:59]
	v_mfma_f32_16x16x32_bf16 v[44:47], v[146:149], v[196:199], v[44:47]
	v_mfma_f32_16x16x32_bf16 v[40:43], v[164:167], v[196:199], v[40:43]
	v_mfma_f32_16x16x32_bf16 v[28:31], v[146:149], v[204:207], v[28:31]
	v_mfma_f32_16x16x32_bf16 v[24:27], v[164:167], v[204:207], v[24:27]
	v_mfma_f32_16x16x32_bf16 v[12:15], v[146:149], v[212:215], v[12:15]
	v_mfma_f32_16x16x32_bf16 v[8:11], v[164:167], v[212:215], v[8:11]
	v_mfma_f32_16x16x32_bf16 v[60:63], v[160:163], v[192:195], v[60:63]
	v_mfma_f32_16x16x32_bf16 v[56:59], v[168:171], v[192:195], v[56:59]
	v_mfma_f32_16x16x32_bf16 v[44:47], v[160:163], v[200:203], v[44:47]
	v_mfma_f32_16x16x32_bf16 v[40:43], v[168:171], v[200:203], v[40:43]
	v_mfma_f32_16x16x32_bf16 v[28:31], v[160:163], v[208:211], v[28:31]
	v_mfma_f32_16x16x32_bf16 v[24:27], v[168:171], v[208:211], v[24:27]
	v_mfma_f32_16x16x32_bf16 v[12:15], v[160:163], v[216:219], v[12:15]
	v_mfma_f32_16x16x32_bf16 v[8:11], v[168:171], v[216:219], v[8:11]
	s_setprio 0
	s_setprio 1
	v_mfma_f32_16x16x32_bf16 v[52:55], v[172:175], v[188:191], v[52:55]
	v_mfma_f32_16x16x32_bf16 v[48:51], v[180:183], v[188:191], v[48:51]
	v_mfma_f32_16x16x32_bf16 v[36:39], v[172:175], v[196:199], v[36:39]
	v_mfma_f32_16x16x32_bf16 v[32:35], v[180:183], v[196:199], v[32:35]
	v_mfma_f32_16x16x32_bf16 v[20:23], v[172:175], v[204:207], v[20:23]
	v_mfma_f32_16x16x32_bf16 v[16:19], v[180:183], v[204:207], v[16:19]
	v_mfma_f32_16x16x32_bf16 v[4:7], v[172:175], v[212:215], v[4:7]
	v_mfma_f32_16x16x32_bf16 v[0:3], v[180:183], v[212:215], v[0:3]
	v_mfma_f32_16x16x32_bf16 v[52:55], v[176:179], v[192:195], v[52:55]
	v_mfma_f32_16x16x32_bf16 v[48:51], v[184:187], v[192:195], v[48:51]
	v_mfma_f32_16x16x32_bf16 v[36:39], v[176:179], v[200:203], v[36:39]
	v_mfma_f32_16x16x32_bf16 v[32:35], v[184:187], v[200:203], v[32:35]
	v_mfma_f32_16x16x32_bf16 v[20:23], v[176:179], v[208:211], v[20:23]
	v_mfma_f32_16x16x32_bf16 v[16:19], v[184:187], v[208:211], v[16:19]
	v_mfma_f32_16x16x32_bf16 v[4:7], v[176:179], v[216:219], v[4:7]
	v_mfma_f32_16x16x32_bf16 v[0:3], v[184:187], v[216:219], v[0:3]
	s_setprio 0
	s_barrier
	s_add_i32 s55, s55, 2
	s_add_u32 s36, s36, 0x1000
	s_addc_u32 s37, s37, 0
	s_add_u32 s53, s53, 0x100
	s_addc_u32 s54, s54, 0
	s_cmp_gt_u32 s55, 29
	s_cbranch_scc0 .LBB0_837
	s_and_b64 vcc, exec, s[12:13]
	s_cbranch_vccz .LBB0_840
	s_barrier
.LBB0_840:
	v_lshl_add_u32 v146, s24, 8, v137
	v_and_b32_e32 v146, -16, v146
	v_ashrrev_i32_e32 v147, 31, v146
	v_lshl_add_u64 v[150:151], v[146:147], 2, s[30:31]
	s_nop 0
	v_lshlrev_b64 v[160:161], 14, v[146:147]
	v_lshl_or_b32 v148, s2, 8, v154
	v_readlane_b32 s36, v242, 6
	v_lshrrev_b32_e32 v149, 5, v148
	v_lshlrev_b32_e32 v149, 10, v149
	v_readlane_b32 s37, v242, 7
	v_and_b32_e32 v148, 63, v136
	v_lshl_add_u32 v148, v148, 4, v149
	v_add_u32_e32 v148, 0x1000, v148
	v_mov_b32_e32 v149, 0
	s_nop 0
	v_fmamk_f32 v147, v230, 0x3a000000, v158
	v_mul_f32_e32 v159, 0x4b800000, v147
	v_cmp_gt_f32_e32 vcc, s50, v147
	v_lshl_add_u64 v[160:161], s[36:37], 0, v[160:161]
	v_lshl_add_u64 v[160:161], v[160:161], 0, v[148:149]
	v_cndmask_b32_e32 v147, v147, v159, vcc
	v_rsq_f32_e32 v147, v147
	s_nop 0
	v_mul_f32_e32 v159, 0x45800000, v147
	v_cndmask_b32_e32 v162, v147, v159, vcc
	v_pk_mul_f32 v[126:127], v[126:127], v[162:163] op_sel_hi:[1,0]
	v_pk_mul_f32 v[124:125], v[124:125], v[162:163] op_sel_hi:[1,0]
	v_pk_mul_f32 v[122:123], v[122:123], v[162:163] op_sel_hi:[1,0]
	v_pk_mul_f32 v[120:121], v[120:121], v[162:163] op_sel_hi:[1,0]
	v_pk_mul_f32 v[114:115], v[114:115], v[162:163] op_sel_hi:[1,0]
	v_pk_mul_f32 v[112:113], v[112:113], v[162:163] op_sel_hi:[1,0]
	v_pk_mul_f32 v[118:119], v[118:119], v[162:163] op_sel_hi:[1,0]
	v_pk_mul_f32 v[116:117], v[116:117], v[162:163] op_sel_hi:[1,0]
	v_max_f32_e32 v124, 0, v124
	v_max_f32_e32 v120, 0, v120
	v_max_f32_e32 v125, 0, v125
	v_max_f32_e32 v121, 0, v121
	v_max_f32_e32 v126, 0, v126
	v_max_f32_e32 v122, 0, v122
	v_max_f32_e32 v127, 0, v127
	v_max_f32_e32 v123, 0, v123
	v_max_f32_e32 v112, 0, v112
	v_max_f32_e32 v113, 0, v113
	v_max_f32_e32 v114, 0, v114
	v_max_f32_e32 v115, 0, v115
	v_max_f32_e32 v116, 0, v116
	v_max_f32_e32 v117, 0, v117
	v_max_f32_e32 v118, 0, v118
	v_max_f32_e32 v119, 0, v119
	v_mul_f32_e32 v124, v124, v124
	v_mul_f32_e32 v120, v120, v120
	v_mul_f32_e32 v125, v125, v125
	v_mul_f32_e32 v121, v121, v121
	v_mul_f32_e32 v126, v126, v126
	v_mul_f32_e32 v122, v122, v122
	v_mul_f32_e32 v127, v127, v127
	v_mul_f32_e32 v123, v123, v123
	v_mul_f32_e32 v147, v112, v112
	v_mul_f32_e32 v159, v113, v113
	v_mul_f32_e32 v162, v114, v114
	v_mul_f32_e32 v163, v115, v115
	v_cvt_pk_bf16_f32 v112, v124, v125
	v_cvt_pk_bf16_f32 v113, v126, v127
	v_cvt_pk_bf16_f32 v114, v120, v121
	v_cvt_pk_bf16_f32 v115, v122, v123
	v_mul_f32_e32 v116, v116, v116
	v_mul_f32_e32 v117, v117, v117
	v_mul_f32_e32 v118, v118, v118
	v_mul_f32_e32 v119, v119, v119
	global_store_dwordx4 v[160:161], v[112:115], off offset:-4096 nt
	s_nop 1
	v_cvt_pk_bf16_f32 v112, v116, v117
	v_cvt_pk_bf16_f32 v113, v118, v119
	v_cvt_pk_bf16_f32 v114, v147, v159
	v_cvt_pk_bf16_f32 v115, v162, v163
	global_store_dwordx4 v[160:161], v[112:115], off nt
	s_nop 0
	s_nop 0
	v_or_b32_e32 v112, 16, v146
	v_ashrrev_i32_e32 v113, 31, v112
	v_lshlrev_b64 v[112:113], 14, v[112:113]
	v_lshl_add_u64 v[112:113], s[36:37], 0, v[112:113]
	v_lshl_add_u64 v[112:113], v[112:113], 0, v[148:149]
	s_nop 0
	v_fmamk_f32 v114, v231, 0x3a000000, v158
	v_mul_f32_e32 v115, 0x4b800000, v114
	v_cmp_gt_f32_e32 vcc, s50, v114
; __device__ __forceinline__ u32x4 pack8(const f32x4 a, const f32x4 b) { u32x4 w; w.x = cvt_pk_bf16(a[0], a[1]); w.y = cvt_pk_bf16(a[2], a[3]); w.z = cvt_pk_bf16(b[0], b[1]); w.w = cvt_pk_bf16(b[2], b[3]); return w; }
;     __device__ __forceinline__ void operator()(AccRef acc, const Unit& u, int wr, int wc, int fr, int fq) const {
; #pragma unroll
;         for (int ai = 0; ai < 2; ++ai)
; #pragma unroll
;             for (int m = 0; m < 4; ++m) { const int row = u.pm * 256 + ai * 128 + wr * 64 + m * 16 + fr;
;                 const float r2 = rsqrtf(ssq[row] * (1.0f / D) + EPS);
; #pragma unroll
;                 for (int bj = 0; bj < 2; ++bj) { const int col = u.pn * 256 + bj * 128 + wc * 32 + 8 * fq;
;                     f32x4 h0 = acc[ai][bj][m][0] * r2, h1 = acc[ai][bj][m][1] * r2;
; #pragma unroll
;                     for (int q = 0; q < 4; ++q) { const float a = fmaxf(h0[q], 0.f), b = fmaxf(h1[q], 0.f); h0[q] = a * a; h1[q] = b * b; }
;                     __builtin_nontemporal_store(pack8(h0, h1), (u32x4*)(HID + (size_t)row * DFF + col)); } }
	s_nop 1
	v_cndmask_b32_e32 v114, v114, v115, vcc
	v_rsq_f32_e32 v114, v114
	s_nop 0
	v_mul_f32_e32 v115, 0x45800000, v114
	v_cndmask_b32_e32 v114, v114, v115, vcc
	v_pk_mul_f32 v[110:111], v[110:111], v[114:115] op_sel_hi:[1,0]
	v_pk_mul_f32 v[108:109], v[108:109], v[114:115] op_sel_hi:[1,0]
	v_pk_mul_f32 v[106:107], v[106:107], v[114:115] op_sel_hi:[1,0]
	v_pk_mul_f32 v[104:105], v[104:105], v[114:115] op_sel_hi:[1,0]
	v_pk_mul_f32 v[98:99], v[98:99], v[114:115] op_sel_hi:[1,0]
	v_pk_mul_f32 v[96:97], v[96:97], v[114:115] op_sel_hi:[1,0]
	v_pk_mul_f32 v[102:103], v[102:103], v[114:115] op_sel_hi:[1,0]
	v_pk_mul_f32 v[100:101], v[100:101], v[114:115] op_sel_hi:[1,0]
	v_max_f32_e32 v108, 0, v108
	v_max_f32_e32 v104, 0, v104
	v_max_f32_e32 v109, 0, v109
	v_max_f32_e32 v105, 0, v105
	v_max_f32_e32 v110, 0, v110
	v_max_f32_e32 v106, 0, v106
	v_max_f32_e32 v111, 0, v111
	v_max_f32_e32 v107, 0, v107
	v_max_f32_e32 v96, 0, v96
	v_max_f32_e32 v97, 0, v97
	v_max_f32_e32 v98, 0, v98
	v_max_f32_e32 v99, 0, v99
	v_max_f32_e32 v100, 0, v100
	v_max_f32_e32 v101, 0, v101
	v_max_f32_e32 v102, 0, v102
	v_max_f32_e32 v103, 0, v103
	v_mul_f32_e32 v108, v108, v108
	v_mul_f32_e32 v104, v104, v104
	v_mul_f32_e32 v109, v109, v109
	v_mul_f32_e32 v105, v105, v105
	v_mul_f32_e32 v110, v110, v110
	v_mul_f32_e32 v106, v106, v106
	v_mul_f32_e32 v111, v111, v111
	v_mul_f32_e32 v107, v107, v107
	v_mul_f32_e32 v114, v96, v96
	v_mul_f32_e32 v115, v97, v97
	v_mul_f32_e32 v116, v98, v98
	v_mul_f32_e32 v117, v99, v99
	v_cvt_pk_bf16_f32 v96, v108, v109
	v_cvt_pk_bf16_f32 v97, v110, v111
	v_cvt_pk_bf16_f32 v98, v104, v105
	v_cvt_pk_bf16_f32 v99, v106, v107
	v_mul_f32_e32 v100, v100, v100
	v_mul_f32_e32 v101, v101, v101
	v_mul_f32_e32 v102, v102, v102
	v_mul_f32_e32 v103, v103, v103
	global_store_dwordx4 v[112:113], v[96:99], off offset:-4096 nt
	s_nop 1
	v_cvt_pk_bf16_f32 v96, v100, v101
	v_cvt_pk_bf16_f32 v97, v102, v103
	v_cvt_pk_bf16_f32 v98, v114, v115
	v_cvt_pk_bf16_f32 v99, v116, v117
	global_store_dwordx4 v[112:113], v[96:99], off nt
	s_nop 0
	s_nop 0
	v_or_b32_e32 v96, 32, v146
	v_ashrrev_i32_e32 v97, 31, v96
	v_lshlrev_b64 v[96:97], 14, v[96:97]
	v_lshl_add_u64 v[96:97], s[36:37], 0, v[96:97]
	v_lshl_add_u64 v[96:97], v[96:97], 0, v[148:149]
	s_nop 0
	v_fmamk_f32 v98, v232, 0x3a000000, v158
	v_mul_f32_e32 v99, 0x4b800000, v98
	v_cmp_gt_f32_e32 vcc, s50, v98
	s_nop 1
	v_cndmask_b32_e32 v98, v98, v99, vcc
	v_rsq_f32_e32 v98, v98
	s_nop 0
	v_mul_f32_e32 v99, 0x45800000, v98
	v_cndmask_b32_e32 v98, v98, v99, vcc
	v_pk_mul_f32 v[94:95], v[94:95], v[98:99] op_sel_hi:[1,0]
	v_pk_mul_f32 v[92:93], v[92:93], v[98:99] op_sel_hi:[1,0]
	v_pk_mul_f32 v[90:91], v[90:91], v[98:99] op_sel_hi:[1,0]
	v_pk_mul_f32 v[88:89], v[88:89], v[98:99] op_sel_hi:[1,0]
	v_pk_mul_f32 v[82:83], v[82:83], v[98:99] op_sel_hi:[1,0]
	v_pk_mul_f32 v[80:81], v[80:81], v[98:99] op_sel_hi:[1,0]
	v_pk_mul_f32 v[86:87], v[86:87], v[98:99] op_sel_hi:[1,0]
	v_pk_mul_f32 v[84:85], v[84:85], v[98:99] op_sel_hi:[1,0]
	v_max_f32_e32 v92, 0, v92
	v_max_f32_e32 v88, 0, v88
	v_max_f32_e32 v93, 0, v93
	v_max_f32_e32 v89, 0, v89
	v_max_f32_e32 v94, 0, v94
	v_max_f32_e32 v90, 0, v90
	v_max_f32_e32 v95, 0, v95
	v_max_f32_e32 v91, 0, v91
	v_max_f32_e32 v80, 0, v80
	v_max_f32_e32 v81, 0, v81
	v_max_f32_e32 v82, 0, v82
	v_max_f32_e32 v83, 0, v83
	v_max_f32_e32 v84, 0, v84
	v_max_f32_e32 v85, 0, v85
	v_max_f32_e32 v86, 0, v86
	v_max_f32_e32 v87, 0, v87
	v_mul_f32_e32 v92, v92, v92
	v_mul_f32_e32 v88, v88, v88
	v_mul_f32_e32 v93, v93, v93
	v_mul_f32_e32 v89, v89, v89
	v_mul_f32_e32 v94, v94, v94
	v_mul_f32_e32 v90, v90, v90
	v_mul_f32_e32 v95, v95, v95
	v_mul_f32_e32 v91, v91, v91
	v_mul_f32_e32 v98, v80, v80
	v_mul_f32_e32 v99, v81, v81
	v_mul_f32_e32 v100, v82, v82
	v_mul_f32_e32 v101, v83, v83
	v_cvt_pk_bf16_f32 v80, v92, v93
	v_cvt_pk_bf16_f32 v81, v94, v95
	v_cvt_pk_bf16_f32 v82, v88, v89
	v_cvt_pk_bf16_f32 v83, v90, v91
	v_mul_f32_e32 v84, v84, v84
	v_mul_f32_e32 v85, v85, v85
	v_mul_f32_e32 v86, v86, v86
	v_mul_f32_e32 v87, v87, v87
	global_store_dwordx4 v[96:97], v[80:83], off offset:-4096 nt
	s_nop 1
	v_cvt_pk_bf16_f32 v80, v84, v85
	v_cvt_pk_bf16_f32 v81, v86, v87
	v_cvt_pk_bf16_f32 v82, v98, v99
	v_cvt_pk_bf16_f32 v83, v100, v101
	global_store_dwordx4 v[96:97], v[80:83], off nt
	s_nop 0
	s_nop 0
	v_or_b32_e32 v80, 48, v146
	v_ashrrev_i32_e32 v81, 31, v80
	v_lshlrev_b64 v[80:81], 14, v[80:81]
	v_lshl_add_u64 v[80:81], s[36:37], 0, v[80:81]
	v_lshl_add_u64 v[80:81], v[80:81], 0, v[148:149]
	s_nop 0
	v_fmamk_f32 v82, v233, 0x3a000000, v158
	v_mul_f32_e32 v83, 0x4b800000, v82
	v_cmp_gt_f32_e32 vcc, s50, v82
	s_nop 1
	v_cndmask_b32_e32 v82, v82, v83, vcc
	v_rsq_f32_e32 v82, v82
	s_nop 0
	v_mul_f32_e32 v83, 0x45800000, v82
	v_cndmask_b32_e32 v82, v82, v83, vcc
	v_pk_mul_f32 v[78:79], v[78:79], v[82:83] op_sel_hi:[1,0]
	v_pk_mul_f32 v[76:77], v[76:77], v[82:83] op_sel_hi:[1,0]
	v_pk_mul_f32 v[74:75], v[74:75], v[82:83] op_sel_hi:[1,0]
	v_pk_mul_f32 v[72:73], v[72:73], v[82:83] op_sel_hi:[1,0]
	v_pk_mul_f32 v[66:67], v[66:67], v[82:83] op_sel_hi:[1,0]
	v_pk_mul_f32 v[64:65], v[64:65], v[82:83] op_sel_hi:[1,0]
	v_pk_mul_f32 v[70:71], v[70:71], v[82:83] op_sel_hi:[1,0]
	v_pk_mul_f32 v[68:69], v[68:69], v[82:83] op_sel_hi:[1,0]
	v_max_f32_e32 v76, 0, v76
	v_max_f32_e32 v72, 0, v72
	v_max_f32_e32 v77, 0, v77
	v_max_f32_e32 v73, 0, v73
	v_max_f32_e32 v78, 0, v78
	v_max_f32_e32 v74, 0, v74
	v_max_f32_e32 v79, 0, v79
	v_max_f32_e32 v75, 0, v75
	v_max_f32_e32 v64, 0, v64
	v_max_f32_e32 v65, 0, v65
	v_max_f32_e32 v66, 0, v66
	v_max_f32_e32 v67, 0, v67
	v_max_f32_e32 v68, 0, v68
	v_max_f32_e32 v69, 0, v69
	v_max_f32_e32 v70, 0, v70
; __device__ __forceinline__ u32x4 pack8(const f32x4 a, const f32x4 b) { u32x4 w; w.x = cvt_pk_bf16(a[0], a[1]); w.y = cvt_pk_bf16(a[2], a[3]); w.z = cvt_pk_bf16(b[0], b[1]); w.w = cvt_pk_bf16(b[2], b[3]); return w; }
;     __device__ __forceinline__ void operator()(AccRef acc, const Unit& u, int wr, int wc, int fr, int fq) const {
; #pragma unroll
;         for (int ai = 0; ai < 2; ++ai)
; #pragma unroll
;             for (int m = 0; m < 4; ++m) { const int row = u.pm * 256 + ai * 128 + wr * 64 + m * 16 + fr;
;                 const float r2 = rsqrtf(ssq[row] * (1.0f / D) + EPS);
; #pragma unroll
;                 for (int bj = 0; bj < 2; ++bj) { const int col = u.pn * 256 + bj * 128 + wc * 32 + 8 * fq;
;                     f32x4 h0 = acc[ai][bj][m][0] * r2, h1 = acc[ai][bj][m][1] * r2;
; #pragma unroll
;                     for (int q = 0; q < 4; ++q) { const float a = fmaxf(h0[q], 0.f), b = fmaxf(h1[q], 0.f); h0[q] = a * a; h1[q] = b * b; }
;                     __builtin_nontemporal_store(pack8(h0, h1), (u32x4*)(HID + (size_t)row * DFF + col)); } }
	v_max_f32_e32 v71, 0, v71
	v_mul_f32_e32 v76, v76, v76
	v_mul_f32_e32 v72, v72, v72
	v_mul_f32_e32 v77, v77, v77
	v_mul_f32_e32 v73, v73, v73
	v_mul_f32_e32 v78, v78, v78
	v_mul_f32_e32 v74, v74, v74
	v_mul_f32_e32 v79, v79, v79
	v_mul_f32_e32 v75, v75, v75
	v_mul_f32_e32 v82, v64, v64
	v_mul_f32_e32 v83, v65, v65
	v_mul_f32_e32 v84, v66, v66
	v_mul_f32_e32 v85, v67, v67
	v_cvt_pk_bf16_f32 v64, v76, v77
	v_cvt_pk_bf16_f32 v65, v78, v79
	v_cvt_pk_bf16_f32 v66, v72, v73
	v_cvt_pk_bf16_f32 v67, v74, v75
	v_mul_f32_e32 v68, v68, v68
	v_mul_f32_e32 v69, v69, v69
	v_mul_f32_e32 v70, v70, v70
	v_mul_f32_e32 v71, v71, v71
	global_store_dwordx4 v[80:81], v[64:67], off offset:-4096 nt
	s_nop 1
	v_cvt_pk_bf16_f32 v64, v68, v69
	v_cvt_pk_bf16_f32 v65, v70, v71
	v_cvt_pk_bf16_f32 v66, v82, v83
	v_cvt_pk_bf16_f32 v67, v84, v85
	global_store_dwordx4 v[80:81], v[64:67], off nt
	s_nop 0
	s_nop 0
	v_add_u32_e32 v64, 0x80, v146
	v_ashrrev_i32_e32 v65, 31, v64
	v_lshlrev_b64 v[64:65], 14, v[64:65]
	v_lshl_add_u64 v[64:65], s[36:37], 0, v[64:65]
	v_lshl_add_u64 v[64:65], v[64:65], 0, v[148:149]
	s_nop 0
	v_fmamk_f32 v66, v234, 0x3a000000, v158
	v_mul_f32_e32 v67, 0x4b800000, v66
	v_cmp_gt_f32_e32 vcc, s50, v66
	s_nop 1
	v_cndmask_b32_e32 v66, v66, v67, vcc
	v_rsq_f32_e32 v66, v66
	s_nop 0
	v_mul_f32_e32 v67, 0x45800000, v66
	v_cndmask_b32_e32 v66, v66, v67, vcc
	v_pk_mul_f32 v[62:63], v[62:63], v[66:67] op_sel_hi:[1,0]
	v_pk_mul_f32 v[60:61], v[60:61], v[66:67] op_sel_hi:[1,0]
	v_pk_mul_f32 v[58:59], v[58:59], v[66:67] op_sel_hi:[1,0]
	v_pk_mul_f32 v[56:57], v[56:57], v[66:67] op_sel_hi:[1,0]
	v_pk_mul_f32 v[50:51], v[50:51], v[66:67] op_sel_hi:[1,0]
	v_pk_mul_f32 v[48:49], v[48:49], v[66:67] op_sel_hi:[1,0]
	v_pk_mul_f32 v[54:55], v[54:55], v[66:67] op_sel_hi:[1,0]
	v_pk_mul_f32 v[52:53], v[52:53], v[66:67] op_sel_hi:[1,0]
	v_max_f32_e32 v60, 0, v60
	v_max_f32_e32 v56, 0, v56
	v_max_f32_e32 v61, 0, v61
	v_max_f32_e32 v57, 0, v57
	v_max_f32_e32 v62, 0, v62
	v_max_f32_e32 v58, 0, v58
	v_max_f32_e32 v63, 0, v63
	v_max_f32_e32 v59, 0, v59
	v_max_f32_e32 v48, 0, v48
	v_max_f32_e32 v49, 0, v49
	v_max_f32_e32 v50, 0, v50
	v_max_f32_e32 v51, 0, v51
	v_max_f32_e32 v52, 0, v52
	v_max_f32_e32 v53, 0, v53
	v_max_f32_e32 v54, 0, v54
	v_max_f32_e32 v55, 0, v55
	v_mul_f32_e32 v60, v60, v60
	v_mul_f32_e32 v56, v56, v56
	v_mul_f32_e32 v61, v61, v61
	v_mul_f32_e32 v57, v57, v57
	v_mul_f32_e32 v62, v62, v62
	v_mul_f32_e32 v58, v58, v58
	v_mul_f32_e32 v63, v63, v63
	v_mul_f32_e32 v59, v59, v59
	v_mul_f32_e32 v66, v48, v48
	v_mul_f32_e32 v67, v49, v49
	v_mul_f32_e32 v68, v50, v50
	v_mul_f32_e32 v69, v51, v51
	v_cvt_pk_bf16_f32 v48, v60, v61
	v_cvt_pk_bf16_f32 v49, v62, v63
	v_cvt_pk_bf16_f32 v50, v56, v57
	v_cvt_pk_bf16_f32 v51, v58, v59
	v_mul_f32_e32 v52, v52, v52
	v_mul_f32_e32 v53, v53, v53
	v_mul_f32_e32 v54, v54, v54
	v_mul_f32_e32 v55, v55, v55
	global_store_dwordx4 v[64:65], v[48:51], off offset:-4096 nt
	s_nop 1
	v_cvt_pk_bf16_f32 v48, v52, v53
	v_cvt_pk_bf16_f32 v49, v54, v55
	v_cvt_pk_bf16_f32 v50, v66, v67
	v_cvt_pk_bf16_f32 v51, v68, v69
	global_store_dwordx4 v[64:65], v[48:51], off nt
	s_nop 0
	s_nop 0
	v_add_u32_e32 v48, 0x90, v146
	v_ashrrev_i32_e32 v49, 31, v48
	v_lshlrev_b64 v[48:49], 14, v[48:49]
	v_lshl_add_u64 v[48:49], s[36:37], 0, v[48:49]
	v_lshl_add_u64 v[48:49], v[48:49], 0, v[148:149]
	s_nop 0
	v_fmamk_f32 v50, v235, 0x3a000000, v158
	v_mul_f32_e32 v51, 0x4b800000, v50
	v_cmp_gt_f32_e32 vcc, s50, v50
	s_nop 1
	v_cndmask_b32_e32 v50, v50, v51, vcc
	v_rsq_f32_e32 v50, v50
	s_nop 0
	v_mul_f32_e32 v51, 0x45800000, v50
	v_cndmask_b32_e32 v50, v50, v51, vcc
	v_pk_mul_f32 v[46:47], v[46:47], v[50:51] op_sel_hi:[1,0]
	v_pk_mul_f32 v[44:45], v[44:45], v[50:51] op_sel_hi:[1,0]
	v_pk_mul_f32 v[42:43], v[42:43], v[50:51] op_sel_hi:[1,0]
	v_pk_mul_f32 v[40:41], v[40:41], v[50:51] op_sel_hi:[1,0]
	v_pk_mul_f32 v[34:35], v[34:35], v[50:51] op_sel_hi:[1,0]
	v_pk_mul_f32 v[32:33], v[32:33], v[50:51] op_sel_hi:[1,0]
	v_pk_mul_f32 v[38:39], v[38:39], v[50:51] op_sel_hi:[1,0]
	v_pk_mul_f32 v[36:37], v[36:37], v[50:51] op_sel_hi:[1,0]
	v_max_f32_e32 v44, 0, v44
	v_max_f32_e32 v40, 0, v40
	v_max_f32_e32 v45, 0, v45
	v_max_f32_e32 v41, 0, v41
	v_max_f32_e32 v46, 0, v46
	v_max_f32_e32 v42, 0, v42
	v_max_f32_e32 v47, 0, v47
	v_max_f32_e32 v43, 0, v43
	v_max_f32_e32 v32, 0, v32
	v_max_f32_e32 v33, 0, v33
	v_max_f32_e32 v34, 0, v34
	v_max_f32_e32 v35, 0, v35
	v_max_f32_e32 v36, 0, v36
	v_max_f32_e32 v37, 0, v37
	v_max_f32_e32 v38, 0, v38
	v_max_f32_e32 v39, 0, v39
	v_mul_f32_e32 v44, v44, v44
	v_mul_f32_e32 v40, v40, v40
	v_mul_f32_e32 v45, v45, v45
	v_mul_f32_e32 v41, v41, v41
	v_mul_f32_e32 v46, v46, v46
	v_mul_f32_e32 v42, v42, v42
	v_mul_f32_e32 v47, v47, v47
	v_mul_f32_e32 v43, v43, v43
	v_mul_f32_e32 v50, v32, v32
	v_mul_f32_e32 v51, v33, v33
	v_mul_f32_e32 v52, v34, v34
	v_mul_f32_e32 v53, v35, v35
	v_cvt_pk_bf16_f32 v32, v44, v45
	v_cvt_pk_bf16_f32 v33, v46, v47
	v_cvt_pk_bf16_f32 v34, v40, v41
; __device__ __forceinline__ u32x4 pack8(const f32x4 a, const f32x4 b) { u32x4 w; w.x = cvt_pk_bf16(a[0], a[1]); w.y = cvt_pk_bf16(a[2], a[3]); w.z = cvt_pk_bf16(b[0], b[1]); w.w = cvt_pk_bf16(b[2], b[3]); return w; }
; #define PG8_BAR __builtin_amdgcn_s_barrier()
; template <class Epi, class Sched>
; __device__ __forceinline__ void gemm_phase(LAS unsigned char* lds, const Gemm g, const Sched& S, const Epi& E) {
;     ...
;         if (!has_next) break;
; #pragma unroll
;         for (int a = 0; a < 2; ++a)
; #pragma unroll
;             for (int b = 0; b < 2; ++b)
; #pragma unroll
;                 for (int m = 0; m < 4; ++m)
; #pragma unroll
;                     for (int n = 0; n < 2; ++n) acc[a][b][m][n] = (f32x4){0.f, 0.f, 0.f, 0.f};
;         cur = nxt; cA = nA; cB = nB; ++ui;
;         if (wr == 1) PG8_BAR;
;     }
;     __device__ __forceinline__ void operator()(AccRef acc, const Unit& u, int wr, int wc, int fr, int fq) const {
; #pragma unroll
;         for (int ai = 0; ai < 2; ++ai)
; #pragma unroll
;             for (int m = 0; m < 4; ++m) { const int row = u.pm * 256 + ai * 128 + wr * 64 + m * 16 + fr;
;                 const float r2 = rsqrtf(ssq[row] * (1.0f / D) + EPS);
; #pragma unroll
;                 for (int bj = 0; bj < 2; ++bj) { const int col = u.pn * 256 + bj * 128 + wc * 32 + 8 * fq;
;                     f32x4 h0 = acc[ai][bj][m][0] * r2, h1 = acc[ai][bj][m][1] * r2;
; #pragma unroll
;                     for (int q = 0; q < 4; ++q) { const float a = fmaxf(h0[q], 0.f), b = fmaxf(h1[q], 0.f); h0[q] = a * a; h1[q] = b * b; }
;                     __builtin_nontemporal_store(pack8(h0, h1), (u32x4*)(HID + (size_t)row * DFF + col)); } }
	v_cvt_pk_bf16_f32 v35, v42, v43
	v_mul_f32_e32 v36, v36, v36
	v_mul_f32_e32 v37, v37, v37
	v_mul_f32_e32 v38, v38, v38
	v_mul_f32_e32 v39, v39, v39
	global_store_dwordx4 v[48:49], v[32:35], off offset:-4096 nt
	s_nop 1
	v_cvt_pk_bf16_f32 v32, v36, v37
	v_cvt_pk_bf16_f32 v33, v38, v39
	v_cvt_pk_bf16_f32 v34, v50, v51
	v_cvt_pk_bf16_f32 v35, v52, v53
	global_store_dwordx4 v[48:49], v[32:35], off nt
	s_nop 0
	s_nop 0
	v_add_u32_e32 v32, 0xa0, v146
	v_ashrrev_i32_e32 v33, 31, v32
	v_lshlrev_b64 v[32:33], 14, v[32:33]
	v_lshl_add_u64 v[32:33], s[36:37], 0, v[32:33]
	v_lshl_add_u64 v[32:33], v[32:33], 0, v[148:149]
	s_nop 0
	v_fmamk_f32 v34, v236, 0x3a000000, v158
	v_mul_f32_e32 v35, 0x4b800000, v34
	v_cmp_gt_f32_e32 vcc, s50, v34
	s_nop 1
	v_cndmask_b32_e32 v34, v34, v35, vcc
	v_rsq_f32_e32 v34, v34
	s_nop 0
	v_mul_f32_e32 v35, 0x45800000, v34
	v_cndmask_b32_e32 v34, v34, v35, vcc
	v_pk_mul_f32 v[30:31], v[30:31], v[34:35] op_sel_hi:[1,0]
	v_pk_mul_f32 v[28:29], v[28:29], v[34:35] op_sel_hi:[1,0]
	v_pk_mul_f32 v[26:27], v[26:27], v[34:35] op_sel_hi:[1,0]
	v_pk_mul_f32 v[24:25], v[24:25], v[34:35] op_sel_hi:[1,0]
	v_pk_mul_f32 v[18:19], v[18:19], v[34:35] op_sel_hi:[1,0]
	v_pk_mul_f32 v[16:17], v[16:17], v[34:35] op_sel_hi:[1,0]
	v_pk_mul_f32 v[22:23], v[22:23], v[34:35] op_sel_hi:[1,0]
	v_pk_mul_f32 v[20:21], v[20:21], v[34:35] op_sel_hi:[1,0]
	v_max_f32_e32 v28, 0, v28
	v_max_f32_e32 v24, 0, v24
	v_max_f32_e32 v29, 0, v29
	v_max_f32_e32 v25, 0, v25
	v_max_f32_e32 v30, 0, v30
	v_max_f32_e32 v26, 0, v26
	v_max_f32_e32 v31, 0, v31
	v_max_f32_e32 v27, 0, v27
	v_max_f32_e32 v16, 0, v16
	v_max_f32_e32 v17, 0, v17
	v_max_f32_e32 v18, 0, v18
	v_max_f32_e32 v19, 0, v19
	v_max_f32_e32 v20, 0, v20
	v_max_f32_e32 v21, 0, v21
	v_max_f32_e32 v22, 0, v22
	v_max_f32_e32 v23, 0, v23
	v_mul_f32_e32 v28, v28, v28
	v_mul_f32_e32 v24, v24, v24
	v_mul_f32_e32 v29, v29, v29
	v_mul_f32_e32 v25, v25, v25
	v_mul_f32_e32 v30, v30, v30
	v_mul_f32_e32 v26, v26, v26
	v_mul_f32_e32 v31, v31, v31
	v_mul_f32_e32 v27, v27, v27
	v_mul_f32_e32 v34, v16, v16
	v_mul_f32_e32 v35, v17, v17
	v_mul_f32_e32 v36, v18, v18
	v_mul_f32_e32 v37, v19, v19
	v_cvt_pk_bf16_f32 v16, v28, v29
	v_cvt_pk_bf16_f32 v17, v30, v31
	v_cvt_pk_bf16_f32 v18, v24, v25
	v_cvt_pk_bf16_f32 v19, v26, v27
	v_mul_f32_e32 v20, v20, v20
	v_mul_f32_e32 v21, v21, v21
	v_mul_f32_e32 v22, v22, v22
	v_mul_f32_e32 v23, v23, v23
	global_store_dwordx4 v[32:33], v[16:19], off offset:-4096 nt
	s_andn2_b64 vcc, exec, s[0:1]
	s_nop 0
	v_cvt_pk_bf16_f32 v16, v20, v21
	v_cvt_pk_bf16_f32 v17, v22, v23
	v_cvt_pk_bf16_f32 v18, v34, v35
	v_cvt_pk_bf16_f32 v19, v36, v37
	global_store_dwordx4 v[32:33], v[16:19], off nt
	s_nop 0
	s_nop 0
	v_add_u32_e32 v16, 0xb0, v146
	v_ashrrev_i32_e32 v17, 31, v16
	v_lshlrev_b64 v[16:17], 14, v[16:17]
	v_lshl_add_u64 v[16:17], s[36:37], 0, v[16:17]
	v_lshl_add_u64 v[16:17], v[16:17], 0, v[148:149]
	s_nop 0
	v_fmamk_f32 v18, v237, 0x3a000000, v158
	v_mul_f32_e32 v19, 0x4b800000, v18
	v_cmp_gt_f32_e64 s[0:1], s50, v18
	s_nop 1
	v_cndmask_b32_e64 v18, v18, v19, s[0:1]
	v_rsq_f32_e32 v18, v18
	s_nop 0
	v_mul_f32_e32 v19, 0x45800000, v18
	v_cndmask_b32_e64 v18, v18, v19, s[0:1]
	v_pk_mul_f32 v[14:15], v[14:15], v[18:19] op_sel_hi:[1,0]
	v_pk_mul_f32 v[12:13], v[12:13], v[18:19] op_sel_hi:[1,0]
	v_pk_mul_f32 v[10:11], v[10:11], v[18:19] op_sel_hi:[1,0]
	v_pk_mul_f32 v[8:9], v[8:9], v[18:19] op_sel_hi:[1,0]
	v_pk_mul_f32 v[2:3], v[2:3], v[18:19] op_sel_hi:[1,0]
	v_pk_mul_f32 v[0:1], v[0:1], v[18:19] op_sel_hi:[1,0]
	v_pk_mul_f32 v[6:7], v[6:7], v[18:19] op_sel_hi:[1,0]
	v_pk_mul_f32 v[4:5], v[4:5], v[18:19] op_sel_hi:[1,0]
	v_max_f32_e32 v12, 0, v12
	v_max_f32_e32 v8, 0, v8
	v_max_f32_e32 v13, 0, v13
	v_max_f32_e32 v9, 0, v9
	v_max_f32_e32 v14, 0, v14
	v_max_f32_e32 v10, 0, v10
	v_max_f32_e32 v15, 0, v15
	v_max_f32_e32 v11, 0, v11
	v_max_f32_e32 v0, 0, v0
	v_max_f32_e32 v1, 0, v1
	v_max_f32_e32 v2, 0, v2
	v_max_f32_e32 v3, 0, v3
	v_max_f32_e32 v4, 0, v4
	v_max_f32_e32 v5, 0, v5
	v_max_f32_e32 v6, 0, v6
	v_max_f32_e32 v7, 0, v7
	v_mul_f32_e32 v12, v12, v12
	v_mul_f32_e32 v8, v8, v8
	v_mul_f32_e32 v13, v13, v13
	v_mul_f32_e32 v9, v9, v9
	v_mul_f32_e32 v14, v14, v14
	v_mul_f32_e32 v10, v10, v10
	v_mul_f32_e32 v15, v15, v15
	v_mul_f32_e32 v11, v11, v11
	v_mul_f32_e32 v18, v0, v0
	v_mul_f32_e32 v19, v1, v1
	v_mul_f32_e32 v20, v2, v2
	v_mul_f32_e32 v21, v3, v3
	v_cvt_pk_bf16_f32 v0, v12, v13
	v_cvt_pk_bf16_f32 v1, v14, v15
	v_cvt_pk_bf16_f32 v2, v8, v9
	v_cvt_pk_bf16_f32 v3, v10, v11
	s_mov_b64 s[0:1], -1
	v_mul_f32_e32 v4, v4, v4
	v_mul_f32_e32 v5, v5, v5
	v_mul_f32_e32 v6, v6, v6
	v_mul_f32_e32 v7, v7, v7
	global_store_dwordx4 v[16:17], v[0:3], off offset:-4096 nt
	s_nop 1
	v_cvt_pk_bf16_f32 v0, v4, v5
	v_cvt_pk_bf16_f32 v1, v6, v7
	v_cvt_pk_bf16_f32 v2, v18, v19
	v_cvt_pk_bf16_f32 v3, v20, v21
	global_store_dwordx4 v[16:17], v[0:3], off nt
	s_cbranch_vccnz .LBB0_829
	s_andn2_b64 vcc, exec, s[8:9]
	s_cbranch_vccnz .LBB0_828
	s_branch .LBB0_828

;     __device__ bool next(int i, Unit& u) const { return at((long)i * G + c, u); }
;     __device__ bool next(int i, Unit& u) const { if (i > 0) return false; u.pm = pm; u.pn = pn; u.g = 0; u.nt = nt; u.k0 = 0; u.part = -1; return true; }
; #define PG8_STAGE(bufoff, gbase, voff) do { _Pragma("unroll") for (int _i = 0; _i < 2; ++_i) \
;         __builtin_amdgcn_global_load_lds((const unsigned*)((const char*)(gbase) + (voff)[_i]), (LAS unsigned*)(lds + (bufoff) + ldsw + _i * 8192), 16, 0, 0); } while (0)
; #define PG8_WAIT_V(n) asm volatile("s_waitcnt vmcnt(" #n ")" ::: "memory")
; template <class Epi, class Sched>
; __device__ __forceinline__ void gemm_phase(LAS unsigned char* lds, const Gemm g, const Sched& S, const Epi& E) {
;     const int tid = threadIdx.x, wid = __builtin_amdgcn_readfirstlane(tid >> 6), lane = tid & 63, wr = wid >> 2, wc = wid & 3, fr = lane & 15, fq = lane >> 4;
;     unsigned voffA[2], voffB[2];
; #pragma unroll
;     for (int i = 0; i < 2; ++i) { int R, C; stage_rc(tid * 16 + i * 8192, R, C); const int Rb = Epi::PERM ? ((R & ~31) + perm32(R & 31)) : R;
;         voffA[i] = (unsigned)(R * g.lda + C) * 2u; voffB[i] = (unsigned)(Rb * g.ldb + C) * 2u; }
;     const size_t kstep = (size_t)(BK * 2);
;     const size_t hstepA = (size_t)HALF * g.lda * 2, hstepB = (size_t)HALF * g.ldb * 2;
;     const unsigned ldsw = (unsigned)wid * 1024u;
;     const int aoff = lds_byte(wr * 64 + fr, fq * 8), boff = lds_byte(wc * 32 + fr, fq * 8);
;     ...
;     Unit cur, nxt; int ui = 0;
;     if (!S.next(0, cur)) return;
;     f32x4 acc[2][2][4][2];
; #pragma unroll
;     for (int a = 0; a < 2; ++a)
; #pragma unroll
;         for (int b = 0; b < 2; ++b)
; #pragma unroll
;             for (int m = 0; m < 4; ++m)
; #pragma unroll
;                 for (int n = 0; n < 2; ++n) acc[a][b][m][n] = (f32x4){0.f, 0.f, 0.f, 0.f};
;     bf16x8 At[4][2], B0[2][2], B1[2][2];
;     const char* cA = PG8_ABASE(cur); const char* cB = PG8_BBASE(cur);
;     PG8_STAGE(PG8_SB(0, 0), cB, voffB); PG8_STAGE(PG8_SB(0, 1), cB + hstepB, voffB); PG8_STAGE(PG8_SA(0, 0), cA, voffA); PG8_STAGE(PG8_SA(0, 1), cA + hstepA, voffA);
;     if (wr == 1) PG8_BAR;
;     PG8_WAIT_V(2); PG8_BAR;
;     PG8_STAGE(PG8_SB(1, 0), cB + kstep, voffB); PG8_STAGE(PG8_SA(1, 0), cA + kstep, voffA); PG8_STAGE(PG8_SB(1, 1), cB + hstepB + kstep, voffB);
;     PG8_WAIT_V(6); PG8_BAR;
.LBB0_905:
	s_andn2_b64 vcc, exec, s[6:7]
	s_cbranch_vccnz .LBB0_953
	v_lshrrev_b32_e32 v2, 1, v136
	v_lshrrev_b32_e32 v3, 5, v136
	v_and_b32_e32 v2, 24, v2
	v_and_b32_e32 v3, 4, v3
	v_bfe_u32 v4, v136, 2, 2
	v_lshlrev_b32_e32 v0, 4, v136
	s_waitcnt lgkmcnt(0)
	v_and_b32_e32 v1, 32, v136
	v_bfe_u32 v10, v136, 2, 4
	v_or3_b32 v2, v3, v4, v2
	v_lshrrev_b32_e32 v3, 3, v136
	s_movk_i32 s6, 0x70
	v_bitop3_b32 v8, v0, v1, 48 bitop3:0x6c
	v_and_b32_e32 v9, 64, v136
	v_and_or_b32 v4, v3, s6, v10
	s_movk_i32 s6, 0x60
	v_add_u32_e32 v11, 0x2000, v0
	v_or_b32_e32 v1, v8, v9
	v_and_or_b32 v3, v3, s6, v2
	v_lshrrev_b32_e32 v0, 7, v11
	s_movk_i32 s6, 0xf0
	v_lshl_or_b32 v156, v3, 14, v1
	v_and_or_b32 v3, v0, s6, v10
	s_movk_i32 s6, 0xe0
	v_and_or_b32 v0, v0, s6, v2
	s_lshr_b32 s6, s2, 6
	s_ashr_i32 s19, s18, 31
	s_lshr_b32 s5, s2, 8
	s_lshl_b32 s39, s6, 10
	s_lshl_b64 s[8:9], s[18:19], 22
	v_readlane_b32 s20, v242, 6
	v_readlane_b32 s21, v242, 7
	s_add_u32 s7, s20, s8
	s_addc_u32 s13, s21, s9
	s_ashr_i32 s17, s16, 31
	s_lshl_b64 s[8:9], s[16:17], 22
	s_add_u32 s8, s90, s8
	s_addc_u32 s9, s91, s9
	s_add_u32 s66, s8, s0
	s_addc_u32 s67, s9, s1
	s_add_i32 s17, s39, 0
	s_add_i32 m0, s17, 0x10000
	v_lshl_or_b32 v160, v0, 14, v1
	global_load_lds_dwordx4 v156, s[66:67]
	s_add_i32 m0, s17, 0x12000
	s_add_u32 s8, s66, 0x200000
	global_load_lds_dwordx4 v160, s[66:67]
	s_addc_u32 s9, s67, 0
	s_add_i32 m0, s17, 0x14000
	v_lshl_or_b32 v154, v4, 14, v1
	v_and_b32_e32 v240, 0x1c0000, v154
	v_and_b32_e32 v241, 64, v154
	v_lshl_or_b32 v240, v241, 4, v240
	v_and_b32_e32 v241, 63, v136
	v_lshl_or_b32 v154, v241, 4, v240
	global_load_lds_dwordx4 v156, s[8:9]
	s_add_i32 m0, s17, 0x16000
	v_lshl_or_b32 v158, v3, 14, v1
	v_and_b32_e32 v240, 0x1c0000, v158
	v_and_b32_e32 v241, 64, v158
	v_lshl_or_b32 v240, v241, 4, v240
	v_and_b32_e32 v241, 63, v136
	v_lshl_or_b32 v158, v241, 4, v240
	global_load_lds_dwordx4 v160, s[8:9]
	s_lshl_b64 s[100:101], s[0:1], 4
	s_add_u32 s8, s7, s100
	s_addc_u32 s9, s13, s101
	s_add_i32 s72, s17, 0x2000
	s_mov_b32 m0, s17
	s_add_u32 s0, s8, 0x200000
	global_load_lds_dwordx4 v154, s[8:9]
	s_mov_b32 m0, s72
	s_addc_u32 s1, s9, 0
	s_add_i32 s73, s17, 0x4000
	global_load_lds_dwordx4 v158, s[8:9]
	s_mov_b32 m0, s73
	s_add_i32 s76, s17, 0x6000
	global_load_lds_dwordx4 v154, s[0:1]
	s_mov_b32 m0, s76
	v_mov_b32_e32 v163, 0
	global_load_lds_dwordx4 v158, s[0:1]
	v_mov_b32_e32 v157, v163
	v_mov_b32_e32 v161, v163
	v_mov_b32_e32 v155, v163
	v_mov_b32_e32 v159, v163
	s_cmp_eq_u32 s5, 1
	s_mov_b32 s75, s87
	s_mov_b32 s13, 0
	v_lshl_add_u64 v[6:7], s[66:67], 0, v[156:157]
	v_lshl_add_u64 v[4:5], s[66:67], 0, v[160:161]
	v_lshl_add_u64 v[0:1], s[8:9], 0, v[154:155]
	s_cselect_b64 s[20:21], -1, 0
	s_cmp_lg_u32 s5, 1
	v_lshl_add_u64 v[2:3], s[8:9], 0, v[158:159]
	s_cbranch_scc1 .LBB0_908
.LBB0_908:
	s_lshl_b32 s0, s6, 5
	s_and_b32 s19, s0, 0x60
	s_lshl_b32 s7, s5, 13
	s_lshl_b32 s6, s19, 7
	s_add_u32 s22, s30, 0xc8000
	s_addc_u32 s23, s31, 0
	s_add_u32 s77, s30, 0xea000
	s_mov_b64 s[24:25], 0x80
	s_mov_b64 s[98:99], 0x800
	s_addc_u32 s78, s31, 0
	s_add_i32 m0, s17, 0x18000
	v_lshl_add_u64 v[6:7], v[6:7], 0, s[24:25]
	s_waitcnt vmcnt(2)
	s_barrier
	global_load_lds_dwordx4 v[6:7], off
	v_lshl_add_u64 v[4:5], v[4:5], 0, s[24:25]
	s_add_i32 m0, s17, 0x1a000
	s_add_i32 s79, s17, 0x8000
	s_add_i32 s80, s17, 0xa000
	global_load_lds_dwordx4 v[4:5], off
	v_lshl_add_u64 v[0:1], v[0:1], 0, s[98:99]
	s_mov_b32 m0, s79
	s_add_u32 s0, s66, 0x200080
	global_load_lds_dwordx4 v[0:1], off
	v_lshl_add_u64 v[0:1], v[2:3], 0, s[98:99]
	s_mov_b32 m0, s80
	s_addc_u32 s1, s67, 0
	global_load_lds_dwordx4 v[0:1], off
	s_add_i32 m0, s17, 0x1c000
	v_lshl_add_u64 v[0:1], s[0:1], 0, v[156:157]
	global_load_lds_dwordx4 v[0:1], off
	v_lshl_add_u64 v[0:1], s[0:1], 0, v[160:161]
	s_add_i32 m0, s17, 0x1e000
	v_bfe_u32 v2, v136, 4, 2
	global_load_lds_dwordx4 v[0:1], off
	v_and_b32_e32 v1, 15, v136
	v_lshlrev_b32_e32 v3, 4, v2
	v_lshlrev_b32_e32 v5, 2, v136
	v_lshlrev_b32_e32 v6, 6, v136
	s_movk_i32 s0, 0x3c0
	v_lshl_or_b32 v164, s5, 6, v1
	v_lshl_or_b32 v4, v1, 6, v3
	v_and_b32_e32 v5, 32, v5
	v_and_or_b32 v3, v6, s0, v3
	v_or_b32_e32 v1, v2, v1
	v_bitop3_b32 v4, v4, s7, v5 bitop3:0xde
	v_bitop3_b32 v153, s6, v3, v5 bitop3:0xf6
	v_cmp_eq_u32_e64 s[6:7], 0, v1
	v_lshlrev_b32_e32 v1, 11, v136
	v_lshlrev_b32_e32 v0, 3, v2
	v_cmp_eq_u32_e64 s[0:1], 0, v2
	v_and_b32_e32 v1, 0x1c0000, v1
	v_lshlrev_b32_e32 v2, 14, v10
	v_or3_b32 v1, v8, v1, v2
	v_add_u32_e32 v168, v1, v9
	v_and_b32_e32 v240, 0x1c0000, v168
	v_and_b32_e32 v241, 64, v168
	v_lshl_or_b32 v240, v241, 4, v240
	v_and_b32_e32 v241, 63, v136
	v_lshl_or_b32 v168, v241, 4, v240
	v_lshlrev_b32_e32 v1, 7, v11
	s_waitcnt vmcnt(6)
	s_cmpk_lt_u32 s2, 0x100
	v_mov_b32_e32 v165, v163
	v_and_b32_e32 v1, 0x3c0000, v1
	s_cselect_b64 s[36:37], -1, 0
	v_lshlrev_b64 v[166:167], 13, v[164:165]
	v_or_b32_e32 v165, s19, v0
	v_or3_b32 v1, v8, v1, v2
	s_add_i32 s81, 0, 0x10000
	s_add_i32 s82, 0, 0x14000
	v_lshlrev_b32_e32 v162, 2, v0
	s_mov_b32 s42, 0xf0060000
	s_mov_b32 s44, 0xf0100000
	s_mov_b32 s48, 0xf0120000
	s_mov_b32 s50, 0xf0140000
	s_mov_b32 s52, 0xf0160000
	v_mbcnt_lo_u32_b32 v0, -1, 0
	v_mov_b32_e32 v169, v163
	v_add_u32_e32 v170, v1, v9
	v_and_b32_e32 v240, 0x1c0000, v170
	v_and_b32_e32 v241, 64, v170
	v_lshl_or_b32 v240, v241, 4, v240
	v_and_b32_e32 v241, 63, v136
	v_lshl_or_b32 v170, v241, 4, v240
	v_mov_b32_e32 v171, v163
	v_add_u32_e32 v208, s81, v153
	v_add_u32_e32 v209, s82, v153
	v_and_b32_e32 v210, 0xffffe000, v4
	v_and_b32_e32 v240, 63, v136
	v_lshl_or_b32 v210, v240, 4, v210
	s_mov_b32 s38, 0x3a000000
	s_mov_b32 s83, 0x800000
	s_lshl_b32 s40, s19, 2
	s_mov_b32 s84, 0xf0040000
	s_mov_b32 s43, -1
	s_mov_b32 s85, 0xf0060000
	s_mov_b32 s45, -1
	s_mov_b32 s86, 0xf0100000
	s_mov_b32 s49, -1
	s_mov_b32 s33, 0xf0120000
	s_mov_b32 s51, -1
	s_mov_b32 s53, -1
	v_mbcnt_hi_u32_b32 v211, -1, v0
	s_mov_b32 s87, s13
	s_barrier
	s_branch .LBB0_911

;     __device__ bool next(int i, Unit& u) const { return at((long)i * G + c, u); }
;     __device__ bool next(int i, Unit& u) const { if (i > 0) return false; u.pm = pm; u.pn = pn; u.g = 0; u.nt = nt; u.k0 = 0; u.part = -1; return true; }
; #define PG8_STAGE(bufoff, gbase, voff) do { _Pragma("unroll") for (int _i = 0; _i < 2; ++_i) \
;         __builtin_amdgcn_global_load_lds((const unsigned*)((const char*)(gbase) + (voff)[_i]), (LAS unsigned*)(lds + (bufoff) + ldsw + _i * 8192), 16, 0, 0); } while (0)
; #define PG8_LDA(dst, b, h) do { _Pragma("unroll") for (int m = 0; m < 4; ++m) _Pragma("unroll") for (int k = 0; k < 2; ++k) dst[m][k] = *(const LAS bf16x8*)(lds + PG8_SA(b, h) + aoff + m * 2048 + k * 1024); } while (0)
; #define PG8_LDB(dst, b, h) do { _Pragma("unroll") for (int n = 0; n < 2; ++n) _Pragma("unroll") for (int k = 0; k < 2; ++k) dst[n][k] = *(const LAS bf16x8*)(lds + PG8_SB(b, h) + boff + n * 2048 + k * 1024); } while (0)
; #define PG8_WAIT_V(n) asm volatile("s_waitcnt vmcnt(" #n ")" ::: "memory")
; template <class Epi, class Sched>
; __device__ __forceinline__ void gemm_phase(LAS unsigned char* lds, const Gemm g, const Sched& S, const Epi& E) {
;     ...
;     for (;;) {
;         const bool has_next = S.next(ui + 1, nxt);
;         const char* nA = has_next ? PG8_ABASE(nxt) : cA; const char* nB = has_next ? PG8_BBASE(nxt) : cB;
;         const int nt = cur.nt;
;         for (int t = 0; t < nt; t += 2) {
;             const bool last = (t == nt - 2);
;             const char* a1 = cA + (size_t)(t + 1) * kstep;
;             const char* a2 = last ? nA : cA + (size_t)(t + 2) * kstep; const char* b2 = last ? nB : cB + (size_t)(t + 2) * kstep;
;             const char* a3 = a2 + kstep; const char* b3 = b2 + kstep;
;             PG8_LDB(B0, 0, 0); PG8_LDB(B1, 0, 1); PG8_SCHED; PG8_LDA(At, 0, 0); PG8_STAGE(PG8_SA(1, 1), a1 + hstepA, voffA);
;             PG8_WAIT_V(8); PG8_WAIT_L(0); PG8_BAR; PG8_MMA(0, 0, At, B0); PG8_MMA(0, 1, At, B1); PG8_BAR; PG8_SCHED;
;     ...
; #pragma unroll
;         for (int a = 0; a < 2; ++a)
; #pragma unroll
;             for (int b = 0; b < 2; ++b)
; #pragma unroll
;                 for (int m = 0; m < 4; ++m)
; #pragma unroll
;                     for (int n = 0; n < 2; ++n) acc[a][b][m][n] = (f32x4){0.f, 0.f, 0.f, 0.f};
;         cur = nxt; cA = nA; cB = nB; ++ui;
;         if (wr == 1) PG8_BAR;
.LBB0_916:
	s_ashr_i32 s55, s54, 31
	s_ashr_i32 s57, s56, 31
	s_lshl_b64 s[34:35], s[56:57], 7
	s_lshl_b64 s[46:47], s[54:55], 22
	v_readlane_b32 s62, v242, 6
	v_readlane_b32 s63, v242, 7
	s_add_u32 s2, s62, s46
	s_addc_u32 s5, s63, s47
	s_lshl_b64 s[100:101], s[56:57], 11
	s_add_u32 s62, s2, s100
	s_addc_u32 s63, s5, s101
	s_and_b64 s[46:47], s[60:61], exec
	s_cselect_b32 s2, s63, s9
	s_cselect_b32 s5, s62, s8
	s_ashr_i32 s59, s58, 31
	s_lshl_b64 s[46:47], s[58:59], 22
	s_add_u32 s19, s90, s46
	s_addc_u32 s41, s91, s47
	s_add_u32 s64, s19, s34
	s_addc_u32 s65, s41, s35
	s_and_b64 s[34:35], s[60:61], exec
	s_cselect_b32 s19, s65, s67
	s_cselect_b32 s34, s64, s66
	s_add_i32 s35, s4, -2
	s_add_u32 s8, s8, 0x200800
	s_addc_u32 s9, s9, 0
	s_add_u32 s41, s66, 0x100
	v_mov_b32_e32 v0, 0
	s_mov_b64 s[92:93], s[90:91]
	s_addc_u32 s46, s67, 0
	s_mov_b32 s47, 0
	v_mov_b32_e32 v1, v0
	v_mov_b32_e32 v2, v0
	v_mov_b32_e32 v3, v0
	v_mov_b32_e32 v4, v0
	v_mov_b32_e32 v5, v0
	v_mov_b32_e32 v6, v0
	v_mov_b32_e32 v7, v0
	v_mov_b32_e32 v8, v0
	v_mov_b32_e32 v9, v0
	v_mov_b32_e32 v10, v0
	v_mov_b32_e32 v11, v0
	v_mov_b32_e32 v12, v0
	v_mov_b32_e32 v13, v0
	v_mov_b32_e32 v14, v0
	v_mov_b32_e32 v15, v0
	v_mov_b32_e32 v20, v0
	v_mov_b32_e32 v21, v0
	v_mov_b32_e32 v22, v0
	v_mov_b32_e32 v23, v0
	v_mov_b32_e32 v28, v0
	v_mov_b32_e32 v29, v0
	v_mov_b32_e32 v30, v0
	v_mov_b32_e32 v31, v0
	v_mov_b32_e32 v36, v0
	v_mov_b32_e32 v37, v0
	v_mov_b32_e32 v38, v0
	v_mov_b32_e32 v39, v0
	v_mov_b32_e32 v44, v0
	v_mov_b32_e32 v45, v0
	v_mov_b32_e32 v46, v0
	v_mov_b32_e32 v47, v0
	v_mov_b32_e32 v16, v0
	v_mov_b32_e32 v17, v0
	v_mov_b32_e32 v18, v0
	v_mov_b32_e32 v19, v0
	s_waitcnt vmcnt(0)
	v_mov_b32_e32 v24, v0
	v_mov_b32_e32 v25, v0
	v_mov_b32_e32 v26, v0
	v_mov_b32_e32 v27, v0
	v_mov_b32_e32 v32, v0
	v_mov_b32_e32 v33, v0
	v_mov_b32_e32 v34, v0
	v_mov_b32_e32 v35, v0
	v_mov_b32_e32 v40, v0
	v_mov_b32_e32 v41, v0
	v_mov_b32_e32 v42, v0
	v_mov_b32_e32 v43, v0
	v_mov_b32_e32 v48, v0
	v_mov_b32_e32 v49, v0
	v_mov_b32_e32 v50, v0
	v_mov_b32_e32 v51, v0
	v_mov_b32_e32 v52, v0
	v_mov_b32_e32 v53, v0
	v_mov_b32_e32 v54, v0
	v_mov_b32_e32 v55, v0
	v_mov_b32_e32 v56, v0
	v_mov_b32_e32 v57, v0
	v_mov_b32_e32 v58, v0
	v_mov_b32_e32 v59, v0
	v_mov_b32_e32 v60, v0
	v_mov_b32_e32 v61, v0
	v_mov_b32_e32 v62, v0
	v_mov_b32_e32 v63, v0
	v_mov_b32_e32 v64, v0
	v_mov_b32_e32 v65, v0
	v_mov_b32_e32 v66, v0
	v_mov_b32_e32 v67, v0
	v_mov_b32_e32 v68, v0
	v_mov_b32_e32 v69, v0
	v_mov_b32_e32 v70, v0
	v_mov_b32_e32 v71, v0
	v_mov_b32_e32 v72, v0
	v_mov_b32_e32 v73, v0
	v_mov_b32_e32 v74, v0
	v_mov_b32_e32 v75, v0
	v_mov_b32_e32 v76, v0
	v_mov_b32_e32 v77, v0
	v_mov_b32_e32 v78, v0
	v_mov_b32_e32 v79, v0
	v_mov_b32_e32 v84, v0
	v_mov_b32_e32 v85, v0
	v_mov_b32_e32 v86, v0
	v_mov_b32_e32 v87, v0
	v_mov_b32_e32 v92, v0
	v_mov_b32_e32 v93, v0
	v_mov_b32_e32 v94, v0
	v_mov_b32_e32 v95, v0
	v_mov_b32_e32 v100, v0
	v_mov_b32_e32 v101, v0
	v_mov_b32_e32 v102, v0
	v_mov_b32_e32 v103, v0
	v_mov_b32_e32 v108, v0
	v_mov_b32_e32 v109, v0
	v_mov_b32_e32 v110, v0
	v_mov_b32_e32 v111, v0
	v_mov_b32_e32 v80, v0
	v_mov_b32_e32 v81, v0
	v_mov_b32_e32 v82, v0
	v_mov_b32_e32 v83, v0
	v_mov_b32_e32 v88, v0
	v_mov_b32_e32 v89, v0
	v_mov_b32_e32 v90, v0
	v_mov_b32_e32 v91, v0
	v_mov_b32_e32 v96, v0
	v_mov_b32_e32 v97, v0
	v_mov_b32_e32 v98, v0
	v_mov_b32_e32 v99, v0
	v_mov_b32_e32 v104, v0
	v_mov_b32_e32 v105, v0
	v_mov_b32_e32 v106, v0
	v_mov_b32_e32 v107, v0
	v_mov_b32_e32 v112, v0
	v_mov_b32_e32 v113, v0
	v_mov_b32_e32 v114, v0
	v_mov_b32_e32 v115, v0
	v_mov_b32_e32 v116, v0
	v_mov_b32_e32 v117, v0
	v_mov_b32_e32 v118, v0
	v_mov_b32_e32 v119, v0
	v_mov_b32_e32 v120, v0
	v_mov_b32_e32 v121, v0
	v_mov_b32_e32 v122, v0
	v_mov_b32_e32 v123, v0
	v_mov_b32_e32 v124, v0
	v_mov_b32_e32 v125, v0
	v_mov_b32_e32 v126, v0
	v_mov_b32_e32 v127, v0
	s_cmp_lg_u64 s[20:21], 0
	s_cbranch_scc0 .Ledge_p8
	s_barrier
.Ledge_p8:
.LBB0_917:
	ds_read_b128 v[128:131], v208
	ds_read_b128 v[132:135], v208 offset:1024
	ds_read_b128 v[136:139], v208 offset:2048
	ds_read_b128 v[140:143], v208 offset:3072
	ds_read_b128 v[144:147], v209
	ds_read_b128 v[148:151], v209 offset:1024
	ds_read_b128 v[172:175], v209 offset:2048
	ds_read_b128 v[176:179], v209 offset:3072
	s_add_i32 s55, s47, 2
	s_add_u32 s57, s8, 0xffe00800
	s_addc_u32 s59, s9, -1
	s_cmp_eq_u32 s35, s47
	s_cselect_b32 s71, s2, s59
	s_cselect_b32 s70, s5, s57
	s_cselect_b32 s67, s19, s46
	s_cselect_b32 s66, s34, s41
	v_lshl_add_u64 v[216:217], s[8:9], 0, v[168:169]
	s_add_i32 m0, s17, 0xc000
	ds_read_b128 v[180:183], v210
	ds_read_b128 v[184:187], v210 offset:1024
	ds_read_b128 v[188:191], v210 offset:2048
	ds_read_b128 v[192:195], v210 offset:3072
	ds_read_b128 v[196:199], v210 offset:4096
	ds_read_b128 v[200:203], v210 offset:5120
	ds_read_b128 v[204:207], v210 offset:6144
	ds_read_b128 v[212:215], v210 offset:7168
	global_load_lds_dwordx4 v[216:217], off
	v_lshl_add_u64 v[216:217], s[8:9], 0, v[170:171]
	s_add_i32 m0, s17, 0xe000
	s_nop 0
	global_load_lds_dwordx4 v[216:217], off
	s_waitcnt vmcnt(8)
	s_waitcnt lgkmcnt(0)
	s_barrier
; #define PG8_STAGE(bufoff, gbase, voff) do { _Pragma("unroll") for (int _i = 0; _i < 2; ++_i) \
;         __builtin_amdgcn_global_load_lds((const unsigned*)((const char*)(gbase) + (voff)[_i]), (LAS unsigned*)(lds + (bufoff) + ldsw + _i * 8192), 16, 0, 0); } while (0)
; #define PG8_LDA(dst, b, h) do { _Pragma("unroll") for (int m = 0; m < 4; ++m) _Pragma("unroll") for (int k = 0; k < 2; ++k) dst[m][k] = *(const LAS bf16x8*)(lds + PG8_SA(b, h) + aoff + m * 2048 + k * 1024); } while (0)
; #define PG8_MMA(ai, bj, At, Bt) do { __builtin_amdgcn_s_setprio(1); _Pragma("unroll") for (int m = 0; m < 4; ++m) _Pragma("unroll") for (int n = 0; n < 2; ++n) _Pragma("unroll") for (int k = 0; k < 2; ++k) \
;         acc[ai][bj][m][n] = __builtin_amdgcn_mfma_f32_16x16x32_bf16(Bt[n][k], At[m][k], acc[ai][bj][m][n], 0, 0, 0); __builtin_amdgcn_s_setprio(0); } while (0)
; #define PG8_WAIT_V(n) asm volatile("s_waitcnt vmcnt(" #n ")" ::: "memory")
; #define PG8_WAIT_L(n) asm volatile("s_waitcnt lgkmcnt(" #n ")" ::: "memory")
; #define PG8_BAR __builtin_amdgcn_s_barrier()
; #define PG8_SCHED __builtin_amdgcn_sched_barrier(0)
; template <class Epi, class Sched>
; __device__ __forceinline__ void gemm_phase(LAS unsigned char* lds, const Gemm g, const Sched& S, const Epi& E) {
;     ...
;             PG8_WAIT_V(8); PG8_WAIT_L(0); PG8_BAR; PG8_MMA(0, 0, At, B0); PG8_MMA(0, 1, At, B1); PG8_BAR; PG8_SCHED;
;             PG8_LDA(At, 0, 1); PG8_STAGE(PG8_SB(0, 0), b2, voffB); PG8_STAGE(PG8_SB(0, 1), b2 + hstepB, voffB); PG8_STAGE(PG8_SA(0, 0), a2, voffA);
;             PG8_WAIT_V(8); PG8_WAIT_L(0); PG8_BAR; PG8_MMA(1, 0, At, B0); PG8_MMA(1, 1, At, B1); PG8_BAR; PG8_SCHED;
	s_setprio 1
	s_waitcnt lgkmcnt(0)
	v_mfma_f32_16x16x32_bf16 v[124:127], v[128:131], v[180:183], v[124:127]
	v_mfma_f32_16x16x32_bf16 v[120:123], v[136:139], v[180:183], v[120:123]
	v_mfma_f32_16x16x32_bf16 v[116:119], v[128:131], v[188:191], v[116:119]
	v_mfma_f32_16x16x32_bf16 v[112:115], v[136:139], v[188:191], v[112:115]
	v_mfma_f32_16x16x32_bf16 v[104:107], v[128:131], v[196:199], v[104:107]
	v_mfma_f32_16x16x32_bf16 v[96:99], v[136:139], v[196:199], v[96:99]
	v_mfma_f32_16x16x32_bf16 v[88:91], v[128:131], v[204:207], v[88:91]
	v_mfma_f32_16x16x32_bf16 v[80:83], v[136:139], v[204:207], v[80:83]
	v_mfma_f32_16x16x32_bf16 v[124:127], v[132:135], v[184:187], v[124:127]
	v_mfma_f32_16x16x32_bf16 v[120:123], v[140:143], v[184:187], v[120:123]
	v_mfma_f32_16x16x32_bf16 v[116:119], v[132:135], v[192:195], v[116:119]
	v_mfma_f32_16x16x32_bf16 v[112:115], v[140:143], v[192:195], v[112:115]
	v_mfma_f32_16x16x32_bf16 v[104:107], v[132:135], v[200:203], v[104:107]
	v_mfma_f32_16x16x32_bf16 v[96:99], v[140:143], v[200:203], v[96:99]
	v_mfma_f32_16x16x32_bf16 v[88:91], v[132:135], v[212:215], v[88:91]
	v_mfma_f32_16x16x32_bf16 v[80:83], v[140:143], v[212:215], v[80:83]
	s_setprio 0
	s_setprio 1
	v_mfma_f32_16x16x32_bf16 v[108:111], v[144:147], v[180:183], v[108:111]
	v_mfma_f32_16x16x32_bf16 v[100:103], v[172:175], v[180:183], v[100:103]
	v_mfma_f32_16x16x32_bf16 v[92:95], v[144:147], v[188:191], v[92:95]
	v_mfma_f32_16x16x32_bf16 v[84:87], v[172:175], v[188:191], v[84:87]
	v_mfma_f32_16x16x32_bf16 v[76:79], v[144:147], v[196:199], v[76:79]
	v_mfma_f32_16x16x32_bf16 v[72:75], v[172:175], v[196:199], v[72:75]
	v_mfma_f32_16x16x32_bf16 v[68:71], v[144:147], v[204:207], v[68:71]
	v_mfma_f32_16x16x32_bf16 v[64:67], v[172:175], v[204:207], v[64:67]
	v_mfma_f32_16x16x32_bf16 v[108:111], v[148:151], v[184:187], v[108:111]
	v_mfma_f32_16x16x32_bf16 v[100:103], v[176:179], v[184:187], v[100:103]
	v_mfma_f32_16x16x32_bf16 v[92:95], v[148:151], v[192:195], v[92:95]
	v_mfma_f32_16x16x32_bf16 v[84:87], v[176:179], v[192:195], v[84:87]
	v_mfma_f32_16x16x32_bf16 v[76:79], v[148:151], v[200:203], v[76:79]
	v_mfma_f32_16x16x32_bf16 v[72:75], v[176:179], v[200:203], v[72:75]
	v_mfma_f32_16x16x32_bf16 v[68:71], v[148:151], v[212:215], v[68:71]
	v_mfma_f32_16x16x32_bf16 v[64:67], v[176:179], v[212:215], v[64:67]
	s_setprio 0
	s_barrier
	s_add_i32 s47, s81, s39
	v_lshl_add_u64 v[216:217], s[66:67], 0, v[156:157]
	s_mov_b32 m0, s47
	ds_read_b128 v[180:183], v210 offset:16384
	ds_read_b128 v[184:187], v210 offset:17408
	ds_read_b128 v[188:191], v210 offset:18432
	ds_read_b128 v[192:195], v210 offset:19456
	ds_read_b128 v[196:199], v210 offset:20480
	ds_read_b128 v[200:203], v210 offset:21504
	ds_read_b128 v[204:207], v210 offset:22528
	ds_read_b128 v[212:215], v210 offset:23552
	global_load_lds_dwordx4 v[216:217], off
	s_add_i32 m0, s47, 0x2000
	s_add_u32 s90, s66, 0x200000
	v_lshl_add_u64 v[218:219], s[66:67], 0, v[160:161]
	s_addc_u32 s91, s67, 0
	s_add_i32 s47, s82, s39
	global_load_lds_dwordx4 v[218:219], off
	v_lshl_add_u64 v[220:221], s[90:91], 0, v[156:157]
	s_mov_b32 m0, s47
	v_lshl_add_u64 v[222:223], s[70:71], 0, v[158:159]
	global_load_lds_dwordx4 v[220:221], off
	v_lshl_add_u64 v[220:221], s[90:91], 0, v[160:161]
	s_add_i32 m0, s47, 0x2000
	s_nop 0
	global_load_lds_dwordx4 v[220:221], off
	v_lshl_add_u64 v[220:221], s[70:71], 0, v[154:155]
	s_mov_b32 m0, s17
	s_nop 0
	global_load_lds_dwordx4 v[220:221], off
	s_mov_b32 m0, s72
	s_nop 0
	global_load_lds_dwordx4 v[222:223], off
	s_waitcnt vmcnt(8)
	s_waitcnt lgkmcnt(0)
	s_barrier
	s_setprio 1
	s_waitcnt lgkmcnt(0)
	v_mfma_f32_16x16x32_bf16 v[60:63], v[128:131], v[180:183], v[60:63]
	v_mfma_f32_16x16x32_bf16 v[56:59], v[136:139], v[180:183], v[56:59]
	v_mfma_f32_16x16x32_bf16 v[52:55], v[128:131], v[188:191], v[52:55]
	v_mfma_f32_16x16x32_bf16 v[48:51], v[136:139], v[188:191], v[48:51]
	v_mfma_f32_16x16x32_bf16 v[40:43], v[128:131], v[196:199], v[40:43]
	v_mfma_f32_16x16x32_bf16 v[32:35], v[136:139], v[196:199], v[32:35]
	v_mfma_f32_16x16x32_bf16 v[24:27], v[128:131], v[204:207], v[24:27]
	v_mfma_f32_16x16x32_bf16 v[16:19], v[136:139], v[204:207], v[16:19]
	v_mfma_f32_16x16x32_bf16 v[60:63], v[132:135], v[184:187], v[60:63]
	v_mfma_f32_16x16x32_bf16 v[56:59], v[140:143], v[184:187], v[56:59]
	v_mfma_f32_16x16x32_bf16 v[52:55], v[132:135], v[192:195], v[52:55]
	v_mfma_f32_16x16x32_bf16 v[48:51], v[140:143], v[192:195], v[48:51]
	v_mfma_f32_16x16x32_bf16 v[40:43], v[132:135], v[200:203], v[40:43]
	v_mfma_f32_16x16x32_bf16 v[32:35], v[140:143], v[200:203], v[32:35]
	v_mfma_f32_16x16x32_bf16 v[24:27], v[132:135], v[212:215], v[24:27]
	v_mfma_f32_16x16x32_bf16 v[16:19], v[140:143], v[212:215], v[16:19]
	s_setprio 0
	s_setprio 1
	v_mfma_f32_16x16x32_bf16 v[44:47], v[144:147], v[180:183], v[44:47]
	v_mfma_f32_16x16x32_bf16 v[36:39], v[172:175], v[180:183], v[36:39]
	v_mfma_f32_16x16x32_bf16 v[28:31], v[144:147], v[188:191], v[28:31]
	v_mfma_f32_16x16x32_bf16 v[20:23], v[172:175], v[188:191], v[20:23]
	v_mfma_f32_16x16x32_bf16 v[12:15], v[144:147], v[196:199], v[12:15]
	v_mfma_f32_16x16x32_bf16 v[8:11], v[172:175], v[196:199], v[8:11]
	v_mfma_f32_16x16x32_bf16 v[4:7], v[144:147], v[204:207], v[4:7]
	v_mfma_f32_16x16x32_bf16 v[0:3], v[172:175], v[204:207], v[0:3]
	v_mfma_f32_16x16x32_bf16 v[44:47], v[148:151], v[184:187], v[44:47]
	v_mfma_f32_16x16x32_bf16 v[36:39], v[176:179], v[184:187], v[36:39]
	v_mfma_f32_16x16x32_bf16 v[28:31], v[148:151], v[192:195], v[28:31]
	v_mfma_f32_16x16x32_bf16 v[20:23], v[176:179], v[192:195], v[20:23]
	v_mfma_f32_16x16x32_bf16 v[12:15], v[148:151], v[200:203], v[12:15]
	v_mfma_f32_16x16x32_bf16 v[8:11], v[176:179], v[200:203], v[8:11]
	v_mfma_f32_16x16x32_bf16 v[4:7], v[148:151], v[212:215], v[4:7]
	v_mfma_f32_16x16x32_bf16 v[0:3], v[176:179], v[212:215], v[0:3]
	s_setprio 0
	s_barrier
; #define PG8_STAGE(bufoff, gbase, voff) do { _Pragma("unroll") for (int _i = 0; _i < 2; ++_i) \
;         __builtin_amdgcn_global_load_lds((const unsigned*)((const char*)(gbase) + (voff)[_i]), (LAS unsigned*)(lds + (bufoff) + ldsw + _i * 8192), 16, 0, 0); } while (0)
; #define PG8_LDA(dst, b, h) do { _Pragma("unroll") for (int m = 0; m < 4; ++m) _Pragma("unroll") for (int k = 0; k < 2; ++k) dst[m][k] = *(const LAS bf16x8*)(lds + PG8_SA(b, h) + aoff + m * 2048 + k * 1024); } while (0)
; #define PG8_LDB(dst, b, h) do { _Pragma("unroll") for (int n = 0; n < 2; ++n) _Pragma("unroll") for (int k = 0; k < 2; ++k) dst[n][k] = *(const LAS bf16x8*)(lds + PG8_SB(b, h) + boff + n * 2048 + k * 1024); } while (0)
; #define PG8_MMA(ai, bj, At, Bt) do { __builtin_amdgcn_s_setprio(1); _Pragma("unroll") for (int m = 0; m < 4; ++m) _Pragma("unroll") for (int n = 0; n < 2; ++n) _Pragma("unroll") for (int k = 0; k < 2; ++k) \
;         acc[ai][bj][m][n] = __builtin_amdgcn_mfma_f32_16x16x32_bf16(Bt[n][k], At[m][k], acc[ai][bj][m][n], 0, 0, 0); __builtin_amdgcn_s_setprio(0); } while (0)
; #define PG8_WAIT_V(n) asm volatile("s_waitcnt vmcnt(" #n ")" ::: "memory")
; #define PG8_WAIT_L(n) asm volatile("s_waitcnt lgkmcnt(" #n ")" ::: "memory")
; #define PG8_BAR __builtin_amdgcn_s_barrier()
; #define PG8_SCHED __builtin_amdgcn_sched_barrier(0)
; template <class Epi, class Sched>
; __device__ __forceinline__ void gemm_phase(LAS unsigned char* lds, const Gemm g, const Sched& S, const Epi& E) {
;     ...
;             PG8_LDB(B0, 1, 0); PG8_LDB(B1, 1, 1); PG8_SCHED; PG8_LDA(At, 1, 0); PG8_STAGE(PG8_SA(0, 1), a2 + hstepA, voffA);
;             PG8_WAIT_V(8); PG8_WAIT_L(0); PG8_BAR; PG8_MMA(0, 0, At, B0); PG8_MMA(0, 1, At, B1); PG8_BAR; PG8_SCHED;
	s_add_i32 s47, 0, 0x18000
	s_add_i32 s57, 0, 0x1c000
	v_add_u32_e32 v140, s47, v153
	v_add_u32_e32 v176, s57, v153
	ds_read_b128 v[128:131], v140
	ds_read_b128 v[132:135], v140 offset:1024
	ds_read_b128 v[136:139], v140 offset:2048
	ds_read_b128 v[140:143], v140 offset:3072
	ds_read_b128 v[144:147], v176
	ds_read_b128 v[148:151], v176 offset:1024
	ds_read_b128 v[172:175], v176 offset:2048
	ds_read_b128 v[176:179], v176 offset:3072
	s_add_u32 s70, s70, 0x200000
	s_addc_u32 s71, s71, 0
	s_mov_b32 m0, s73
	v_lshl_add_u64 v[224:225], s[70:71], 0, v[154:155]
	ds_read_b128 v[180:183], v210 offset:32768
	ds_read_b128 v[184:187], v210 offset:33792
	ds_read_b128 v[188:191], v210 offset:34816
	ds_read_b128 v[192:195], v210 offset:35840
	ds_read_b128 v[196:199], v210 offset:36864
	ds_read_b128 v[200:203], v210 offset:37888
	ds_read_b128 v[204:207], v210 offset:38912
	ds_read_b128 v[212:215], v210 offset:39936
	global_load_lds_dwordx4 v[224:225], off
	v_lshl_add_u64 v[224:225], s[70:71], 0, v[158:159]
	s_mov_b32 m0, s76
	s_nop 0
	global_load_lds_dwordx4 v[224:225], off
	s_waitcnt vmcnt(8)
	s_waitcnt lgkmcnt(0)
	s_barrier
	s_setprio 1
	s_waitcnt lgkmcnt(0)
	v_mfma_f32_16x16x32_bf16 v[124:127], v[128:131], v[180:183], v[124:127]
	v_mfma_f32_16x16x32_bf16 v[120:123], v[136:139], v[180:183], v[120:123]
	v_mfma_f32_16x16x32_bf16 v[116:119], v[128:131], v[188:191], v[116:119]
	v_mfma_f32_16x16x32_bf16 v[112:115], v[136:139], v[188:191], v[112:115]
	v_mfma_f32_16x16x32_bf16 v[104:107], v[128:131], v[196:199], v[104:107]
	v_mfma_f32_16x16x32_bf16 v[96:99], v[136:139], v[196:199], v[96:99]
	v_mfma_f32_16x16x32_bf16 v[88:91], v[128:131], v[204:207], v[88:91]
	v_mfma_f32_16x16x32_bf16 v[80:83], v[136:139], v[204:207], v[80:83]
	v_mfma_f32_16x16x32_bf16 v[124:127], v[132:135], v[184:187], v[124:127]
	v_mfma_f32_16x16x32_bf16 v[120:123], v[140:143], v[184:187], v[120:123]
	v_mfma_f32_16x16x32_bf16 v[116:119], v[132:135], v[192:195], v[116:119]
	v_mfma_f32_16x16x32_bf16 v[112:115], v[140:143], v[192:195], v[112:115]
	v_mfma_f32_16x16x32_bf16 v[104:107], v[132:135], v[200:203], v[104:107]
	v_mfma_f32_16x16x32_bf16 v[96:99], v[140:143], v[200:203], v[96:99]
	v_mfma_f32_16x16x32_bf16 v[88:91], v[132:135], v[212:215], v[88:91]
	v_mfma_f32_16x16x32_bf16 v[80:83], v[140:143], v[212:215], v[80:83]
	s_setprio 0
	s_setprio 1
	v_mfma_f32_16x16x32_bf16 v[108:111], v[144:147], v[180:183], v[108:111]
	v_mfma_f32_16x16x32_bf16 v[100:103], v[172:175], v[180:183], v[100:103]
	v_mfma_f32_16x16x32_bf16 v[92:95], v[144:147], v[188:191], v[92:95]
	v_mfma_f32_16x16x32_bf16 v[84:87], v[172:175], v[188:191], v[84:87]
	v_mfma_f32_16x16x32_bf16 v[76:79], v[144:147], v[196:199], v[76:79]
	v_mfma_f32_16x16x32_bf16 v[72:75], v[172:175], v[196:199], v[72:75]
	v_mfma_f32_16x16x32_bf16 v[68:71], v[144:147], v[204:207], v[68:71]
	v_mfma_f32_16x16x32_bf16 v[64:67], v[172:175], v[204:207], v[64:67]
	v_mfma_f32_16x16x32_bf16 v[108:111], v[148:151], v[184:187], v[108:111]
	v_mfma_f32_16x16x32_bf16 v[100:103], v[176:179], v[184:187], v[100:103]
	v_mfma_f32_16x16x32_bf16 v[92:95], v[148:151], v[192:195], v[92:95]
	v_mfma_f32_16x16x32_bf16 v[84:87], v[176:179], v[192:195], v[84:87]
	v_mfma_f32_16x16x32_bf16 v[76:79], v[148:151], v[200:203], v[76:79]
	v_mfma_f32_16x16x32_bf16 v[72:75], v[176:179], v[200:203], v[72:75]
	v_mfma_f32_16x16x32_bf16 v[68:71], v[148:151], v[212:215], v[68:71]
	v_mfma_f32_16x16x32_bf16 v[64:67], v[176:179], v[212:215], v[64:67]
	s_setprio 0
	s_barrier
; #define PG8_STAGE(bufoff, gbase, voff) do { _Pragma("unroll") for (int _i = 0; _i < 2; ++_i) \
;         __builtin_amdgcn_global_load_lds((const unsigned*)((const char*)(gbase) + (voff)[_i]), (LAS unsigned*)(lds + (bufoff) + ldsw + _i * 8192), 16, 0, 0); } while (0)
; #define PG8_LDA(dst, b, h) do { _Pragma("unroll") for (int m = 0; m < 4; ++m) _Pragma("unroll") for (int k = 0; k < 2; ++k) dst[m][k] = *(const LAS bf16x8*)(lds + PG8_SA(b, h) + aoff + m * 2048 + k * 1024); } while (0)
; #define PG8_MMA(ai, bj, At, Bt) do { __builtin_amdgcn_s_setprio(1); _Pragma("unroll") for (int m = 0; m < 4; ++m) _Pragma("unroll") for (int n = 0; n < 2; ++n) _Pragma("unroll") for (int k = 0; k < 2; ++k) \
;         acc[ai][bj][m][n] = __builtin_amdgcn_mfma_f32_16x16x32_bf16(Bt[n][k], At[m][k], acc[ai][bj][m][n], 0, 0, 0); __builtin_amdgcn_s_setprio(0); } while (0)
; #define PG8_WAIT_V(n) asm volatile("s_waitcnt vmcnt(" #n ")" ::: "memory")
; #define PG8_WAIT_L(n) asm volatile("s_waitcnt lgkmcnt(" #n ")" ::: "memory")
; #define PG8_BAR __builtin_amdgcn_s_barrier()
; #define PG8_SCHED __builtin_amdgcn_sched_barrier(0)
; template <class Epi, class Sched>
; __device__ __forceinline__ void gemm_phase(LAS unsigned char* lds, const Gemm g, const Sched& S, const Epi& E) {
;     ...
;             PG8_LDA(At, 1, 1); PG8_STAGE(PG8_SB(1, 0), b3, voffB); PG8_STAGE(PG8_SB(1, 1), b3 + hstepB, voffB); PG8_STAGE(PG8_SA(1, 0), a3, voffA);
;             PG8_WAIT_V(8); PG8_WAIT_L(0); PG8_BAR; PG8_MMA(1, 0, At, B0); PG8_MMA(1, 1, At, B1); PG8_BAR; PG8_SCHED;
;         }
;         if (wr == 0) PG8_BAR;
;         E(acc, cur, wr, wc, fr, fq);
	s_add_i32 s47, s47, s39
	v_lshl_add_u64 v[216:217], v[216:217], 0, s[24:25]
	s_mov_b32 m0, s47
	ds_read_b128 v[180:183], v210 offset:49152
	ds_read_b128 v[184:187], v210 offset:50176
	ds_read_b128 v[188:191], v210 offset:51200
	ds_read_b128 v[192:195], v210 offset:52224
	ds_read_b128 v[196:199], v210 offset:53248
	ds_read_b128 v[200:203], v210 offset:54272
	ds_read_b128 v[204:207], v210 offset:55296
	ds_read_b128 v[212:215], v210 offset:56320
	global_load_lds_dwordx4 v[216:217], off
	s_add_i32 m0, s47, 0x2000
	s_add_u32 s66, s66, 0x200080
	v_lshl_add_u64 v[216:217], v[218:219], 0, s[24:25]
	s_addc_u32 s67, s67, 0
	s_add_i32 s47, s57, s39
	global_load_lds_dwordx4 v[216:217], off
	v_lshl_add_u64 v[216:217], s[66:67], 0, v[156:157]
	s_mov_b32 m0, s47
	s_nop 0
	global_load_lds_dwordx4 v[216:217], off
	v_lshl_add_u64 v[216:217], s[66:67], 0, v[160:161]
	s_add_i32 m0, s47, 0x2000
	s_nop 0
	global_load_lds_dwordx4 v[216:217], off
	v_lshl_add_u64 v[216:217], v[220:221], 0, s[98:99]
	s_mov_b32 m0, s79
	s_nop 0
	global_load_lds_dwordx4 v[216:217], off
	v_lshl_add_u64 v[216:217], v[222:223], 0, s[98:99]
	s_mov_b32 m0, s80
	s_nop 0
	global_load_lds_dwordx4 v[216:217], off
	s_waitcnt vmcnt(8)
	s_waitcnt lgkmcnt(0)
	s_barrier
	s_setprio 1
	s_waitcnt lgkmcnt(0)
	v_mfma_f32_16x16x32_bf16 v[60:63], v[128:131], v[180:183], v[60:63]
	v_mfma_f32_16x16x32_bf16 v[56:59], v[136:139], v[180:183], v[56:59]
	v_mfma_f32_16x16x32_bf16 v[52:55], v[128:131], v[188:191], v[52:55]
	v_mfma_f32_16x16x32_bf16 v[48:51], v[136:139], v[188:191], v[48:51]
	v_mfma_f32_16x16x32_bf16 v[40:43], v[128:131], v[196:199], v[40:43]
	v_mfma_f32_16x16x32_bf16 v[32:35], v[136:139], v[196:199], v[32:35]
	v_mfma_f32_16x16x32_bf16 v[24:27], v[128:131], v[204:207], v[24:27]
	v_mfma_f32_16x16x32_bf16 v[16:19], v[136:139], v[204:207], v[16:19]
	v_mfma_f32_16x16x32_bf16 v[60:63], v[132:135], v[184:187], v[60:63]
	v_mfma_f32_16x16x32_bf16 v[56:59], v[140:143], v[184:187], v[56:59]
	v_mfma_f32_16x16x32_bf16 v[52:55], v[132:135], v[192:195], v[52:55]
	v_mfma_f32_16x16x32_bf16 v[48:51], v[140:143], v[192:195], v[48:51]
	v_mfma_f32_16x16x32_bf16 v[40:43], v[132:135], v[200:203], v[40:43]
	v_mfma_f32_16x16x32_bf16 v[32:35], v[140:143], v[200:203], v[32:35]
	v_mfma_f32_16x16x32_bf16 v[24:27], v[132:135], v[212:215], v[24:27]
	v_mfma_f32_16x16x32_bf16 v[16:19], v[140:143], v[212:215], v[16:19]
	s_setprio 0
	s_setprio 1
	v_mfma_f32_16x16x32_bf16 v[44:47], v[144:147], v[180:183], v[44:47]
	v_mfma_f32_16x16x32_bf16 v[36:39], v[172:175], v[180:183], v[36:39]
	v_mfma_f32_16x16x32_bf16 v[28:31], v[144:147], v[188:191], v[28:31]
	v_mfma_f32_16x16x32_bf16 v[20:23], v[172:175], v[188:191], v[20:23]
	v_mfma_f32_16x16x32_bf16 v[12:15], v[144:147], v[196:199], v[12:15]
	v_mfma_f32_16x16x32_bf16 v[8:11], v[172:175], v[196:199], v[8:11]
	v_mfma_f32_16x16x32_bf16 v[4:7], v[144:147], v[204:207], v[4:7]
	v_mfma_f32_16x16x32_bf16 v[0:3], v[172:175], v[204:207], v[0:3]
	v_mfma_f32_16x16x32_bf16 v[44:47], v[148:151], v[184:187], v[44:47]
	v_mfma_f32_16x16x32_bf16 v[36:39], v[176:179], v[184:187], v[36:39]
	v_mfma_f32_16x16x32_bf16 v[28:31], v[148:151], v[192:195], v[28:31]
	v_mfma_f32_16x16x32_bf16 v[20:23], v[176:179], v[192:195], v[20:23]
	v_mfma_f32_16x16x32_bf16 v[12:15], v[148:151], v[200:203], v[12:15]
	v_mfma_f32_16x16x32_bf16 v[8:11], v[176:179], v[200:203], v[8:11]
	v_mfma_f32_16x16x32_bf16 v[4:7], v[148:151], v[212:215], v[4:7]
	v_mfma_f32_16x16x32_bf16 v[0:3], v[176:179], v[212:215], v[0:3]
	s_setprio 0
	s_barrier
	s_add_u32 s8, s8, 0x1000
	s_addc_u32 s9, s9, 0
	s_add_u32 s41, s41, 0x100
	s_addc_u32 s46, s46, 0
	s_cmp_ge_i32 s55, s4
	s_mov_b32 s47, s55
	s_cbranch_scc0 .LBB0_917
	s_and_b64 vcc, exec, s[36:37]
	s_cbranch_vccz .LBB0_922
	s_barrier
	s_cmp_lt_i32 s12, 0
	s_mov_b64 s[8:9], -1
	s_cbranch_scc1 .LBB0_923

; #define PG8_BAR __builtin_amdgcn_s_barrier()
; template <class Epi, class Sched>
; __device__ __forceinline__ void gemm_phase(LAS unsigned char* lds, const Gemm g, const Sched& S, const Epi& E) {
;     ...
;         cur = nxt; cA = nA; cB = nB; ++ui;
;         if (wr == 1) PG8_BAR;
;     }
.LBB0_950:
	s_andn2_b64 vcc, exec, s[20:21]
	s_cbranch_vccnz .LBB0_909
	s_branch .LBB0_909
